# dn_prep S0 loads batched; sgu/pool epilogue row loads hoisted
# speedup vs baseline: 1.0238x; 1.0238x over previous
; DI unsigned pk2(float lo, float hi) { f32x2 v = {lo, hi}; bfv2 b = __builtin_convertvector(v, bfv2); return __builtin_bit_cast(unsigned, b); }
; DI int crow(int i, int h) { return (i & 3) + 8 * (i >> 2) + 4 * h; }
; DI f32x16 mfma32(bf16x8 a, bf16x8 b, f32x16 c) { return __builtin_amdgcn_mfma_f32_32x32x16_bf16(a, b, c, 0, 0, 0); }
; DI void unpack8(u32x4 v, float* x) { x[0] = bflo(v.x); x[1] = bfhi(v.x); x[2] = bflo(v.y); x[3] = bfhi(v.y); x[4] = bflo(v.z); x[5] = bfhi(v.z); x[6] = bflo(v.w); x[7] = bfhi(v.w); }
; DI void pool_task(const Params& p, int layer, int tile, unsigned char* lds) {
;     ...
;       float x0[8]; unpack8(*(const u32x4*)(xs + (tl + 8) * 72 + 16 * ks + 8 * hh), x0);
;       const u32x4 w4 = {pk2(sum[0] * inv - x0[0], sum[1] * inv - x0[1]), pk2(sum[2] * inv - x0[2], sum[3] * inv - x0[3]), pk2(sum[4] * inv - x0[4], sum[5] * inv - x0[5]), pk2(sum[6] * inv - x0[6], sum[7] * inv - x0[7])};
;       const bf16x8 a = __builtin_bit_cast(bf16x8, w4);
; #pragma unroll
;       for (int nt = 0; nt < 2; ++nt) { const bf16x8 b = *(const bf16x8*)(WT + (32 * nt + r) * 64 + 16 * ks + 8 * hh); acc[mt][nt] = mfma32(a, b, acc[mt][nt]); }
;     }
;   }
;   __syncthreads();
;   {
;     float* Ct = (float*)lds + wid * (64 * 68);
; #pragma unroll
;     for (int nt = 0; nt < 2; ++nt) {
;       const float psc = p.pool_scale[layer * 256 + 64 * g + 32 * nt + r];
; #pragma unroll
;       for (int mt = 0; mt < 2; ++mt)
; #pragma unroll
;         for (int i = 0; i < 16; ++i) Ct[(32 * mt + crow(i, hh)) * 68 + 32 * nt + r] = acc[mt][nt][i] * psc;
;     }
;     asm volatile("s_waitcnt lgkmcnt(0)" ::: "memory");
.LBB0_171:
	s_or_b64 exec, exec, s[0:1]
	ds_read_b128 v[72:75], v108 offset:1248
	s_waitcnt lgkmcnt(0)
	s_barrier
	s_movk_i32 s0, 0x4400
	v_lshlrev_b32_e32 v76, 16, v72
	v_and_b32_e32 v77, 0xffff0000, v72
	v_lshlrev_b32_e32 v72, 16, v73
	v_and_b32_e32 v73, 0xffff0000, v73
	v_pk_fma_f32 v[70:71], v[90:91], v[70:71], v[76:77] neg_lo:[0,0,1] neg_hi:[0,0,1]
	v_pk_fma_f32 v[68:69], v[90:91], v[68:69], v[72:73] neg_lo:[0,0,1] neg_hi:[0,0,1]
	v_cvt_pk_bf16_f32 v70, v70, v71
	v_cvt_pk_bf16_f32 v71, v68, v69
	v_lshlrev_b32_e32 v68, 16, v74
	v_and_b32_e32 v69, 0xffff0000, v74
	v_pk_fma_f32 v[66:67], v[90:91], v[66:67], v[68:69] neg_lo:[0,0,1] neg_hi:[0,0,1]
	v_lshlrev_b32_e32 v68, 2, v104
	v_cvt_pk_bf16_f32 v72, v66, v67
	v_lshlrev_b32_e32 v66, 16, v75
	v_and_b32_e32 v67, 0xffff0000, v75
	v_pk_fma_f32 v[64:65], v[90:91], v[64:65], v[66:67] neg_lo:[0,0,1] neg_hi:[0,0,1]
	v_add_u32_e32 v66, s98, v88
	v_cvt_pk_bf16_f32 v73, v64, v65
	v_or_b32_e32 v66, v66, v104
	v_ashrrev_i32_e32 v67, 31, v66
	v_lshl_add_u64 v[74:75], v[66:67], 2, s[74:75]
	v_mfma_f32_32x32x16_bf16 v[48:63], v[70:73], v[80:83], v[48:63]
	v_mul_lo_u32 v64, v102, s0
	v_add_u32_e32 v65, 0, v64
	s_mul_i32 s0, s4, 0x31000
	v_mfma_f32_32x32x16_bf16 v[32:47], v[70:73], v[84:87], v[32:47]
	global_load_dword v73, v[74:75], off
	s_waitcnt vmcnt(0)
	v_mul_f32_e32 v76, v16, v73
	v_mul_u32_u24_e32 v16, 0x440, v103
	v_add3_u32 v16, v65, v68, v16
	v_mul_f32_e32 v65, v31, v73
	s_nop 1
	v_mul_f32_e32 v31, v49, v73
	global_load_dword v49, v[74:75], off offset:128
	v_mul_f32_e32 v77, v17, v73
	v_mul_f32_e32 v78, v18, v73
	v_mul_f32_e32 v79, v19, v73
	v_mul_f32_e32 v80, v20, v73
	v_mul_f32_e32 v81, v21, v73
	v_mul_f32_e32 v82, v22, v73
	v_mul_f32_e32 v83, v23, v73
	v_mul_f32_e32 v72, v24, v73
	v_mul_f32_e32 v71, v25, v73
	v_mul_f32_e32 v70, v26, v73
	v_mul_f32_e32 v69, v27, v73
	v_mul_f32_e32 v68, v28, v73
	v_mul_f32_e32 v67, v29, v73
	v_mul_f32_e32 v66, v30, v73
	v_mul_f32_e32 v48, v48, v73
	v_mul_f32_e32 v30, v50, v73
	v_mul_f32_e32 v29, v51, v73
	v_mul_f32_e32 v28, v52, v73
	v_mul_f32_e32 v27, v53, v73
	v_mul_f32_e32 v26, v54, v73
	v_mul_f32_e32 v25, v55, v73
	v_mul_f32_e32 v24, v56, v73
	v_mul_f32_e32 v23, v57, v73
	v_mul_f32_e32 v22, v58, v73
	v_mul_f32_e32 v21, v59, v73
	v_mul_f32_e32 v20, v60, v73
	v_mul_f32_e32 v19, v61, v73
	v_mul_f32_e32 v18, v62, v73
	v_mul_f32_e32 v17, v63, v73
	s_waitcnt vmcnt(0)
	v_mul_f32_e32 v0, v0, v49
	ds_write2_b32 v16, v76, v0 offset1:32
	v_mul_f32_e32 v0, v1, v49
	ds_write2_b32 v16, v77, v0 offset0:68 offset1:100
	v_mul_f32_e32 v0, v2, v49
	ds_write2_b32 v16, v78, v0 offset0:136 offset1:168
	v_mul_f32_e32 v0, v3, v49
	ds_write2_b32 v16, v79, v0 offset0:204 offset1:236
	v_mul_f32_e32 v0, v4, v49
	v_add_u32_e32 v1, 0x800, v16
	ds_write2_b32 v1, v80, v0 offset0:32 offset1:64
	v_mul_f32_e32 v0, v5, v49
	ds_write2_b32 v1, v81, v0 offset0:100 offset1:132
	v_mul_f32_e32 v0, v6, v49
	ds_write2_b32 v1, v82, v0 offset0:168 offset1:200
	v_mul_f32_e32 v0, v7, v49
	v_add_u32_e32 v1, 0xa00, v16
	ds_write2_b32 v1, v83, v0 offset0:108 offset1:140
	v_mul_f32_e32 v0, v8, v49
	v_add_u32_e32 v1, 0x1000, v16
	ds_write2_b32 v1, v72, v0 offset0:64 offset1:96
	v_mul_f32_e32 v0, v9, v49
	ds_write2_b32 v1, v71, v0 offset0:132 offset1:164
	v_mul_f32_e32 v0, v10, v49
	ds_write2_b32 v1, v70, v0 offset0:200 offset1:232
	v_mul_f32_e32 v0, v11, v49
	v_add_u32_e32 v1, 0x1400, v16
	ds_write2_b32 v1, v69, v0 offset0:12 offset1:44
	v_mul_f32_e32 v0, v12, v49
	v_add_u32_e32 v1, 0x1800, v16
	ds_write2_b32 v1, v68, v0 offset0:96 offset1:128
	v_mul_f32_e32 v0, v13, v49
	ds_write2_b32 v1, v67, v0 offset0:164 offset1:196
	v_mul_f32_e32 v0, v14, v49
	v_add_u32_e32 v1, 0x1a00, v16
	ds_write2_b32 v1, v66, v0 offset0:104 offset1:136
	v_mul_f32_e32 v0, v15, v49
	v_add_u32_e32 v1, 0x1c00, v16
	ds_write2_b32 v1, v65, v0 offset0:44 offset1:76
	v_mul_f32_e32 v0, v32, v49
	v_add_u32_e32 v1, 0x2000, v16
	ds_write2_b32 v1, v48, v0 offset0:128 offset1:160
	v_mul_f32_e32 v0, v33, v49
	ds_write2_b32 v1, v31, v0 offset0:196 offset1:228
	v_mul_f32_e32 v0, v34, v49
	v_add_u32_e32 v1, 0x2400, v16
	ds_write2_b32 v1, v30, v0 offset0:8 offset1:40
	v_mul_f32_e32 v0, v35, v49
	ds_write2_b32 v1, v29, v0 offset0:76 offset1:108
	v_mul_f32_e32 v0, v36, v49
	v_add_u32_e32 v1, 0x2800, v16
	ds_write2_b32 v1, v28, v0 offset0:160 offset1:192
	v_mul_f32_e32 v0, v37, v49
	v_add_u32_e32 v1, 0x2a00, v16
	ds_write2_b32 v1, v27, v0 offset0:100 offset1:132
	v_mul_f32_e32 v0, v38, v49
	v_add_u32_e32 v1, 0x2c00, v16
	ds_write2_b32 v1, v26, v0 offset0:40 offset1:72
	v_mul_f32_e32 v0, v39, v49
	ds_write2_b32 v1, v25, v0 offset0:108 offset1:140
	v_mul_f32_e32 v0, v40, v49
	v_add_u32_e32 v1, 0x3000, v16
	ds_write2_b32 v1, v24, v0 offset0:192 offset1:224
	v_mul_f32_e32 v0, v41, v49
	v_add_u32_e32 v1, 0x3400, v16
	ds_write2_b32 v1, v23, v0 offset0:4 offset1:36
	v_mul_f32_e32 v0, v42, v49
	ds_write2_b32 v1, v22, v0 offset0:72 offset1:104
	v_mul_f32_e32 v0, v43, v49
	ds_write2_b32 v1, v21, v0 offset0:140 offset1:172
	v_mul_f32_e32 v0, v44, v49
	v_add_u32_e32 v1, 0x3a00, v16
	ds_write2_b32 v1, v20, v0 offset0:96 offset1:128
	v_mul_f32_e32 v0, v45, v49
	v_add_u32_e32 v1, 0x3c00, v16
	ds_write2_b32 v1, v19, v0 offset0:36 offset1:68
	v_mul_f32_e32 v0, v46, v49
	ds_write2_b32 v1, v18, v0 offset0:104 offset1:136
	v_mul_f32_e32 v0, v47, v49
	ds_write2_b32 v1, v17, v0 offset0:172 offset1:204
	v_lshrrev_b32_e32 v1, 4, v101
	v_mov_b32_e32 v2, s0
	s_movk_i32 s0, 0xc40
	s_waitcnt lgkmcnt(0)
; DI float bflo(unsigned u) { return __uint_as_float(u << 16); }
; DI float bfhi(unsigned u) { return __uint_as_float(u & 0xffff0000u); }
; DI unsigned pk2(float lo, float hi) { f32x2 v = {lo, hi}; bfv2 b = __builtin_convertvector(v, bfv2); return __builtin_bit_cast(unsigned, b); }
; DI float silu(float x) { return x * __builtin_amdgcn_rcpf(1.f + __expf(-x)); }
; DI void pool_task(const Params& p, int layer, int tile, unsigned char* lds) {
;     ...
; #pragma unroll 4
;     for (int j = 0; j < 16; ++j) {
;       const int rl = 4 * j + rsub;
;       const f32x4 cv = *(const f32x4*)(Ct + rl * 68 + c4);
;       bf16_t* ptr = proj + (size_t)(t0 + rl) * PP + D_Z + 64 * g + c4;
;       const u32x2 zr = *(const u32x2*)ptr;
;       *(u32x2*)ptr = (u32x2){pk2(cv.x * silu(bflo(zr.x)), cv.y * silu(bfhi(zr.x))), pk2(cv.z * silu(bflo(zr.y)), cv.w * silu(bfhi(zr.y)))};
;     }
	v_lshlrev_b32_e32 v0, 2, v100
	v_mad_u32_u24 v4, v1, s0, v2
	v_mul_u32_u24_e32 v1, 0x110, v1
	v_and_b32_e32 v2, 15, v100
	v_and_b32_e32 v0, 60, v0
	v_or_b32_e32 v1, v64, v1
	v_lshlrev_b32_e32 v2, 4, v2
	v_add3_u32 v5, v1, v2, 0
	s_mov_b32 s0, 0
	v_lshlrev_b32_e32 v0, 1, v0
	v_add_u32_e32 v6, s0, v4
	v_add_u32_e32 v160, 0xbfb00000, v6
	v_lshl_add_u64 v[226:227], v[160:161], 1, s[46:47]
	v_lshlrev_b64 v[2:3], 1, v[88:89]
	v_lshl_add_u64 v[226:227], v[226:227], 0, v[2:3]
	v_mov_b32_e32 v1, v161
	v_lshl_add_u64 v[226:227], v[226:227], 0, v[0:1]
	v_add_co_u32_e32 v226, vcc, 0x1000, v226
	s_nop 1
	v_addc_co_u32_e32 v227, vcc, 0, v227, vcc
	global_load_dwordx2 v[120:121], v[226:227], off offset:1536
	v_add_co_u32_e32 v226, vcc, 0x6200, v226
	s_nop 1
	v_addc_co_u32_e32 v227, vcc, 0, v227, vcc
	global_load_dwordx2 v[122:123], v[226:227], off offset:1536
	v_add_co_u32_e32 v226, vcc, 0x6200, v226
	s_nop 1
	v_addc_co_u32_e32 v227, vcc, 0, v227, vcc
	global_load_dwordx2 v[124:125], v[226:227], off offset:1536
	v_add_co_u32_e32 v226, vcc, 0x6200, v226
	s_nop 1
	v_addc_co_u32_e32 v227, vcc, 0, v227, vcc
	global_load_dwordx2 v[126:127], v[226:227], off offset:1536
	v_add_co_u32_e32 v226, vcc, 0x6200, v226
	s_nop 1
	v_addc_co_u32_e32 v227, vcc, 0, v227, vcc
	global_load_dwordx2 v[128:129], v[226:227], off offset:1536
	v_add_co_u32_e32 v226, vcc, 0x6200, v226
	s_nop 1
	v_addc_co_u32_e32 v227, vcc, 0, v227, vcc
	global_load_dwordx2 v[130:131], v[226:227], off offset:1536
	v_add_co_u32_e32 v226, vcc, 0x6200, v226
	s_nop 1
	v_addc_co_u32_e32 v227, vcc, 0, v227, vcc
	global_load_dwordx2 v[132:133], v[226:227], off offset:1536
	v_add_co_u32_e32 v226, vcc, 0x6200, v226
	s_nop 1
	v_addc_co_u32_e32 v227, vcc, 0, v227, vcc
	global_load_dwordx2 v[134:135], v[226:227], off offset:1536
	v_add_co_u32_e32 v226, vcc, 0x6200, v226
	s_nop 1
	v_addc_co_u32_e32 v227, vcc, 0, v227, vcc
	global_load_dwordx2 v[136:137], v[226:227], off offset:1536
	v_add_co_u32_e32 v226, vcc, 0x6200, v226
	s_nop 1
	v_addc_co_u32_e32 v227, vcc, 0, v227, vcc
	global_load_dwordx2 v[138:139], v[226:227], off offset:1536
	v_add_co_u32_e32 v226, vcc, 0x6200, v226
	s_nop 1
	v_addc_co_u32_e32 v227, vcc, 0, v227, vcc
	global_load_dwordx2 v[140:141], v[226:227], off offset:1536
	v_add_co_u32_e32 v226, vcc, 0x6200, v226
	s_nop 1
	v_addc_co_u32_e32 v227, vcc, 0, v227, vcc
	global_load_dwordx2 v[142:143], v[226:227], off offset:1536
	v_add_co_u32_e32 v226, vcc, 0x6200, v226
	s_nop 1
	v_addc_co_u32_e32 v227, vcc, 0, v227, vcc
	global_load_dwordx2 v[144:145], v[226:227], off offset:1536
	v_add_co_u32_e32 v226, vcc, 0x6200, v226
	s_nop 1
	v_addc_co_u32_e32 v227, vcc, 0, v227, vcc
	global_load_dwordx2 v[146:147], v[226:227], off offset:1536
	v_add_co_u32_e32 v226, vcc, 0x6200, v226
	s_nop 1
	v_addc_co_u32_e32 v227, vcc, 0, v227, vcc
	global_load_dwordx2 v[148:149], v[226:227], off offset:1536
	v_add_co_u32_e32 v226, vcc, 0x6200, v226
	s_nop 1
	v_addc_co_u32_e32 v227, vcc, 0, v227, vcc
	global_load_dwordx2 v[150:151], v[226:227], off offset:1536
	v_add_u32_e32 v6, s0, v4
	v_add_u32_e32 v160, 0xbfb00000, v6
	v_lshl_add_u64 v[12:13], v[160:161], 1, s[46:47]
	v_lshlrev_b64 v[2:3], 1, v[88:89]
	v_lshl_add_u64 v[12:13], v[12:13], 0, v[2:3]
	v_mov_b32_e32 v1, v161
	v_lshl_add_u64 v[12:13], v[12:13], 0, v[0:1]
	v_add_co_u32_e32 v12, vcc, 0x1000, v12
	ds_read_b128 v[8:11], v5
	s_nop 0
	v_addc_co_u32_e32 v13, vcc, 0, v13, vcc
	v_add_u32_e32 v160, 0xbfb03100, v6
	s_add_i32 s0, s0, 0xc400
	s_cmp_lg_u32 s0, 0x31000
	s_waitcnt vmcnt(15)
	v_mov_b32_e32 v14, v120
	v_mov_b32_e32 v15, v121
	v_lshlrev_b32_e32 v16, 16, v14
	v_mul_f32_e32 v7, 0xbfb8aa3b, v16
	v_exp_f32_e32 v7, v7
	v_and_b32_e32 v17, 0xffff0000, v14
	v_lshlrev_b32_e32 v14, 16, v15
	v_and_b32_e32 v15, 0xffff0000, v15
	v_add_f32_e32 v7, 1.0, v7
	v_rcp_f32_e32 v18, v7
	v_mul_f32_e32 v7, 0xbfb8aa3b, v17
	v_exp_f32_e32 v7, v7
	s_nop 0
	v_add_f32_e32 v7, 1.0, v7
	v_rcp_f32_e32 v19, v7
	v_mul_f32_e32 v7, 0xbfb8aa3b, v14
	v_exp_f32_e32 v7, v7
	v_pk_mul_f32 v[16:17], v[18:19], v[16:17]
	s_waitcnt lgkmcnt(0)
	v_pk_mul_f32 v[8:9], v[8:9], v[16:17]
	v_add_f32_e32 v7, 1.0, v7
	v_rcp_f32_e32 v16, v7
	v_mul_f32_e32 v7, 0xbfb8aa3b, v15
	v_exp_f32_e32 v7, v7
	v_cvt_pk_bf16_f32 v8, v8, v9
	v_add_f32_e32 v7, 1.0, v7
	v_rcp_f32_e32 v17, v7
	s_nop 0
	v_pk_mul_f32 v[14:15], v[16:17], v[14:15]
	s_nop 0
	v_pk_mul_f32 v[10:11], v[10:11], v[14:15]
	s_nop 0
	v_cvt_pk_bf16_f32 v9, v10, v11
	global_store_dwordx2 v[12:13], v[8:9], off offset:1536
	v_lshl_add_u64 v[12:13], v[160:161], 1, s[46:47]
	v_lshl_add_u64 v[12:13], v[12:13], 0, v[2:3]
	v_lshl_add_u64 v[12:13], v[12:13], 0, v[0:1]
	v_add_co_u32_e32 v12, vcc, s13, v12
	ds_read_b128 v[8:11], v5 offset:1088
	s_nop 0
	v_addc_co_u32_e32 v13, vcc, 0, v13, vcc
	v_add_u32_e32 v160, 0xbfb06200, v6
	s_waitcnt vmcnt(15)
	v_mov_b32_e32 v14, v122
	v_mov_b32_e32 v15, v123
	v_lshlrev_b32_e32 v16, 16, v14
	v_mul_f32_e32 v7, 0xbfb8aa3b, v16
	v_exp_f32_e32 v7, v7
	v_and_b32_e32 v17, 0xffff0000, v14
	v_lshlrev_b32_e32 v14, 16, v15
	v_and_b32_e32 v15, 0xffff0000, v15
	v_add_f32_e32 v7, 1.0, v7
	v_rcp_f32_e32 v18, v7
	v_mul_f32_e32 v7, 0xbfb8aa3b, v17
	v_exp_f32_e32 v7, v7
	s_nop 0
	v_add_f32_e32 v7, 1.0, v7
	v_rcp_f32_e32 v19, v7
	v_mul_f32_e32 v7, 0xbfb8aa3b, v14
	v_exp_f32_e32 v7, v7
	v_pk_mul_f32 v[16:17], v[18:19], v[16:17]
	s_waitcnt lgkmcnt(0)
; DI float bflo(unsigned u) { return __uint_as_float(u << 16); }
; DI float bfhi(unsigned u) { return __uint_as_float(u & 0xffff0000u); }
; DI unsigned pk2(float lo, float hi) { f32x2 v = {lo, hi}; bfv2 b = __builtin_convertvector(v, bfv2); return __builtin_bit_cast(unsigned, b); }
; DI float silu(float x) { return x * __builtin_amdgcn_rcpf(1.f + __expf(-x)); }
; DI void pool_task(const Params& p, int layer, int tile, unsigned char* lds) {
;     ...
; #pragma unroll 4
;     for (int j = 0; j < 16; ++j) {
;       const int rl = 4 * j + rsub;
;       const f32x4 cv = *(const f32x4*)(Ct + rl * 68 + c4);
;       bf16_t* ptr = proj + (size_t)(t0 + rl) * PP + D_Z + 64 * g + c4;
;       const u32x2 zr = *(const u32x2*)ptr;
;       *(u32x2*)ptr = (u32x2){pk2(cv.x * silu(bflo(zr.x)), cv.y * silu(bfhi(zr.x))), pk2(cv.z * silu(bflo(zr.y)), cv.w * silu(bfhi(zr.y)))};
;     }
	v_pk_mul_f32 v[8:9], v[8:9], v[16:17]
	v_add_f32_e32 v7, 1.0, v7
	v_rcp_f32_e32 v16, v7
	v_mul_f32_e32 v7, 0xbfb8aa3b, v15
	v_exp_f32_e32 v7, v7
	v_cvt_pk_bf16_f32 v8, v8, v9
	v_add_f32_e32 v7, 1.0, v7
	v_rcp_f32_e32 v17, v7
	s_nop 0
	v_pk_mul_f32 v[14:15], v[16:17], v[14:15]
	s_nop 0
	v_pk_mul_f32 v[10:11], v[10:11], v[14:15]
	s_nop 0
	v_cvt_pk_bf16_f32 v9, v10, v11
	global_store_dwordx2 v[12:13], v[8:9], off offset:1536
	v_lshl_add_u64 v[12:13], v[160:161], 1, s[46:47]
	v_lshl_add_u64 v[12:13], v[12:13], 0, v[2:3]
	v_lshl_add_u64 v[12:13], v[12:13], 0, v[0:1]
	v_add_co_u32_e32 v12, vcc, s13, v12
	ds_read_b128 v[8:11], v5 offset:2176
	s_nop 0
	v_addc_co_u32_e32 v13, vcc, 0, v13, vcc
	v_add_u32_e32 v160, 0xbfb09300, v6
	s_waitcnt vmcnt(15)
	v_mov_b32_e32 v14, v124
	v_mov_b32_e32 v15, v125
	v_lshlrev_b32_e32 v16, 16, v14
	v_mul_f32_e32 v7, 0xbfb8aa3b, v16
	v_exp_f32_e32 v7, v7
	v_and_b32_e32 v17, 0xffff0000, v14
	v_lshlrev_b32_e32 v14, 16, v15
	v_and_b32_e32 v15, 0xffff0000, v15
	v_add_f32_e32 v7, 1.0, v7
	v_rcp_f32_e32 v18, v7
	v_mul_f32_e32 v7, 0xbfb8aa3b, v17
	v_exp_f32_e32 v7, v7
	s_nop 0
	v_add_f32_e32 v7, 1.0, v7
	v_rcp_f32_e32 v19, v7
	v_mul_f32_e32 v7, 0xbfb8aa3b, v14
	v_exp_f32_e32 v7, v7
	v_pk_mul_f32 v[16:17], v[18:19], v[16:17]
	s_waitcnt lgkmcnt(0)
	v_pk_mul_f32 v[8:9], v[8:9], v[16:17]
	v_add_f32_e32 v7, 1.0, v7
	v_rcp_f32_e32 v16, v7
	v_mul_f32_e32 v7, 0xbfb8aa3b, v15
	v_exp_f32_e32 v7, v7
	v_cvt_pk_bf16_f32 v8, v8, v9
	v_add_f32_e32 v7, 1.0, v7
	v_rcp_f32_e32 v17, v7
	v_lshl_add_u64 v[6:7], v[160:161], 1, s[46:47]
	v_lshl_add_u64 v[2:3], v[6:7], 0, v[2:3]
	v_lshl_add_u64 v[2:3], v[2:3], 0, v[0:1]
	v_add_co_u32_e32 v2, vcc, s13, v2
	v_pk_mul_f32 v[14:15], v[16:17], v[14:15]
	s_nop 0
	v_addc_co_u32_e32 v3, vcc, 0, v3, vcc
	v_pk_mul_f32 v[10:11], v[10:11], v[14:15]
	s_nop 0
	v_cvt_pk_bf16_f32 v9, v10, v11
	global_store_dwordx2 v[12:13], v[8:9], off offset:1536
	ds_read_b128 v[8:11], v5 offset:3264
	v_add_u32_e32 v5, 0x1100, v5
	s_waitcnt vmcnt(15)
	v_mov_b32_e32 v6, v126
	v_mov_b32_e32 v7, v127
	v_lshlrev_b32_e32 v12, 16, v6
	v_mul_f32_e32 v1, 0xbfb8aa3b, v12
	v_exp_f32_e32 v1, v1
	v_and_b32_e32 v13, 0xffff0000, v6
	v_add_f32_e32 v1, 1.0, v1
	v_rcp_f32_e32 v14, v1
	v_mul_f32_e32 v1, 0xbfb8aa3b, v13
	v_exp_f32_e32 v1, v1
	s_nop 0
	v_add_f32_e32 v1, 1.0, v1
	v_rcp_f32_e32 v15, v1
	s_nop 0
	v_pk_mul_f32 v[12:13], v[14:15], v[12:13]
	s_waitcnt lgkmcnt(0)
	v_pk_mul_f32 v[8:9], v[8:9], v[12:13]
	s_nop 0
	v_cvt_pk_bf16_f32 v6, v8, v9
	v_lshlrev_b32_e32 v8, 16, v7
	v_mul_f32_e32 v1, 0xbfb8aa3b, v8
	v_exp_f32_e32 v1, v1
	v_and_b32_e32 v9, 0xffff0000, v7
	v_add_f32_e32 v1, 1.0, v1
	v_rcp_f32_e32 v12, v1
	v_mul_f32_e32 v1, 0xbfb8aa3b, v9
	v_exp_f32_e32 v1, v1
	s_nop 0
	v_add_f32_e32 v1, 1.0, v1
	v_rcp_f32_e32 v13, v1
	s_nop 0
	v_pk_mul_f32 v[8:9], v[12:13], v[8:9]
	s_nop 0
	v_pk_mul_f32 v[8:9], v[10:11], v[8:9]
	s_nop 0
	v_cvt_pk_bf16_f32 v7, v8, v9
	global_store_dwordx2 v[2:3], v[6:7], off offset:1536
	v_add_u32_e32 v6, s0, v4
	v_add_u32_e32 v160, 0xbfb00000, v6
	v_lshl_add_u64 v[12:13], v[160:161], 1, s[46:47]
	v_lshlrev_b64 v[2:3], 1, v[88:89]
	v_lshl_add_u64 v[12:13], v[12:13], 0, v[2:3]
	v_mov_b32_e32 v1, v161
	v_lshl_add_u64 v[12:13], v[12:13], 0, v[0:1]
	v_add_co_u32_e32 v12, vcc, 0x1000, v12
	ds_read_b128 v[8:11], v5
	s_nop 0
	v_addc_co_u32_e32 v13, vcc, 0, v13, vcc
	v_add_u32_e32 v160, 0xbfb03100, v6
	s_add_i32 s0, s0, 0xc400
	s_cmp_lg_u32 s0, 0x31000
	s_waitcnt vmcnt(15)
	v_mov_b32_e32 v14, v128
	v_mov_b32_e32 v15, v129
	v_lshlrev_b32_e32 v16, 16, v14
	v_mul_f32_e32 v7, 0xbfb8aa3b, v16
	v_exp_f32_e32 v7, v7
	v_and_b32_e32 v17, 0xffff0000, v14
	v_lshlrev_b32_e32 v14, 16, v15
	v_and_b32_e32 v15, 0xffff0000, v15
	v_add_f32_e32 v7, 1.0, v7
	v_rcp_f32_e32 v18, v7
	v_mul_f32_e32 v7, 0xbfb8aa3b, v17
	v_exp_f32_e32 v7, v7
	s_nop 0
	v_add_f32_e32 v7, 1.0, v7
	v_rcp_f32_e32 v19, v7
	v_mul_f32_e32 v7, 0xbfb8aa3b, v14
	v_exp_f32_e32 v7, v7
	v_pk_mul_f32 v[16:17], v[18:19], v[16:17]
	s_waitcnt lgkmcnt(0)
	v_pk_mul_f32 v[8:9], v[8:9], v[16:17]
	v_add_f32_e32 v7, 1.0, v7
	v_rcp_f32_e32 v16, v7
	v_mul_f32_e32 v7, 0xbfb8aa3b, v15
	v_exp_f32_e32 v7, v7
	v_cvt_pk_bf16_f32 v8, v8, v9
	v_add_f32_e32 v7, 1.0, v7
	v_rcp_f32_e32 v17, v7
	s_nop 0
	v_pk_mul_f32 v[14:15], v[16:17], v[14:15]
	s_nop 0
	v_pk_mul_f32 v[10:11], v[10:11], v[14:15]
	s_nop 0
	v_cvt_pk_bf16_f32 v9, v10, v11
	global_store_dwordx2 v[12:13], v[8:9], off offset:1536
	v_lshl_add_u64 v[12:13], v[160:161], 1, s[46:47]
	v_lshl_add_u64 v[12:13], v[12:13], 0, v[2:3]
	v_lshl_add_u64 v[12:13], v[12:13], 0, v[0:1]
	v_add_co_u32_e32 v12, vcc, s13, v12
	ds_read_b128 v[8:11], v5 offset:1088
	s_nop 0
	v_addc_co_u32_e32 v13, vcc, 0, v13, vcc
	v_add_u32_e32 v160, 0xbfb06200, v6
	s_waitcnt vmcnt(15)
	v_mov_b32_e32 v14, v130
	v_mov_b32_e32 v15, v131
	v_lshlrev_b32_e32 v16, 16, v14
	v_mul_f32_e32 v7, 0xbfb8aa3b, v16
	v_exp_f32_e32 v7, v7
	v_and_b32_e32 v17, 0xffff0000, v14
	v_lshlrev_b32_e32 v14, 16, v15
	v_and_b32_e32 v15, 0xffff0000, v15
	v_add_f32_e32 v7, 1.0, v7
	v_rcp_f32_e32 v18, v7
	v_mul_f32_e32 v7, 0xbfb8aa3b, v17
	v_exp_f32_e32 v7, v7
	s_nop 0
	v_add_f32_e32 v7, 1.0, v7
	v_rcp_f32_e32 v19, v7
	v_mul_f32_e32 v7, 0xbfb8aa3b, v14
	v_exp_f32_e32 v7, v7
	v_pk_mul_f32 v[16:17], v[18:19], v[16:17]
	s_waitcnt lgkmcnt(0)
	v_pk_mul_f32 v[8:9], v[8:9], v[16:17]
	v_add_f32_e32 v7, 1.0, v7
	v_rcp_f32_e32 v16, v7
	v_mul_f32_e32 v7, 0xbfb8aa3b, v15
	v_exp_f32_e32 v7, v7
	v_cvt_pk_bf16_f32 v8, v8, v9
	v_add_f32_e32 v7, 1.0, v7
	v_rcp_f32_e32 v17, v7
	s_nop 0
	v_pk_mul_f32 v[14:15], v[16:17], v[14:15]
	s_nop 0
	v_pk_mul_f32 v[10:11], v[10:11], v[14:15]
	s_nop 0
	v_cvt_pk_bf16_f32 v9, v10, v11
	global_store_dwordx2 v[12:13], v[8:9], off offset:1536
	v_lshl_add_u64 v[12:13], v[160:161], 1, s[46:47]
	v_lshl_add_u64 v[12:13], v[12:13], 0, v[2:3]
	v_lshl_add_u64 v[12:13], v[12:13], 0, v[0:1]
	v_add_co_u32_e32 v12, vcc, s13, v12
	ds_read_b128 v[8:11], v5 offset:2176
	s_nop 0
	v_addc_co_u32_e32 v13, vcc, 0, v13, vcc
	v_add_u32_e32 v160, 0xbfb09300, v6
	s_waitcnt vmcnt(15)
; DI float bflo(unsigned u) { return __uint_as_float(u << 16); }
; DI float bfhi(unsigned u) { return __uint_as_float(u & 0xffff0000u); }
; DI unsigned pk2(float lo, float hi) { f32x2 v = {lo, hi}; bfv2 b = __builtin_convertvector(v, bfv2); return __builtin_bit_cast(unsigned, b); }
; DI float silu(float x) { return x * __builtin_amdgcn_rcpf(1.f + __expf(-x)); }
; DI void pool_task(const Params& p, int layer, int tile, unsigned char* lds) {
;     ...
; #pragma unroll 4
;     for (int j = 0; j < 16; ++j) {
;       const int rl = 4 * j + rsub;
;       const f32x4 cv = *(const f32x4*)(Ct + rl * 68 + c4);
;       bf16_t* ptr = proj + (size_t)(t0 + rl) * PP + D_Z + 64 * g + c4;
;       const u32x2 zr = *(const u32x2*)ptr;
;       *(u32x2*)ptr = (u32x2){pk2(cv.x * silu(bflo(zr.x)), cv.y * silu(bfhi(zr.x))), pk2(cv.z * silu(bflo(zr.y)), cv.w * silu(bfhi(zr.y)))};
;     }
	v_mov_b32_e32 v14, v132
	v_mov_b32_e32 v15, v133
	v_lshlrev_b32_e32 v16, 16, v14
	v_mul_f32_e32 v7, 0xbfb8aa3b, v16
	v_exp_f32_e32 v7, v7
	v_and_b32_e32 v17, 0xffff0000, v14
	v_lshlrev_b32_e32 v14, 16, v15
	v_and_b32_e32 v15, 0xffff0000, v15
	v_add_f32_e32 v7, 1.0, v7
	v_rcp_f32_e32 v18, v7
	v_mul_f32_e32 v7, 0xbfb8aa3b, v17
	v_exp_f32_e32 v7, v7
	s_nop 0
	v_add_f32_e32 v7, 1.0, v7
	v_rcp_f32_e32 v19, v7
	v_mul_f32_e32 v7, 0xbfb8aa3b, v14
	v_exp_f32_e32 v7, v7
	v_pk_mul_f32 v[16:17], v[18:19], v[16:17]
	s_waitcnt lgkmcnt(0)
	v_pk_mul_f32 v[8:9], v[8:9], v[16:17]
	v_add_f32_e32 v7, 1.0, v7
	v_rcp_f32_e32 v16, v7
	v_mul_f32_e32 v7, 0xbfb8aa3b, v15
	v_exp_f32_e32 v7, v7
	v_cvt_pk_bf16_f32 v8, v8, v9
	v_add_f32_e32 v7, 1.0, v7
	v_rcp_f32_e32 v17, v7
	v_lshl_add_u64 v[6:7], v[160:161], 1, s[46:47]
	v_lshl_add_u64 v[2:3], v[6:7], 0, v[2:3]
	v_lshl_add_u64 v[2:3], v[2:3], 0, v[0:1]
	v_add_co_u32_e32 v2, vcc, s13, v2
	v_pk_mul_f32 v[14:15], v[16:17], v[14:15]
	s_nop 0
	v_addc_co_u32_e32 v3, vcc, 0, v3, vcc
	v_pk_mul_f32 v[10:11], v[10:11], v[14:15]
	s_nop 0
	v_cvt_pk_bf16_f32 v9, v10, v11
	global_store_dwordx2 v[12:13], v[8:9], off offset:1536
	ds_read_b128 v[8:11], v5 offset:3264
	v_add_u32_e32 v5, 0x1100, v5
	s_waitcnt vmcnt(15)
	v_mov_b32_e32 v6, v134
	v_mov_b32_e32 v7, v135
	v_lshlrev_b32_e32 v12, 16, v6
	v_mul_f32_e32 v1, 0xbfb8aa3b, v12
	v_exp_f32_e32 v1, v1
	v_and_b32_e32 v13, 0xffff0000, v6
	v_add_f32_e32 v1, 1.0, v1
	v_rcp_f32_e32 v14, v1
	v_mul_f32_e32 v1, 0xbfb8aa3b, v13
	v_exp_f32_e32 v1, v1
	s_nop 0
	v_add_f32_e32 v1, 1.0, v1
	v_rcp_f32_e32 v15, v1
	s_nop 0
	v_pk_mul_f32 v[12:13], v[14:15], v[12:13]
	s_waitcnt lgkmcnt(0)
	v_pk_mul_f32 v[8:9], v[8:9], v[12:13]
	s_nop 0
	v_cvt_pk_bf16_f32 v6, v8, v9
	v_lshlrev_b32_e32 v8, 16, v7
	v_mul_f32_e32 v1, 0xbfb8aa3b, v8
	v_exp_f32_e32 v1, v1
	v_and_b32_e32 v9, 0xffff0000, v7
	v_add_f32_e32 v1, 1.0, v1
	v_rcp_f32_e32 v12, v1
	v_mul_f32_e32 v1, 0xbfb8aa3b, v9
	v_exp_f32_e32 v1, v1
	s_nop 0
	v_add_f32_e32 v1, 1.0, v1
	v_rcp_f32_e32 v13, v1
	s_nop 0
	v_pk_mul_f32 v[8:9], v[12:13], v[8:9]
	s_nop 0
	v_pk_mul_f32 v[8:9], v[10:11], v[8:9]
	s_nop 0
	v_cvt_pk_bf16_f32 v7, v8, v9
	global_store_dwordx2 v[2:3], v[6:7], off offset:1536
	v_add_u32_e32 v6, s0, v4
	v_add_u32_e32 v160, 0xbfb00000, v6
	v_lshl_add_u64 v[12:13], v[160:161], 1, s[46:47]
	v_lshlrev_b64 v[2:3], 1, v[88:89]
	v_lshl_add_u64 v[12:13], v[12:13], 0, v[2:3]
	v_mov_b32_e32 v1, v161
	v_lshl_add_u64 v[12:13], v[12:13], 0, v[0:1]
	v_add_co_u32_e32 v12, vcc, 0x1000, v12
	ds_read_b128 v[8:11], v5
	s_nop 0
	v_addc_co_u32_e32 v13, vcc, 0, v13, vcc
	v_add_u32_e32 v160, 0xbfb03100, v6
	s_add_i32 s0, s0, 0xc400
	s_cmp_lg_u32 s0, 0x31000
	s_waitcnt vmcnt(15)
	v_mov_b32_e32 v14, v136
	v_mov_b32_e32 v15, v137
	v_lshlrev_b32_e32 v16, 16, v14
	v_mul_f32_e32 v7, 0xbfb8aa3b, v16
	v_exp_f32_e32 v7, v7
	v_and_b32_e32 v17, 0xffff0000, v14
	v_lshlrev_b32_e32 v14, 16, v15
	v_and_b32_e32 v15, 0xffff0000, v15
	v_add_f32_e32 v7, 1.0, v7
	v_rcp_f32_e32 v18, v7
	v_mul_f32_e32 v7, 0xbfb8aa3b, v17
	v_exp_f32_e32 v7, v7
	s_nop 0
	v_add_f32_e32 v7, 1.0, v7
	v_rcp_f32_e32 v19, v7
	v_mul_f32_e32 v7, 0xbfb8aa3b, v14
	v_exp_f32_e32 v7, v7
	v_pk_mul_f32 v[16:17], v[18:19], v[16:17]
	s_waitcnt lgkmcnt(0)
	v_pk_mul_f32 v[8:9], v[8:9], v[16:17]
	v_add_f32_e32 v7, 1.0, v7
	v_rcp_f32_e32 v16, v7
	v_mul_f32_e32 v7, 0xbfb8aa3b, v15
	v_exp_f32_e32 v7, v7
	v_cvt_pk_bf16_f32 v8, v8, v9
	v_add_f32_e32 v7, 1.0, v7
	v_rcp_f32_e32 v17, v7
	s_nop 0
	v_pk_mul_f32 v[14:15], v[16:17], v[14:15]
	s_nop 0
	v_pk_mul_f32 v[10:11], v[10:11], v[14:15]
	s_nop 0
	v_cvt_pk_bf16_f32 v9, v10, v11
	global_store_dwordx2 v[12:13], v[8:9], off offset:1536
	v_lshl_add_u64 v[12:13], v[160:161], 1, s[46:47]
	v_lshl_add_u64 v[12:13], v[12:13], 0, v[2:3]
	v_lshl_add_u64 v[12:13], v[12:13], 0, v[0:1]
	v_add_co_u32_e32 v12, vcc, s13, v12
	ds_read_b128 v[8:11], v5 offset:1088
	s_nop 0
	v_addc_co_u32_e32 v13, vcc, 0, v13, vcc
	v_add_u32_e32 v160, 0xbfb06200, v6
	s_waitcnt vmcnt(15)
	v_mov_b32_e32 v14, v138
	v_mov_b32_e32 v15, v139
	v_lshlrev_b32_e32 v16, 16, v14
	v_mul_f32_e32 v7, 0xbfb8aa3b, v16
	v_exp_f32_e32 v7, v7
	v_and_b32_e32 v17, 0xffff0000, v14
	v_lshlrev_b32_e32 v14, 16, v15
	v_and_b32_e32 v15, 0xffff0000, v15
	v_add_f32_e32 v7, 1.0, v7
	v_rcp_f32_e32 v18, v7
	v_mul_f32_e32 v7, 0xbfb8aa3b, v17
	v_exp_f32_e32 v7, v7
	s_nop 0
	v_add_f32_e32 v7, 1.0, v7
	v_rcp_f32_e32 v19, v7
	v_mul_f32_e32 v7, 0xbfb8aa3b, v14
	v_exp_f32_e32 v7, v7
	v_pk_mul_f32 v[16:17], v[18:19], v[16:17]
	s_waitcnt lgkmcnt(0)
	v_pk_mul_f32 v[8:9], v[8:9], v[16:17]
	v_add_f32_e32 v7, 1.0, v7
	v_rcp_f32_e32 v16, v7
	v_mul_f32_e32 v7, 0xbfb8aa3b, v15
	v_exp_f32_e32 v7, v7
	v_cvt_pk_bf16_f32 v8, v8, v9
	v_add_f32_e32 v7, 1.0, v7
	v_rcp_f32_e32 v17, v7
	s_nop 0
	v_pk_mul_f32 v[14:15], v[16:17], v[14:15]
	s_nop 0
	v_pk_mul_f32 v[10:11], v[10:11], v[14:15]
	s_nop 0
	v_cvt_pk_bf16_f32 v9, v10, v11
	global_store_dwordx2 v[12:13], v[8:9], off offset:1536
	v_lshl_add_u64 v[12:13], v[160:161], 1, s[46:47]
	v_lshl_add_u64 v[12:13], v[12:13], 0, v[2:3]
	v_lshl_add_u64 v[12:13], v[12:13], 0, v[0:1]
	v_add_co_u32_e32 v12, vcc, s13, v12
	ds_read_b128 v[8:11], v5 offset:2176
	s_nop 0
	v_addc_co_u32_e32 v13, vcc, 0, v13, vcc
	v_add_u32_e32 v160, 0xbfb09300, v6
	s_waitcnt vmcnt(15)
	v_mov_b32_e32 v14, v140
	v_mov_b32_e32 v15, v141
	v_lshlrev_b32_e32 v16, 16, v14
	v_mul_f32_e32 v7, 0xbfb8aa3b, v16
	v_exp_f32_e32 v7, v7
	v_and_b32_e32 v17, 0xffff0000, v14
	v_lshlrev_b32_e32 v14, 16, v15
	v_and_b32_e32 v15, 0xffff0000, v15
	v_add_f32_e32 v7, 1.0, v7
	v_rcp_f32_e32 v18, v7
	v_mul_f32_e32 v7, 0xbfb8aa3b, v17
	v_exp_f32_e32 v7, v7
	s_nop 0
	v_add_f32_e32 v7, 1.0, v7
	v_rcp_f32_e32 v19, v7
	v_mul_f32_e32 v7, 0xbfb8aa3b, v14
	v_exp_f32_e32 v7, v7
	v_pk_mul_f32 v[16:17], v[18:19], v[16:17]
	s_waitcnt lgkmcnt(0)
; DI float bflo(unsigned u) { return __uint_as_float(u << 16); }
; DI float bfhi(unsigned u) { return __uint_as_float(u & 0xffff0000u); }
; DI unsigned pk2(float lo, float hi) { f32x2 v = {lo, hi}; bfv2 b = __builtin_convertvector(v, bfv2); return __builtin_bit_cast(unsigned, b); }
; DI float silu(float x) { return x * __builtin_amdgcn_rcpf(1.f + __expf(-x)); }
; DI void pool_task(const Params& p, int layer, int tile, unsigned char* lds) {
;     ...
; #pragma unroll 4
;     for (int j = 0; j < 16; ++j) {
;       const int rl = 4 * j + rsub;
;       const f32x4 cv = *(const f32x4*)(Ct + rl * 68 + c4);
;       bf16_t* ptr = proj + (size_t)(t0 + rl) * PP + D_Z + 64 * g + c4;
;       const u32x2 zr = *(const u32x2*)ptr;
;       *(u32x2*)ptr = (u32x2){pk2(cv.x * silu(bflo(zr.x)), cv.y * silu(bfhi(zr.x))), pk2(cv.z * silu(bflo(zr.y)), cv.w * silu(bfhi(zr.y)))};
;     }
	v_pk_mul_f32 v[8:9], v[8:9], v[16:17]
	v_add_f32_e32 v7, 1.0, v7
	v_rcp_f32_e32 v16, v7
	v_mul_f32_e32 v7, 0xbfb8aa3b, v15
	v_exp_f32_e32 v7, v7
	v_cvt_pk_bf16_f32 v8, v8, v9
	v_add_f32_e32 v7, 1.0, v7
	v_rcp_f32_e32 v17, v7
	v_lshl_add_u64 v[6:7], v[160:161], 1, s[46:47]
	v_lshl_add_u64 v[2:3], v[6:7], 0, v[2:3]
	v_lshl_add_u64 v[2:3], v[2:3], 0, v[0:1]
	v_add_co_u32_e32 v2, vcc, s13, v2
	v_pk_mul_f32 v[14:15], v[16:17], v[14:15]
	s_nop 0
	v_addc_co_u32_e32 v3, vcc, 0, v3, vcc
	v_pk_mul_f32 v[10:11], v[10:11], v[14:15]
	s_nop 0
	v_cvt_pk_bf16_f32 v9, v10, v11
	global_store_dwordx2 v[12:13], v[8:9], off offset:1536
	ds_read_b128 v[8:11], v5 offset:3264
	v_add_u32_e32 v5, 0x1100, v5
	s_waitcnt vmcnt(15)
	v_mov_b32_e32 v6, v142
	v_mov_b32_e32 v7, v143
	v_lshlrev_b32_e32 v12, 16, v6
	v_mul_f32_e32 v1, 0xbfb8aa3b, v12
	v_exp_f32_e32 v1, v1
	v_and_b32_e32 v13, 0xffff0000, v6
	v_add_f32_e32 v1, 1.0, v1
	v_rcp_f32_e32 v14, v1
	v_mul_f32_e32 v1, 0xbfb8aa3b, v13
	v_exp_f32_e32 v1, v1
	s_nop 0
	v_add_f32_e32 v1, 1.0, v1
	v_rcp_f32_e32 v15, v1
	s_nop 0
	v_pk_mul_f32 v[12:13], v[14:15], v[12:13]
	s_waitcnt lgkmcnt(0)
	v_pk_mul_f32 v[8:9], v[8:9], v[12:13]
	s_nop 0
	v_cvt_pk_bf16_f32 v6, v8, v9
	v_lshlrev_b32_e32 v8, 16, v7
	v_mul_f32_e32 v1, 0xbfb8aa3b, v8
	v_exp_f32_e32 v1, v1
	v_and_b32_e32 v9, 0xffff0000, v7
	v_add_f32_e32 v1, 1.0, v1
	v_rcp_f32_e32 v12, v1
	v_mul_f32_e32 v1, 0xbfb8aa3b, v9
	v_exp_f32_e32 v1, v1
	s_nop 0
	v_add_f32_e32 v1, 1.0, v1
	v_rcp_f32_e32 v13, v1
	s_nop 0
	v_pk_mul_f32 v[8:9], v[12:13], v[8:9]
	s_nop 0
	v_pk_mul_f32 v[8:9], v[10:11], v[8:9]
	s_nop 0
	v_cvt_pk_bf16_f32 v7, v8, v9
	global_store_dwordx2 v[2:3], v[6:7], off offset:1536
	v_add_u32_e32 v6, s0, v4
	v_add_u32_e32 v160, 0xbfb00000, v6
	v_lshl_add_u64 v[12:13], v[160:161], 1, s[46:47]
	v_lshlrev_b64 v[2:3], 1, v[88:89]
	v_lshl_add_u64 v[12:13], v[12:13], 0, v[2:3]
	v_mov_b32_e32 v1, v161
	v_lshl_add_u64 v[12:13], v[12:13], 0, v[0:1]
	v_add_co_u32_e32 v12, vcc, 0x1000, v12
	ds_read_b128 v[8:11], v5
	s_nop 0
	v_addc_co_u32_e32 v13, vcc, 0, v13, vcc
	v_add_u32_e32 v160, 0xbfb03100, v6
	s_add_i32 s0, s0, 0xc400
	s_cmp_lg_u32 s0, 0x31000
	s_waitcnt vmcnt(15)
	v_mov_b32_e32 v14, v144
	v_mov_b32_e32 v15, v145
	v_lshlrev_b32_e32 v16, 16, v14
	v_mul_f32_e32 v7, 0xbfb8aa3b, v16
	v_exp_f32_e32 v7, v7
	v_and_b32_e32 v17, 0xffff0000, v14
	v_lshlrev_b32_e32 v14, 16, v15
	v_and_b32_e32 v15, 0xffff0000, v15
	v_add_f32_e32 v7, 1.0, v7
	v_rcp_f32_e32 v18, v7
	v_mul_f32_e32 v7, 0xbfb8aa3b, v17
	v_exp_f32_e32 v7, v7
	s_nop 0
	v_add_f32_e32 v7, 1.0, v7
	v_rcp_f32_e32 v19, v7
	v_mul_f32_e32 v7, 0xbfb8aa3b, v14
	v_exp_f32_e32 v7, v7
	v_pk_mul_f32 v[16:17], v[18:19], v[16:17]
	s_waitcnt lgkmcnt(0)
	v_pk_mul_f32 v[8:9], v[8:9], v[16:17]
	v_add_f32_e32 v7, 1.0, v7
	v_rcp_f32_e32 v16, v7
	v_mul_f32_e32 v7, 0xbfb8aa3b, v15
	v_exp_f32_e32 v7, v7
	v_cvt_pk_bf16_f32 v8, v8, v9
	v_add_f32_e32 v7, 1.0, v7
	v_rcp_f32_e32 v17, v7
	s_nop 0
	v_pk_mul_f32 v[14:15], v[16:17], v[14:15]
	s_nop 0
	v_pk_mul_f32 v[10:11], v[10:11], v[14:15]
	s_nop 0
	v_cvt_pk_bf16_f32 v9, v10, v11
	global_store_dwordx2 v[12:13], v[8:9], off offset:1536
	v_lshl_add_u64 v[12:13], v[160:161], 1, s[46:47]
	v_lshl_add_u64 v[12:13], v[12:13], 0, v[2:3]
	v_lshl_add_u64 v[12:13], v[12:13], 0, v[0:1]
	v_add_co_u32_e32 v12, vcc, s13, v12
	ds_read_b128 v[8:11], v5 offset:1088
	s_nop 0
	v_addc_co_u32_e32 v13, vcc, 0, v13, vcc
	v_add_u32_e32 v160, 0xbfb06200, v6
	s_waitcnt vmcnt(15)
	v_mov_b32_e32 v14, v146
	v_mov_b32_e32 v15, v147
	v_lshlrev_b32_e32 v16, 16, v14
	v_mul_f32_e32 v7, 0xbfb8aa3b, v16
	v_exp_f32_e32 v7, v7
	v_and_b32_e32 v17, 0xffff0000, v14
	v_lshlrev_b32_e32 v14, 16, v15
	v_and_b32_e32 v15, 0xffff0000, v15
	v_add_f32_e32 v7, 1.0, v7
	v_rcp_f32_e32 v18, v7
	v_mul_f32_e32 v7, 0xbfb8aa3b, v17
	v_exp_f32_e32 v7, v7
	s_nop 0
	v_add_f32_e32 v7, 1.0, v7
	v_rcp_f32_e32 v19, v7
	v_mul_f32_e32 v7, 0xbfb8aa3b, v14
	v_exp_f32_e32 v7, v7
	v_pk_mul_f32 v[16:17], v[18:19], v[16:17]
	s_waitcnt lgkmcnt(0)
	v_pk_mul_f32 v[8:9], v[8:9], v[16:17]
	v_add_f32_e32 v7, 1.0, v7
	v_rcp_f32_e32 v16, v7
	v_mul_f32_e32 v7, 0xbfb8aa3b, v15
	v_exp_f32_e32 v7, v7
	v_cvt_pk_bf16_f32 v8, v8, v9
	v_add_f32_e32 v7, 1.0, v7
	v_rcp_f32_e32 v17, v7
	s_nop 0
	v_pk_mul_f32 v[14:15], v[16:17], v[14:15]
	s_nop 0
	v_pk_mul_f32 v[10:11], v[10:11], v[14:15]
	s_nop 0
	v_cvt_pk_bf16_f32 v9, v10, v11
	global_store_dwordx2 v[12:13], v[8:9], off offset:1536
	v_lshl_add_u64 v[12:13], v[160:161], 1, s[46:47]
	v_lshl_add_u64 v[12:13], v[12:13], 0, v[2:3]
	v_lshl_add_u64 v[12:13], v[12:13], 0, v[0:1]
	v_add_co_u32_e32 v12, vcc, s13, v12
	ds_read_b128 v[8:11], v5 offset:2176
	s_nop 0
	v_addc_co_u32_e32 v13, vcc, 0, v13, vcc
	v_add_u32_e32 v160, 0xbfb09300, v6
	s_waitcnt vmcnt(15)
	v_mov_b32_e32 v14, v148
	v_mov_b32_e32 v15, v149
	v_lshlrev_b32_e32 v16, 16, v14
	v_mul_f32_e32 v7, 0xbfb8aa3b, v16
	v_exp_f32_e32 v7, v7
	v_and_b32_e32 v17, 0xffff0000, v14
	v_lshlrev_b32_e32 v14, 16, v15
	v_and_b32_e32 v15, 0xffff0000, v15
	v_add_f32_e32 v7, 1.0, v7
	v_rcp_f32_e32 v18, v7
	v_mul_f32_e32 v7, 0xbfb8aa3b, v17
	v_exp_f32_e32 v7, v7
	s_nop 0
	v_add_f32_e32 v7, 1.0, v7
	v_rcp_f32_e32 v19, v7
	v_mul_f32_e32 v7, 0xbfb8aa3b, v14
	v_exp_f32_e32 v7, v7
	v_pk_mul_f32 v[16:17], v[18:19], v[16:17]
	s_waitcnt lgkmcnt(0)
	v_pk_mul_f32 v[8:9], v[8:9], v[16:17]
	v_add_f32_e32 v7, 1.0, v7
	v_rcp_f32_e32 v16, v7
	v_mul_f32_e32 v7, 0xbfb8aa3b, v15
	v_exp_f32_e32 v7, v7
	v_cvt_pk_bf16_f32 v8, v8, v9
	v_add_f32_e32 v7, 1.0, v7
	v_rcp_f32_e32 v17, v7
	v_lshl_add_u64 v[6:7], v[160:161], 1, s[46:47]
	v_lshl_add_u64 v[2:3], v[6:7], 0, v[2:3]
	v_lshl_add_u64 v[2:3], v[2:3], 0, v[0:1]
	v_add_co_u32_e32 v2, vcc, s13, v2
	v_pk_mul_f32 v[14:15], v[16:17], v[14:15]
	s_nop 0
	v_addc_co_u32_e32 v3, vcc, 0, v3, vcc
	v_pk_mul_f32 v[10:11], v[10:11], v[14:15]
	s_nop 0
	v_cvt_pk_bf16_f32 v9, v10, v11
	global_store_dwordx2 v[12:13], v[8:9], off offset:1536
	ds_read_b128 v[8:11], v5 offset:3264
	v_add_u32_e32 v5, 0x1100, v5
	s_waitcnt vmcnt(15)
	v_mov_b32_e32 v6, v150
	v_mov_b32_e32 v7, v151
	v_lshlrev_b32_e32 v12, 16, v6
	v_mul_f32_e32 v1, 0xbfb8aa3b, v12
	v_exp_f32_e32 v1, v1
	v_and_b32_e32 v13, 0xffff0000, v6
	v_add_f32_e32 v1, 1.0, v1
	v_rcp_f32_e32 v14, v1
	v_mul_f32_e32 v1, 0xbfb8aa3b, v13
	v_exp_f32_e32 v1, v1
	s_nop 0
	v_add_f32_e32 v1, 1.0, v1
	v_rcp_f32_e32 v15, v1
	s_nop 0
	v_pk_mul_f32 v[12:13], v[14:15], v[12:13]
	s_waitcnt lgkmcnt(0)
	v_pk_mul_f32 v[8:9], v[8:9], v[12:13]
	s_nop 0
	v_cvt_pk_bf16_f32 v6, v8, v9
	v_lshlrev_b32_e32 v8, 16, v7
	v_mul_f32_e32 v1, 0xbfb8aa3b, v8
	v_exp_f32_e32 v1, v1
	v_and_b32_e32 v9, 0xffff0000, v7
	v_add_f32_e32 v1, 1.0, v1
	v_rcp_f32_e32 v12, v1
	v_mul_f32_e32 v1, 0xbfb8aa3b, v9
	v_exp_f32_e32 v1, v1
	s_nop 0
	v_add_f32_e32 v1, 1.0, v1
	v_rcp_f32_e32 v13, v1
	s_nop 0
	v_pk_mul_f32 v[8:9], v[12:13], v[8:9]
	s_nop 0
	v_pk_mul_f32 v[8:9], v[10:11], v[8:9]
	s_nop 0
	v_cvt_pk_bf16_f32 v7, v8, v9
	global_store_dwordx2 v[2:3], v[6:7], off offset:1536
	s_barrier
	s_mov_b64 s[0:1], 0
; DI bf16_t f2bf(float x) { return (bf16_t)(pk2(x, 0.f) & 0xffffu); }
; DI void unpack8(u32x4 v, float* x) { x[0] = bflo(v.x); x[1] = bfhi(v.x); x[2] = bflo(v.y); x[3] = bfhi(v.y); x[4] = bflo(v.z); x[5] = bfhi(v.z); x[6] = bflo(v.w); x[7] = bfhi(v.w); }
; DI void sgu_task(const Params& p, int layer, int chunk, int h, unsigned char* lds) {
;     ...
;   {
;     const int j = tid >> 1, half = tid & 1;
;     const bf16_t* src = proj + (size_t)(t0 + j) * PP + A_V + 64 * h + half * 32;
;     float x[32];
; #pragma unroll
;     for (int i = 0; i < 4; ++i) unpack8(*(const u32x4*)(src + 8 * i), x + 8 * i);
;     float ss = 0.f;
; #pragma unroll
;     for (int e = 0; e < 32; ++e) ss += x[e] * x[e];
;     ss += __shfl_xor(ss, 1);
;     const float rn = rsqrtf(ss * (1.f / 64.f) + EPSF);
; #pragma unroll
;     for (int e = 0; e < 32; ++e) vT[(half * 32 + e) * 136 + j] = f2bf(x[e] * rn);
.LBB0_174:
	s_and_b64 vcc, exec, s[0:1]
	s_cbranch_vccz .LBB0_178
	s_lshl_b32 s1, s4, 5
	v_mov_b32_e32 v35, v180
	s_and_b32 s9, s1, 0x3ff80
	s_add_i32 s8, s9, 0xfffe2000
	v_ashrrev_i32_e32 v0, 1, v35
	v_add_u32_e32 v2, s8, v0
	v_mov_b64_e32 v[0:1], s[46:47]
	s_and_b32 s0, s4, 3
	v_mad_i64_i32 v[0:1], s[6:7], v2, s12, v[0:1]
	v_lshlrev_b32_e32 v2, 5, v35
	s_lshl_b32 s84, s0, 7
	v_and_b32_e32 v30, 32, v2
	v_lshl_add_u64 v[0:1], v[0:1], 0, s[84:85]
	v_lshlrev_b32_e32 v160, 1, v30
	v_lshl_add_u64 v[8:9], v[0:1], 0, v[160:161]
	global_load_dwordx4 v[36:39], v[8:9], off offset:560
	global_load_dwordx4 v[0:3], v[8:9], off offset:544
	global_load_dwordx4 v[4:7], v[8:9], off offset:528
	s_nop 0
	global_load_dwordx4 v[8:11], v[8:9], off offset:512
	v_cmp_lt_i32_e32 vcc, v185, v187
	v_ashrrev_i32_e32 v33, 6, v35
	v_mul_u32_u24_e32 v30, 0x110, v30
	v_and_b32_e32 v32, 31, v35
	v_readlane_b32 s2, v247, 24
	v_readlane_b32 s3, v247, 25
	s_waitcnt vmcnt(2) lgkmcnt(0)
	v_lshlrev_b32_e32 v15, 16, v0
	s_waitcnt vmcnt(1)
	v_lshlrev_b32_e32 v23, 16, v4
	s_waitcnt vmcnt(0)
	v_and_b32_e32 v31, 0xffff0000, v8
	v_lshlrev_b32_e32 v34, 16, v8
	v_lshlrev_b32_e32 v27, 16, v10
	v_and_b32_e32 v26, 0xffff0000, v10
	v_lshlrev_b32_e32 v25, 16, v11
	v_and_b32_e32 v24, 0xffff0000, v11
	v_lshlrev_b32_e32 v11, 16, v2
	v_and_b32_e32 v10, 0xffff0000, v2
	v_mul_f32_e32 v2, v31, v31
	v_lshlrev_b32_e32 v29, 16, v9
	v_fmac_f32_e32 v2, v34, v34
	v_and_b32_e32 v28, 0xffff0000, v9
	v_fmac_f32_e32 v2, v29, v29
	v_fmac_f32_e32 v2, v28, v28
	v_fmac_f32_e32 v2, v27, v27
	v_fmac_f32_e32 v2, v26, v26
	v_fmac_f32_e32 v2, v25, v25
	v_fmac_f32_e32 v2, v24, v24
	v_and_b32_e32 v22, 0xffff0000, v4
	v_fmac_f32_e32 v2, v23, v23
	v_lshlrev_b32_e32 v21, 16, v5
	v_fmac_f32_e32 v2, v22, v22
	v_and_b32_e32 v20, 0xffff0000, v5
	v_fmac_f32_e32 v2, v21, v21
	v_lshlrev_b32_e32 v19, 16, v6
	v_fmac_f32_e32 v2, v20, v20
	v_and_b32_e32 v18, 0xffff0000, v6
	v_fmac_f32_e32 v2, v19, v19
	v_lshlrev_b32_e32 v17, 16, v7
	v_fmac_f32_e32 v2, v18, v18
	v_and_b32_e32 v16, 0xffff0000, v7
	v_fmac_f32_e32 v2, v17, v17
	v_fmac_f32_e32 v2, v16, v16
	v_and_b32_e32 v14, 0xffff0000, v0
	v_fmac_f32_e32 v2, v15, v15
	v_lshlrev_b32_e32 v13, 16, v1
	v_fmac_f32_e32 v2, v14, v14
	v_and_b32_e32 v12, 0xffff0000, v1
	v_fmac_f32_e32 v2, v13, v13
	v_fmac_f32_e32 v2, v12, v12
	v_fmac_f32_e32 v2, v11, v11
	v_and_b32_e32 v8, 0xffff0000, v3
	v_lshlrev_b32_e32 v9, 16, v3
	v_fmac_f32_e32 v2, v10, v10
	v_pk_mul_f32 v[0:1], v[8:9], v[8:9]
	v_and_b32_e32 v6, 0xffff0000, v36
	v_add_f32_e32 v1, v1, v2
	v_lshlrev_b32_e32 v7, 16, v36
	v_add_f32_e32 v2, v0, v1
	v_pk_mul_f32 v[0:1], v[6:7], v[6:7]
	v_and_b32_e32 v4, 0xffff0000, v37
	v_add_f32_e32 v1, v1, v2
	v_lshlrev_b32_e32 v5, 16, v37
	v_add_f32_e32 v2, v0, v1
	v_pk_mul_f32 v[0:1], v[4:5], v[4:5]
	v_lshlrev_b32_e32 v3, 16, v38
	v_add_f32_e32 v1, v1, v2
	v_and_b32_e32 v2, 0xffff0000, v38
	v_add_f32_e32 v36, v0, v1
	v_pk_mul_f32 v[0:1], v[2:3], v[2:3]
	s_nop 0
	v_add_f32_e32 v1, v1, v36
	v_add_f32_e32 v38, v0, v1
	v_and_b32_e32 v0, 0xffff0000, v39
	v_lshlrev_b32_e32 v1, 16, v39
	v_pk_mul_f32 v[36:37], v[0:1], v[0:1]
	s_nop 0
	v_add_f32_e32 v37, v37, v38
	v_add_f32_e32 v36, v36, v37
	v_cndmask_b32_e32 v37, v184, v185, vcc
	v_lshlrev_b32_e32 v37, 2, v37
	ds_bpermute_b32 v37, v37, v36
	s_waitcnt lgkmcnt(0)
	v_add_f32_e32 v36, v36, v37
	v_fmamk_f32 v36, v36, 0x3c800000, v181
	v_cmp_gt_f32_e32 vcc, s44, v36
	v_mul_f32_e32 v37, 0x4b800000, v36
	s_nop 0
	v_cndmask_b32_e32 v36, v36, v37, vcc
	v_rsq_f32_e32 v36, v36
	s_nop 0
	v_mul_f32_e32 v37, 0x45800000, v36
	v_cndmask_b32_e32 v36, v36, v37, vcc
	v_mul_f32_e32 v34, v36, v34
	v_mul_f32_e32 v31, v36, v31
	v_mul_f32_e32 v29, v36, v29
	v_mul_f32_e32 v28, v36, v28
	v_mul_f32_e32 v27, v36, v27
	v_mul_f32_e32 v26, v36, v26
	v_mul_f32_e32 v25, v36, v25
	v_mul_f32_e32 v24, v36, v24
	v_mul_f32_e32 v23, v36, v23
	v_mul_f32_e32 v22, v36, v22
	v_mul_f32_e32 v21, v36, v21
	v_mul_f32_e32 v20, v36, v20
	v_mul_f32_e32 v19, v36, v19
	v_mul_f32_e32 v18, v36, v18
	v_mul_f32_e32 v17, v36, v17
	v_mul_f32_e32 v16, v36, v16
	v_mul_f32_e32 v15, v36, v15
	v_mul_f32_e32 v14, v36, v14
	v_mul_f32_e32 v13, v36, v13
	v_mul_f32_e32 v12, v36, v12
	v_mul_f32_e32 v11, v36, v11
	v_mul_f32_e32 v10, v36, v10
	v_mul_f32_e32 v9, v36, v9
	v_mul_f32_e32 v8, v36, v8
	v_mul_f32_e32 v7, v36, v7
	v_mul_f32_e32 v6, v36, v6
	v_mul_f32_e32 v5, v36, v5
	v_mul_f32_e32 v4, v36, v4
	v_mul_f32_e32 v3, v36, v3
	v_mul_f32_e32 v2, v36, v2
	v_mul_f32_e32 v1, v36, v1
	v_mul_f32_e32 v0, v36, v0
	v_cvt_pk_bf16_f32 v34, v34, s0
	v_cvt_pk_bf16_f32 v31, v31, s0
	v_cvt_pk_bf16_f32 v29, v29, s0
	v_cvt_pk_bf16_f32 v28, v28, s0
	v_cvt_pk_bf16_f32 v27, v27, s0
	v_cvt_pk_bf16_f32 v26, v26, s0
	v_cvt_pk_bf16_f32 v25, v25, s0
	v_cvt_pk_bf16_f32 v24, v24, s0
	v_cvt_pk_bf16_f32 v23, v23, s0
	v_cvt_pk_bf16_f32 v22, v22, s0
	v_cvt_pk_bf16_f32 v21, v21, s0
	v_cvt_pk_bf16_f32 v20, v20, s0
	v_cvt_pk_bf16_f32 v19, v19, s0
	v_cvt_pk_bf16_f32 v18, v18, s0
	v_cvt_pk_bf16_f32 v17, v17, s0
	v_cvt_pk_bf16_f32 v16, v16, s0
	v_cvt_pk_bf16_f32 v15, v15, s0
	v_cvt_pk_bf16_f32 v14, v14, s0
	v_cvt_pk_bf16_f32 v13, v13, s0
	v_cvt_pk_bf16_f32 v12, v12, s0
	v_cvt_pk_bf16_f32 v11, v11, s0
	v_cvt_pk_bf16_f32 v10, v10, s0
	v_cvt_pk_bf16_f32 v9, v9, s0
	v_cvt_pk_bf16_f32 v8, v8, s0
	v_cvt_pk_bf16_f32 v7, v7, s0
	v_cvt_pk_bf16_f32 v6, v6, s0
	v_cvt_pk_bf16_f32 v5, v5, s0
	v_cvt_pk_bf16_f32 v4, v4, s0
	v_cvt_pk_bf16_f32 v3, v3, s0
	v_cvt_pk_bf16_f32 v2, v2, s0
	v_cvt_pk_bf16_f32 v1, v1, s0
	v_cvt_pk_bf16_f32 v0, v0, s0
	s_or_b32 s0, s0, s29
	v_and_b32_e32 v37, -2, v35
	s_ashr_i32 s1, s0, 31
	v_lshlrev_b32_e32 v36, 5, v33
	v_add3_u32 v30, 0, v37, v30
; DI bf16_t f2bf(float x) { return (bf16_t)(pk2(x, 0.f) & 0xffffu); }
; DI int crow(int i, int h) { return (i & 3) + 8 * (i >> 2) + 4 * h; }
; DI f32x16 mfma32(bf16x8 a, bf16x8 b, f32x16 c) { return __builtin_amdgcn_mfma_f32_32x32x16_bf16(a, b, c, 0, 0, 0); }
; DI void sgu_task(const Params& p, int layer, int chunk, int h, unsigned char* lds) {
;     ...
;     for (int e = 0; e < 32; ++e) vT[(half * 32 + e) * 136 + j] = f2bf(x[e] * rn);
;   }
;   __syncthreads();
;   const bf16_t* W = (const bf16_t*)(p.ws + WS_SGUW) + ((size_t)(layer * 4 + h) * 128 + 32 * wid + r) * 128;
;   f32x16 acc[2];
; #pragma unroll
;   for (int a = 0; a < 2; ++a)
; #pragma unroll
;     for (int i = 0; i < 16; ++i) acc[a][i] = 0.f;
; #pragma unroll
;   for (int ks = 0; ks < 8; ++ks) {
;     const bf16x8 a = *(const bf16x8*)(W + 16 * ks + 8 * hh);
; #pragma unroll
;     for (int nt = 0; nt < 2; ++nt) { const bf16x8 b = *(const bf16x8*)(vT + (32 * nt + r) * 136 + 16 * ks + 8 * hh); acc[nt] = mfma32(a, b, acc[nt]); }
;   }
;   const float* bias = p.sgu_b + (layer * 4 + h) * 128;
;   __syncthreads();
;   {
;     float* Ct = (float*)lds + wid * (32 * 68);
; #pragma unroll
;     for (int nt = 0; nt < 2; ++nt)
; #pragma unroll
;       for (int i = 0; i < 16; ++i) Ct[crow(i, hh) * 68 + 32 * nt + r] = acc[nt][i] + bias[32 * wid + crow(i, hh)];
	s_lshl_b64 s[6:7], s[0:1], 7
	v_ashrrev_i32_e32 v37, 31, v36
	ds_write_b16 v30, v1 offset:8160
	ds_write_b16 v30, v0 offset:8432
	v_lshl_add_u64 v[0:1], s[6:7], 0, v[36:37]
	v_or_b32_e32 v0, v0, v32
	ds_write_b16 v30, v34
	v_lshlrev_b64 v[0:1], 8, v[0:1]
	v_bfe_u32 v34, v35, 5, 1
	v_lshl_add_u64 v[0:1], s[2:3], 0, v[0:1]
	v_lshlrev_b32_e32 v160, 4, v34
	v_lshl_add_u64 v[46:47], v[0:1], 0, v[160:161]
	ds_write_b16 v30, v31 offset:272
	ds_write_b16 v30, v29 offset:544
	ds_write_b16 v30, v28 offset:816
	ds_write_b16 v30, v27 offset:1088
	ds_write_b16 v30, v26 offset:1360
	ds_write_b16 v30, v25 offset:1632
	ds_write_b16 v30, v24 offset:1904
	ds_write_b16 v30, v23 offset:2176
	ds_write_b16 v30, v22 offset:2448
	ds_write_b16 v30, v21 offset:2720
	ds_write_b16 v30, v20 offset:2992
	ds_write_b16 v30, v19 offset:3264
	ds_write_b16 v30, v18 offset:3536
	ds_write_b16 v30, v17 offset:3808
	ds_write_b16 v30, v16 offset:4080
	ds_write_b16 v30, v15 offset:4352
	ds_write_b16 v30, v14 offset:4624
	ds_write_b16 v30, v13 offset:4896
	ds_write_b16 v30, v12 offset:5168
	ds_write_b16 v30, v11 offset:5440
	ds_write_b16 v30, v10 offset:5712
	ds_write_b16 v30, v9 offset:5984
	ds_write_b16 v30, v8 offset:6256
	ds_write_b16 v30, v7 offset:6528
	ds_write_b16 v30, v6 offset:6800
	ds_write_b16 v30, v5 offset:7072
	ds_write_b16 v30, v4 offset:7344
	ds_write_b16 v30, v3 offset:7616
	ds_write_b16 v30, v2 offset:7888
	s_waitcnt lgkmcnt(0)
	s_barrier
	global_load_dwordx4 v[0:3], v[46:47], off
	v_mul_u32_u24_e32 v4, 0x110, v32
	v_add3_u32 v48, 0, v160, v4
	ds_read_b128 v[4:7], v48
	ds_read_b128 v[38:41], v48 offset:32
	global_load_dwordx4 v[42:45], v[46:47], off offset:32
	s_waitcnt vmcnt(1) lgkmcnt(1)
	v_mfma_f32_32x32x16_bf16 v[16:31], v[0:3], v[4:7], 0
	ds_read_b128 v[4:7], v48 offset:8704
	s_lshl_b32 s0, s0, 7
	s_ashr_i32 s1, s0, 31
	s_movk_i32 s2, 0x2200
	s_lshl_b64 s[0:1], s[0:1], 2
	v_lshlrev_b32_e32 v32, 2, v32
	s_add_u32 s0, s58, s0
	s_waitcnt vmcnt(0) lgkmcnt(1)
	v_mfma_f32_32x32x16_bf16 v[16:31], v[42:45], v[38:41], v[16:31]
	ds_read_b128 v[38:41], v48 offset:8736
	s_addc_u32 s1, s59, s1
	s_waitcnt lgkmcnt(1)
	v_mfma_f32_32x32x16_bf16 v[0:15], v[0:3], v[4:7], 0
	s_waitcnt lgkmcnt(0)
	v_mfma_f32_32x32x16_bf16 v[0:15], v[42:45], v[38:41], v[0:15]
	global_load_dwordx4 v[38:41], v[46:47], off offset:64
	ds_read_b128 v[42:45], v48 offset:64
	s_waitcnt vmcnt(0) lgkmcnt(0)
	v_mfma_f32_32x32x16_bf16 v[16:31], v[38:41], v[42:45], v[16:31]
	ds_read_b128 v[42:45], v48 offset:8768
	s_waitcnt lgkmcnt(0)
	v_mfma_f32_32x32x16_bf16 v[0:15], v[38:41], v[42:45], v[0:15]
	global_load_dwordx4 v[38:41], v[46:47], off offset:96
	ds_read_b128 v[42:45], v48 offset:96
	s_waitcnt vmcnt(0) lgkmcnt(0)
	v_mfma_f32_32x32x16_bf16 v[16:31], v[38:41], v[42:45], v[16:31]
	ds_read_b128 v[42:45], v48 offset:8800
	s_waitcnt lgkmcnt(0)
	v_mfma_f32_32x32x16_bf16 v[0:15], v[38:41], v[42:45], v[0:15]
	global_load_dwordx4 v[38:41], v[46:47], off offset:128
	ds_read_b128 v[42:45], v48 offset:128
	s_waitcnt vmcnt(0) lgkmcnt(0)
	v_mfma_f32_32x32x16_bf16 v[16:31], v[38:41], v[42:45], v[16:31]
	ds_read_b128 v[42:45], v48 offset:8832
	s_waitcnt lgkmcnt(0)
	v_mfma_f32_32x32x16_bf16 v[0:15], v[38:41], v[42:45], v[0:15]
	global_load_dwordx4 v[38:41], v[46:47], off offset:160
	ds_read_b128 v[42:45], v48 offset:160
	s_waitcnt vmcnt(0) lgkmcnt(0)
	v_mfma_f32_32x32x16_bf16 v[16:31], v[38:41], v[42:45], v[16:31]
	ds_read_b128 v[42:45], v48 offset:8864
	s_waitcnt lgkmcnt(0)
	v_mfma_f32_32x32x16_bf16 v[0:15], v[38:41], v[42:45], v[0:15]
	global_load_dwordx4 v[38:41], v[46:47], off offset:192
	ds_read_b128 v[42:45], v48 offset:192
	s_waitcnt vmcnt(0) lgkmcnt(0)
	v_mfma_f32_32x32x16_bf16 v[16:31], v[38:41], v[42:45], v[16:31]
	ds_read_b128 v[42:45], v48 offset:8896
	s_waitcnt lgkmcnt(0)
	v_mfma_f32_32x32x16_bf16 v[0:15], v[38:41], v[42:45], v[0:15]
	global_load_dwordx4 v[38:41], v[46:47], off offset:224
	ds_read_b128 v[42:45], v48 offset:224
	s_waitcnt vmcnt(0) lgkmcnt(0)
	v_mfma_f32_32x32x16_bf16 v[16:31], v[38:41], v[42:45], v[16:31]
	ds_read_b128 v[42:45], v48 offset:8928
	s_waitcnt lgkmcnt(0)
	s_barrier
	v_mfma_f32_32x32x16_bf16 v[0:15], v[38:41], v[42:45], v[0:15]
	v_mul_lo_u32 v40, v33, s2
	v_lshlrev_b32_e32 v41, 2, v34
	v_add3_u32 v42, 0, v40, v32
	v_or_b32_e32 v32, v41, v36
	v_ashrrev_i32_e32 v33, 31, v32
	v_lshl_add_u64 v[38:39], v[32:33], 2, s[0:1]
	global_load_dword v43, v[38:39], off
	v_mov_b32_e32 v33, v37
	s_movk_i32 s2, 0x440
	v_lshl_add_u64 v[38:39], v[32:33], 2, s[0:1]
	v_mad_u32_u24 v44, v34, s2, v42
	global_load_dwordx3 v[32:34], v[38:39], off offset:4
	s_movk_i32 s2, 0x110
	s_waitcnt vmcnt(1)
	v_add_f32_e32 v16, v16, v43
	ds_write_b32 v44, v16
	v_or_b32_e32 v16, 1, v41
	v_mad_u32_u24 v37, v16, s2, v42
	v_add_f32_e32 v0, v0, v43
	s_waitcnt vmcnt(0)
	v_add_f32_e32 v16, v18, v33
	v_add_f32_e32 v17, v17, v32
	ds_write_b32 v37, v16 offset:272
	v_add_f32_e32 v16, v19, v34
	ds_write_b32 v37, v17
	ds_write_b32 v37, v16 offset:544
	global_load_dwordx4 v[16:19], v[38:39], off offset:32
	s_waitcnt vmcnt(0)
	v_add_f32_e32 v20, v20, v16
	ds_write_b32 v37, v20 offset:1904
	v_add_f32_e32 v20, v21, v17
	ds_write_b32 v37, v20 offset:2176
	v_add_f32_e32 v20, v22, v18
	ds_write_b32 v37, v20 offset:2448
	v_add_f32_e32 v20, v23, v19
	ds_write_b32 v37, v20 offset:2720
	global_load_dwordx4 v[20:23], v[38:39], off offset:64
	s_waitcnt vmcnt(0)
	v_add_f32_e32 v24, v24, v20
	ds_write_b32 v37, v24 offset:4080
	v_add_f32_e32 v24, v25, v21
	ds_write_b32 v37, v24 offset:4352
	v_add_f32_e32 v24, v26, v22
	ds_write_b32 v37, v24 offset:4624
	v_add_f32_e32 v24, v27, v23
	ds_write_b32 v37, v24 offset:4896
	global_load_dwordx4 v[24:27], v[38:39], off offset:96
	s_waitcnt vmcnt(0)
; DI float bflo(unsigned u) { return __uint_as_float(u << 16); }
; DI float bfhi(unsigned u) { return __uint_as_float(u & 0xffff0000u); }
; DI unsigned pk2(float lo, float hi) { f32x2 v = {lo, hi}; bfv2 b = __builtin_convertvector(v, bfv2); return __builtin_bit_cast(unsigned, b); }
; DI float silu(float x) { return x * __builtin_amdgcn_rcpf(1.f + __expf(-x)); }
; DI int crow(int i, int h) { return (i & 3) + 8 * (i >> 2) + 4 * h; }
; DI void sgu_task(const Params& p, int layer, int chunk, int h, unsigned char* lds) {
;     ...
;       for (int i = 0; i < 16; ++i) Ct[crow(i, hh) * 68 + 32 * nt + r] = acc[nt][i] + bias[32 * wid + crow(i, hh)];
;     asm volatile("s_waitcnt lgkmcnt(0)" ::: "memory");
;     const int rsub = lane >> 4, c4 = (lane & 15) * 4;
; #pragma unroll 4
;     for (int j = 0; j < 8; ++j) {
;       const int rl = 4 * j + rsub;
;       const f32x4 cv = *(const f32x4*)(Ct + rl * 68 + c4);
;       bf16_t* base = proj + (size_t)(t0 + 32 * wid + rl) * PP + 64 * h + c4;
;       const u32x2 ur = *(const u32x2*)(base + A_U), zr = *(const u32x2*)(base + A_Z);
;       *(u32x2*)(base + A_U) = (u32x2){pk2(bflo(ur.x) * cv.x * silu(bflo(zr.x)), bfhi(ur.x) * cv.y * silu(bfhi(zr.x))), pk2(bflo(ur.y) * cv.z * silu(bflo(zr.y)), bfhi(ur.y) * cv.w * silu(bfhi(zr.y)))};
;     }
	v_add_f32_e32 v28, v28, v24
	ds_write_b32 v37, v28 offset:6256
	v_add_f32_e32 v28, v29, v25
	ds_write_b32 v37, v28 offset:6528
	v_add_f32_e32 v28, v30, v26
	ds_write_b32 v37, v28 offset:6800
	v_add_f32_e32 v28, v31, v27
	ds_write_b32 v37, v28 offset:7072
	ds_write_b32 v44, v0 offset:128
	v_add_f32_e32 v0, v1, v32
	ds_write_b32 v37, v0 offset:128
	v_add_f32_e32 v0, v2, v33
	ds_write_b32 v37, v0 offset:400
	v_add_f32_e32 v0, v3, v34
	ds_write_b32 v37, v0 offset:672
	v_add_f32_e32 v0, v4, v16
	ds_write_b32 v37, v0 offset:2032
	v_add_f32_e32 v0, v5, v17
	ds_write_b32 v37, v0 offset:2304
	v_add_f32_e32 v0, v6, v18
	ds_write_b32 v37, v0 offset:2576
	v_add_f32_e32 v0, v7, v19
	ds_write_b32 v37, v0 offset:2848
	v_add_f32_e32 v0, v8, v20
	ds_write_b32 v37, v0 offset:4208
	v_add_f32_e32 v0, v9, v21
	ds_write_b32 v37, v0 offset:4480
	v_add_f32_e32 v0, v10, v22
	ds_write_b32 v37, v0 offset:4752
	v_add_f32_e32 v0, v11, v23
	ds_write_b32 v37, v0 offset:5024
	v_add_f32_e32 v0, v12, v24
	ds_write_b32 v37, v0 offset:6384
	v_add_f32_e32 v0, v13, v25
	ds_write_b32 v37, v0 offset:6656
	v_add_f32_e32 v0, v14, v26
	ds_write_b32 v37, v0 offset:6928
	v_add_f32_e32 v0, v15, v27
	v_bfe_u32 v10, v35, 4, 2
	ds_write_b32 v37, v0 offset:7200
	v_or_b32_e32 v0, s9, v10
	v_add_u32_e32 v8, v0, v36
	v_add_u32_e32 v2, 0xfffe200c, v8
	v_mov_b64_e32 v[0:1], s[84:85]
	v_and_b32_e32 v6, 15, v35
	v_mad_i64_i32 v[2:3], s[0:1], v2, s12, v[0:1]
	v_lshlrev_b32_e32 v11, 3, v6
	v_or_b32_e32 v2, v2, v11
	v_lshl_add_u64 v[4:5], s[88:89], 0, v[2:3]
	v_mad_u32_u24 v2, v10, s2, v40
	v_lshlrev_b32_e32 v3, 4, v6
	v_add3_u32 v12, v2, v3, 0
	v_add_u32_e32 v2, 0xfffe2008, v8
	v_mad_i64_i32 v[2:3], s[0:1], v2, s12, v[0:1]
	v_or_b32_e32 v2, v2, v11
	v_lshl_add_u64 v[6:7], s[88:89], 0, v[2:3]
	v_add_u32_e32 v2, 0xfffe2004, v8
	v_mad_i64_i32 v[2:3], s[0:1], v2, s12, v[0:1]
	v_or_b32_e32 v2, v2, v11
	v_lshl_add_u64 v[8:9], s[88:89], 0, v[2:3]
	v_or_b32_e32 v2, s8, v10
	s_waitcnt lgkmcnt(0)
	v_add_u32_e32 v2, v2, v36
	v_mad_i64_i32 v[0:1], s[0:1], v2, s12, v[0:1]
	v_or_b32_e32 v0, v0, v11
	v_lshl_add_u64 v[10:11], s[88:89], 0, v[0:1]
	s_mov_b64 s[0:1], 0
	v_add_co_u32_e32 v226, vcc, 0x1438000, v10
	s_nop 1
	v_addc_co_u32_e32 v227, vcc, 0, v11, vcc
	global_load_dwordx2 v[100:101], v[226:227], off offset:256
	global_load_dwordx2 v[102:103], v[226:227], off offset:1280
	v_add_co_u32_e32 v226, vcc, 0x1438000, v8
	s_nop 1
	v_addc_co_u32_e32 v227, vcc, 0, v9, vcc
	global_load_dwordx2 v[104:105], v[226:227], off offset:256
	global_load_dwordx2 v[106:107], v[226:227], off offset:1280
	v_add_co_u32_e32 v226, vcc, 0x1438000, v6
	s_nop 1
	v_addc_co_u32_e32 v227, vcc, 0, v7, vcc
	global_load_dwordx2 v[108:109], v[226:227], off offset:256
	global_load_dwordx2 v[110:111], v[226:227], off offset:1280
	v_add_co_u32_e32 v226, vcc, 0x1438000, v4
	s_nop 1
	v_addc_co_u32_e32 v227, vcc, 0, v5, vcc
	global_load_dwordx2 v[112:113], v[226:227], off offset:256
	global_load_dwordx2 v[114:115], v[226:227], off offset:1280
	v_add_co_u32_e32 v226, vcc, 0x1450800, v10
	s_nop 1
	v_addc_co_u32_e32 v227, vcc, 0, v11, vcc
	global_load_dwordx2 v[116:117], v[226:227], off offset:256
	global_load_dwordx2 v[118:119], v[226:227], off offset:1280
	v_add_co_u32_e32 v226, vcc, 0x1450800, v8
	s_nop 1
	v_addc_co_u32_e32 v227, vcc, 0, v9, vcc
	global_load_dwordx2 v[120:121], v[226:227], off offset:256
	global_load_dwordx2 v[122:123], v[226:227], off offset:1280
	v_add_co_u32_e32 v226, vcc, 0x1450800, v6
	s_nop 1
	v_addc_co_u32_e32 v227, vcc, 0, v7, vcc
	global_load_dwordx2 v[124:125], v[226:227], off offset:256
	global_load_dwordx2 v[126:127], v[226:227], off offset:1280
	v_add_co_u32_e32 v226, vcc, 0x1450800, v4
	s_nop 1
	v_addc_co_u32_e32 v227, vcc, 0, v5, vcc
	global_load_dwordx2 v[128:129], v[226:227], off offset:256
	global_load_dwordx2 v[130:131], v[226:227], off offset:1280
	v_lshl_add_u64 v[14:15], v[10:11], 0, s[0:1]
	v_add_co_u32_e32 v14, vcc, 0x1438000, v14
	ds_read_b128 v[0:3], v12
	s_nop 0
	v_addc_co_u32_e32 v15, vcc, 0, v15, vcc
	s_waitcnt vmcnt(15)
	v_mov_b32_e32 v16, v100
	v_mov_b32_e32 v17, v101
	v_lshlrev_b32_e32 v24, 16, v16
	s_waitcnt vmcnt(14)
	v_mov_b32_e32 v18, v102
	v_mov_b32_e32 v19, v103
	v_lshlrev_b32_e32 v20, 16, v18
	v_mul_f32_e32 v13, 0xbfb8aa3b, v20
	v_exp_f32_e32 v13, v13
	v_and_b32_e32 v21, 0xffff0000, v18
	v_and_b32_e32 v25, 0xffff0000, v16
	s_waitcnt lgkmcnt(0)
	v_pk_mul_f32 v[0:1], v[0:1], v[24:25]
	v_add_f32_e32 v13, 1.0, v13
	v_rcp_f32_e32 v22, v13
	v_mul_f32_e32 v13, 0xbfb8aa3b, v21
	v_exp_f32_e32 v13, v13
	v_lshlrev_b32_e32 v18, 16, v19
	v_and_b32_e32 v19, 0xffff0000, v19
	v_add_f32_e32 v13, 1.0, v13
	v_rcp_f32_e32 v23, v13
	s_nop 0
	v_pk_mul_f32 v[20:21], v[22:23], v[20:21]
	s_nop 0
	v_pk_mul_f32 v[0:1], v[0:1], v[20:21]
	v_lshlrev_b32_e32 v20, 16, v17
	v_cvt_pk_bf16_f32 v0, v0, v1
	v_mul_f32_e32 v1, 0xbfb8aa3b, v18
	v_exp_f32_e32 v1, v1
	v_and_b32_e32 v21, 0xffff0000, v17
	v_pk_mul_f32 v[2:3], v[2:3], v[20:21]
	v_add_f32_e32 v1, 1.0, v1
	v_rcp_f32_e32 v16, v1
	v_mul_f32_e32 v1, 0xbfb8aa3b, v19
	v_exp_f32_e32 v1, v1
	s_nop 0
	v_add_f32_e32 v1, 1.0, v1
	v_rcp_f32_e32 v17, v1
	s_nop 0
	v_pk_mul_f32 v[16:17], v[16:17], v[18:19]
	s_nop 0
	v_pk_mul_f32 v[2:3], v[2:3], v[16:17]
	s_nop 0
	v_cvt_pk_bf16_f32 v1, v2, v3
	global_store_dwordx2 v[14:15], v[0:1], off offset:256
	v_lshl_add_u64 v[14:15], v[8:9], 0, s[0:1]
	v_add_co_u32_e32 v14, vcc, s80, v14
	ds_read_b128 v[0:3], v12 offset:1088
	s_nop 0
	v_addc_co_u32_e32 v15, vcc, 0, v15, vcc
	s_waitcnt vmcnt(14)
	v_mov_b32_e32 v16, v104
	v_mov_b32_e32 v17, v105
	v_lshlrev_b32_e32 v24, 16, v16
	s_waitcnt vmcnt(13)
; DI float bflo(unsigned u) { return __uint_as_float(u << 16); }
; DI float bfhi(unsigned u) { return __uint_as_float(u & 0xffff0000u); }
; DI unsigned pk2(float lo, float hi) { f32x2 v = {lo, hi}; bfv2 b = __builtin_convertvector(v, bfv2); return __builtin_bit_cast(unsigned, b); }
; DI float silu(float x) { return x * __builtin_amdgcn_rcpf(1.f + __expf(-x)); }
; DI void sgu_task(const Params& p, int layer, int chunk, int h, unsigned char* lds) {
;     ...
;     for (int j = 0; j < 8; ++j) {
;       const int rl = 4 * j + rsub;
;       const f32x4 cv = *(const f32x4*)(Ct + rl * 68 + c4);
;       bf16_t* base = proj + (size_t)(t0 + 32 * wid + rl) * PP + 64 * h + c4;
;       const u32x2 ur = *(const u32x2*)(base + A_U), zr = *(const u32x2*)(base + A_Z);
;       *(u32x2*)(base + A_U) = (u32x2){pk2(bflo(ur.x) * cv.x * silu(bflo(zr.x)), bfhi(ur.x) * cv.y * silu(bfhi(zr.x))), pk2(bflo(ur.y) * cv.z * silu(bflo(zr.y)), bfhi(ur.y) * cv.w * silu(bfhi(zr.y)))};
;     }
	v_mov_b32_e32 v18, v106
	v_mov_b32_e32 v19, v107
	v_lshlrev_b32_e32 v20, 16, v18
	v_mul_f32_e32 v13, 0xbfb8aa3b, v20
	v_exp_f32_e32 v13, v13
	v_and_b32_e32 v21, 0xffff0000, v18
	v_and_b32_e32 v25, 0xffff0000, v16
	s_waitcnt lgkmcnt(0)
	v_pk_mul_f32 v[0:1], v[0:1], v[24:25]
	v_add_f32_e32 v13, 1.0, v13
	v_rcp_f32_e32 v22, v13
	v_mul_f32_e32 v13, 0xbfb8aa3b, v21
	v_exp_f32_e32 v13, v13
	v_lshlrev_b32_e32 v18, 16, v19
	v_and_b32_e32 v19, 0xffff0000, v19
	v_add_f32_e32 v13, 1.0, v13
	v_rcp_f32_e32 v23, v13
	s_nop 0
	v_pk_mul_f32 v[20:21], v[22:23], v[20:21]
	s_nop 0
	v_pk_mul_f32 v[0:1], v[0:1], v[20:21]
	v_lshlrev_b32_e32 v20, 16, v17
	v_cvt_pk_bf16_f32 v0, v0, v1
	v_mul_f32_e32 v1, 0xbfb8aa3b, v18
	v_exp_f32_e32 v1, v1
	v_and_b32_e32 v21, 0xffff0000, v17
	v_pk_mul_f32 v[2:3], v[2:3], v[20:21]
	v_add_f32_e32 v1, 1.0, v1
	v_rcp_f32_e32 v16, v1
	v_mul_f32_e32 v1, 0xbfb8aa3b, v19
	v_exp_f32_e32 v1, v1
	s_nop 0
	v_add_f32_e32 v1, 1.0, v1
	v_rcp_f32_e32 v17, v1
	s_nop 0
	v_pk_mul_f32 v[16:17], v[16:17], v[18:19]
	s_nop 0
	v_pk_mul_f32 v[2:3], v[2:3], v[16:17]
	s_nop 0
	v_cvt_pk_bf16_f32 v1, v2, v3
	global_store_dwordx2 v[14:15], v[0:1], off offset:256
	v_lshl_add_u64 v[14:15], v[6:7], 0, s[0:1]
	v_add_co_u32_e32 v14, vcc, s80, v14
	ds_read_b128 v[0:3], v12 offset:2176
	s_nop 0
	v_addc_co_u32_e32 v15, vcc, 0, v15, vcc
	s_waitcnt vmcnt(13)
	v_mov_b32_e32 v16, v108
	v_mov_b32_e32 v17, v109
	v_lshlrev_b32_e32 v24, 16, v16
	s_waitcnt vmcnt(12)
	v_mov_b32_e32 v18, v110
	v_mov_b32_e32 v19, v111
	v_lshlrev_b32_e32 v20, 16, v18
	v_mul_f32_e32 v13, 0xbfb8aa3b, v20
	v_exp_f32_e32 v13, v13
	v_and_b32_e32 v21, 0xffff0000, v18
	v_and_b32_e32 v25, 0xffff0000, v16
	s_waitcnt lgkmcnt(0)
	v_pk_mul_f32 v[0:1], v[0:1], v[24:25]
	v_add_f32_e32 v13, 1.0, v13
	v_rcp_f32_e32 v22, v13
	v_mul_f32_e32 v13, 0xbfb8aa3b, v21
	v_exp_f32_e32 v13, v13
	v_lshlrev_b32_e32 v18, 16, v19
	v_and_b32_e32 v19, 0xffff0000, v19
	v_add_f32_e32 v13, 1.0, v13
	v_rcp_f32_e32 v23, v13
	s_nop 0
	v_pk_mul_f32 v[20:21], v[22:23], v[20:21]
	s_nop 0
	v_pk_mul_f32 v[0:1], v[0:1], v[20:21]
	v_lshlrev_b32_e32 v20, 16, v17
	v_cvt_pk_bf16_f32 v0, v0, v1
	v_mul_f32_e32 v1, 0xbfb8aa3b, v18
	v_exp_f32_e32 v1, v1
	v_and_b32_e32 v21, 0xffff0000, v17
	v_pk_mul_f32 v[2:3], v[2:3], v[20:21]
	v_add_f32_e32 v1, 1.0, v1
	v_rcp_f32_e32 v16, v1
	v_mul_f32_e32 v1, 0xbfb8aa3b, v19
	v_exp_f32_e32 v1, v1
	s_nop 0
	v_add_f32_e32 v1, 1.0, v1
	v_rcp_f32_e32 v17, v1
	s_nop 0
	v_pk_mul_f32 v[16:17], v[16:17], v[18:19]
	s_nop 0
	v_pk_mul_f32 v[2:3], v[2:3], v[16:17]
	s_nop 0
	v_cvt_pk_bf16_f32 v1, v2, v3
	global_store_dwordx2 v[14:15], v[0:1], off offset:256
	v_lshl_add_u64 v[14:15], v[4:5], 0, s[0:1]
	v_add_co_u32_e32 v14, vcc, s80, v14
	ds_read_b128 v[0:3], v12 offset:3264
	s_nop 0
	v_addc_co_u32_e32 v15, vcc, 0, v15, vcc
	s_add_u32 s0, s0, 0x18800
	s_addc_u32 s1, s1, 0
	v_add_u32_e32 v12, 0x1100, v12
	s_cmp_lg_u32 s0, 0x31000
	s_waitcnt vmcnt(12)
	v_mov_b32_e32 v16, v112
	v_mov_b32_e32 v17, v113
	v_lshlrev_b32_e32 v24, 16, v16
	s_waitcnt vmcnt(11)
	v_mov_b32_e32 v18, v114
	v_mov_b32_e32 v19, v115
	v_lshlrev_b32_e32 v20, 16, v18
	v_mul_f32_e32 v13, 0xbfb8aa3b, v20
	v_exp_f32_e32 v13, v13
	v_and_b32_e32 v21, 0xffff0000, v18
	v_and_b32_e32 v25, 0xffff0000, v16
	s_waitcnt lgkmcnt(0)
	v_pk_mul_f32 v[0:1], v[0:1], v[24:25]
	v_add_f32_e32 v13, 1.0, v13
	v_rcp_f32_e32 v22, v13
	v_mul_f32_e32 v13, 0xbfb8aa3b, v21
	v_exp_f32_e32 v13, v13
	v_lshlrev_b32_e32 v18, 16, v19
	v_and_b32_e32 v19, 0xffff0000, v19
	v_add_f32_e32 v13, 1.0, v13
	v_rcp_f32_e32 v23, v13
	s_nop 0
	v_pk_mul_f32 v[20:21], v[22:23], v[20:21]
	s_nop 0
	v_pk_mul_f32 v[0:1], v[0:1], v[20:21]
	v_lshlrev_b32_e32 v20, 16, v17
	v_cvt_pk_bf16_f32 v0, v0, v1
	v_mul_f32_e32 v1, 0xbfb8aa3b, v18
	v_exp_f32_e32 v1, v1
	v_and_b32_e32 v21, 0xffff0000, v17
	v_pk_mul_f32 v[2:3], v[2:3], v[20:21]
	v_add_f32_e32 v1, 1.0, v1
	v_rcp_f32_e32 v16, v1
	v_mul_f32_e32 v1, 0xbfb8aa3b, v19
	v_exp_f32_e32 v1, v1
	s_nop 0
	v_add_f32_e32 v1, 1.0, v1
	v_rcp_f32_e32 v17, v1
	s_nop 0
	v_pk_mul_f32 v[16:17], v[16:17], v[18:19]
	s_nop 0
	v_pk_mul_f32 v[2:3], v[2:3], v[16:17]
	s_nop 0
	v_cvt_pk_bf16_f32 v1, v2, v3
	global_store_dwordx2 v[14:15], v[0:1], off offset:256
	v_lshl_add_u64 v[14:15], v[10:11], 0, s[0:1]
	v_add_co_u32_e32 v14, vcc, 0x1438000, v14
	ds_read_b128 v[0:3], v12
	s_nop 0
	v_addc_co_u32_e32 v15, vcc, 0, v15, vcc
	s_waitcnt vmcnt(11)
	v_mov_b32_e32 v16, v116
	v_mov_b32_e32 v17, v117
	v_lshlrev_b32_e32 v24, 16, v16
	s_waitcnt vmcnt(10)
	v_mov_b32_e32 v18, v118
	v_mov_b32_e32 v19, v119
	v_lshlrev_b32_e32 v20, 16, v18
	v_mul_f32_e32 v13, 0xbfb8aa3b, v20
	v_exp_f32_e32 v13, v13
	v_and_b32_e32 v21, 0xffff0000, v18
	v_and_b32_e32 v25, 0xffff0000, v16
	s_waitcnt lgkmcnt(0)
; DI float bflo(unsigned u) { return __uint_as_float(u << 16); }
; DI float bfhi(unsigned u) { return __uint_as_float(u & 0xffff0000u); }
; DI unsigned pk2(float lo, float hi) { f32x2 v = {lo, hi}; bfv2 b = __builtin_convertvector(v, bfv2); return __builtin_bit_cast(unsigned, b); }
; DI float silu(float x) { return x * __builtin_amdgcn_rcpf(1.f + __expf(-x)); }
; DI void sgu_task(const Params& p, int layer, int chunk, int h, unsigned char* lds) {
;     ...
;     for (int j = 0; j < 8; ++j) {
;       const int rl = 4 * j + rsub;
;       const f32x4 cv = *(const f32x4*)(Ct + rl * 68 + c4);
;       bf16_t* base = proj + (size_t)(t0 + 32 * wid + rl) * PP + 64 * h + c4;
;       const u32x2 ur = *(const u32x2*)(base + A_U), zr = *(const u32x2*)(base + A_Z);
;       *(u32x2*)(base + A_U) = (u32x2){pk2(bflo(ur.x) * cv.x * silu(bflo(zr.x)), bfhi(ur.x) * cv.y * silu(bfhi(zr.x))), pk2(bflo(ur.y) * cv.z * silu(bflo(zr.y)), bfhi(ur.y) * cv.w * silu(bfhi(zr.y)))};
;     }
	v_pk_mul_f32 v[0:1], v[0:1], v[24:25]
	v_add_f32_e32 v13, 1.0, v13
	v_rcp_f32_e32 v22, v13
	v_mul_f32_e32 v13, 0xbfb8aa3b, v21
	v_exp_f32_e32 v13, v13
	v_lshlrev_b32_e32 v18, 16, v19
	v_and_b32_e32 v19, 0xffff0000, v19
	v_add_f32_e32 v13, 1.0, v13
	v_rcp_f32_e32 v23, v13
	s_nop 0
	v_pk_mul_f32 v[20:21], v[22:23], v[20:21]
	s_nop 0
	v_pk_mul_f32 v[0:1], v[0:1], v[20:21]
	v_lshlrev_b32_e32 v20, 16, v17
	v_cvt_pk_bf16_f32 v0, v0, v1
	v_mul_f32_e32 v1, 0xbfb8aa3b, v18
	v_exp_f32_e32 v1, v1
	v_and_b32_e32 v21, 0xffff0000, v17
	v_pk_mul_f32 v[2:3], v[2:3], v[20:21]
	v_add_f32_e32 v1, 1.0, v1
	v_rcp_f32_e32 v16, v1
	v_mul_f32_e32 v1, 0xbfb8aa3b, v19
	v_exp_f32_e32 v1, v1
	s_nop 0
	v_add_f32_e32 v1, 1.0, v1
	v_rcp_f32_e32 v17, v1
	s_nop 0
	v_pk_mul_f32 v[16:17], v[16:17], v[18:19]
	s_nop 0
	v_pk_mul_f32 v[2:3], v[2:3], v[16:17]
	s_nop 0
	v_cvt_pk_bf16_f32 v1, v2, v3
	global_store_dwordx2 v[14:15], v[0:1], off offset:256
	v_lshl_add_u64 v[14:15], v[8:9], 0, s[0:1]
	v_add_co_u32_e32 v14, vcc, s80, v14
	ds_read_b128 v[0:3], v12 offset:1088
	s_nop 0
	v_addc_co_u32_e32 v15, vcc, 0, v15, vcc
	s_waitcnt vmcnt(10)
	v_mov_b32_e32 v16, v120
	v_mov_b32_e32 v17, v121
	v_lshlrev_b32_e32 v24, 16, v16
	s_waitcnt vmcnt(9)
	v_mov_b32_e32 v18, v122
	v_mov_b32_e32 v19, v123
	v_lshlrev_b32_e32 v20, 16, v18
	v_mul_f32_e32 v13, 0xbfb8aa3b, v20
	v_exp_f32_e32 v13, v13
	v_and_b32_e32 v21, 0xffff0000, v18
	v_and_b32_e32 v25, 0xffff0000, v16
	s_waitcnt lgkmcnt(0)
	v_pk_mul_f32 v[0:1], v[0:1], v[24:25]
	v_add_f32_e32 v13, 1.0, v13
	v_rcp_f32_e32 v22, v13
	v_mul_f32_e32 v13, 0xbfb8aa3b, v21
	v_exp_f32_e32 v13, v13
	v_lshlrev_b32_e32 v18, 16, v19
	v_and_b32_e32 v19, 0xffff0000, v19
	v_add_f32_e32 v13, 1.0, v13
	v_rcp_f32_e32 v23, v13
	s_nop 0
	v_pk_mul_f32 v[20:21], v[22:23], v[20:21]
	s_nop 0
	v_pk_mul_f32 v[0:1], v[0:1], v[20:21]
	v_lshlrev_b32_e32 v20, 16, v17
	v_cvt_pk_bf16_f32 v0, v0, v1
	v_mul_f32_e32 v1, 0xbfb8aa3b, v18
	v_exp_f32_e32 v1, v1
	v_and_b32_e32 v21, 0xffff0000, v17
	v_pk_mul_f32 v[2:3], v[2:3], v[20:21]
	v_add_f32_e32 v1, 1.0, v1
	v_rcp_f32_e32 v16, v1
	v_mul_f32_e32 v1, 0xbfb8aa3b, v19
	v_exp_f32_e32 v1, v1
	s_nop 0
	v_add_f32_e32 v1, 1.0, v1
	v_rcp_f32_e32 v17, v1
	s_nop 0
	v_pk_mul_f32 v[16:17], v[16:17], v[18:19]
	s_nop 0
	v_pk_mul_f32 v[2:3], v[2:3], v[16:17]
	s_nop 0
	v_cvt_pk_bf16_f32 v1, v2, v3
	global_store_dwordx2 v[14:15], v[0:1], off offset:256
	v_lshl_add_u64 v[14:15], v[6:7], 0, s[0:1]
	v_add_co_u32_e32 v14, vcc, s80, v14
	ds_read_b128 v[0:3], v12 offset:2176
	s_nop 0
	v_addc_co_u32_e32 v15, vcc, 0, v15, vcc
	s_waitcnt vmcnt(9)
	v_mov_b32_e32 v16, v124
	v_mov_b32_e32 v17, v125
	v_lshlrev_b32_e32 v24, 16, v16
	s_waitcnt vmcnt(8)
	v_mov_b32_e32 v18, v126
	v_mov_b32_e32 v19, v127
	v_lshlrev_b32_e32 v20, 16, v18
	v_mul_f32_e32 v13, 0xbfb8aa3b, v20
	v_exp_f32_e32 v13, v13
	v_and_b32_e32 v21, 0xffff0000, v18
	v_and_b32_e32 v25, 0xffff0000, v16
	s_waitcnt lgkmcnt(0)
	v_pk_mul_f32 v[0:1], v[0:1], v[24:25]
	v_add_f32_e32 v13, 1.0, v13
	v_rcp_f32_e32 v22, v13
	v_mul_f32_e32 v13, 0xbfb8aa3b, v21
	v_exp_f32_e32 v13, v13
	v_lshlrev_b32_e32 v18, 16, v19
	v_and_b32_e32 v19, 0xffff0000, v19
	v_add_f32_e32 v13, 1.0, v13
	v_rcp_f32_e32 v23, v13
	s_nop 0
	v_pk_mul_f32 v[20:21], v[22:23], v[20:21]
	s_nop 0
	v_pk_mul_f32 v[0:1], v[0:1], v[20:21]
	v_lshlrev_b32_e32 v20, 16, v17
	v_cvt_pk_bf16_f32 v0, v0, v1
	v_mul_f32_e32 v1, 0xbfb8aa3b, v18
	v_exp_f32_e32 v1, v1
	v_and_b32_e32 v21, 0xffff0000, v17
	v_pk_mul_f32 v[2:3], v[2:3], v[20:21]
	v_add_f32_e32 v1, 1.0, v1
	v_rcp_f32_e32 v16, v1
	v_mul_f32_e32 v1, 0xbfb8aa3b, v19
	v_exp_f32_e32 v1, v1
	s_nop 0
	v_add_f32_e32 v1, 1.0, v1
	v_rcp_f32_e32 v17, v1
	s_nop 0
	v_pk_mul_f32 v[16:17], v[16:17], v[18:19]
	s_nop 0
	v_pk_mul_f32 v[2:3], v[2:3], v[16:17]
	s_nop 0
	v_cvt_pk_bf16_f32 v1, v2, v3
	global_store_dwordx2 v[14:15], v[0:1], off offset:256
	v_lshl_add_u64 v[14:15], v[4:5], 0, s[0:1]
	v_add_co_u32_e32 v14, vcc, s80, v14
	ds_read_b128 v[0:3], v12 offset:3264
	s_nop 0
	v_addc_co_u32_e32 v15, vcc, 0, v15, vcc
	s_add_u32 s0, s0, 0x18800
	s_addc_u32 s1, s1, 0
	v_add_u32_e32 v12, 0x1100, v12
	s_cmp_lg_u32 s0, 0x31000
	s_waitcnt vmcnt(8)
	v_mov_b32_e32 v16, v128
	v_mov_b32_e32 v17, v129
	v_lshlrev_b32_e32 v24, 16, v16
	s_waitcnt vmcnt(7)
	v_mov_b32_e32 v18, v130
	v_mov_b32_e32 v19, v131
	v_lshlrev_b32_e32 v20, 16, v18
	v_mul_f32_e32 v13, 0xbfb8aa3b, v20
	v_exp_f32_e32 v13, v13
	v_and_b32_e32 v21, 0xffff0000, v18
	v_and_b32_e32 v25, 0xffff0000, v16
	s_waitcnt lgkmcnt(0)
	v_pk_mul_f32 v[0:1], v[0:1], v[24:25]
	v_add_f32_e32 v13, 1.0, v13
	v_rcp_f32_e32 v22, v13
	v_mul_f32_e32 v13, 0xbfb8aa3b, v21
	v_exp_f32_e32 v13, v13
	v_lshlrev_b32_e32 v18, 16, v19
	v_and_b32_e32 v19, 0xffff0000, v19
	v_add_f32_e32 v13, 1.0, v13
	v_rcp_f32_e32 v23, v13
	s_nop 0
	v_pk_mul_f32 v[20:21], v[22:23], v[20:21]
	s_nop 0
	v_pk_mul_f32 v[0:1], v[0:1], v[20:21]
	v_lshlrev_b32_e32 v20, 16, v17
	v_cvt_pk_bf16_f32 v0, v0, v1
	v_mul_f32_e32 v1, 0xbfb8aa3b, v18
	v_exp_f32_e32 v1, v1
	v_and_b32_e32 v21, 0xffff0000, v17
	v_pk_mul_f32 v[2:3], v[2:3], v[20:21]
	v_add_f32_e32 v1, 1.0, v1
	v_rcp_f32_e32 v16, v1
	v_mul_f32_e32 v1, 0xbfb8aa3b, v19
	v_exp_f32_e32 v1, v1
	s_nop 0
	v_add_f32_e32 v1, 1.0, v1
	v_rcp_f32_e32 v17, v1
	s_nop 0
	v_pk_mul_f32 v[16:17], v[16:17], v[18:19]
	s_nop 0
	v_pk_mul_f32 v[2:3], v[2:3], v[16:17]
	s_nop 0
	v_cvt_pk_bf16_f32 v1, v2, v3
	global_store_dwordx2 v[14:15], v[0:1], off offset:256
	s_barrier

; DI void dn_prep(const Params& p, int layer, int cgi, int h, unsigned char* lds) {
;     ...
; #pragma unroll
;   for (int i = 0; i < 7; ++i) {
;     const int ch = tid + 256 * i;
;     if (ch < 1632) {
;       const int tr = ch / 24, rem = ch - tr * 24, m = rem >> 3, c8 = rem & 7, tt = t0 - 2 + tr;
;       u32x4 v = {0u, 0u, 0u, 0u};
;       if (tt >= s0 && tt < s0 + S) v = *(const u32x4*)(proj + (size_t)tt * PP + B_Q + m * 256 + h * 64 + c8 * 8);
;       *(u32x4*)(stg + tr * 200 + m * 64 + c8 * 8) = v;
;     }
;   }
.LBB0_182:
	s_andn2_b64 vcc, exec, s[0:1]
	s_cbranch_vccnz .LBB0_115
	s_ashr_i32 s0, s4, 2
	s_and_b32 s21, s4, 3
	s_lshl_b32 s38, s0, 6
	s_cmpk_lt_i32 s0, 0x200
	s_movk_i32 s0, 0xc000
	v_mov_b32_e32 v100, v180
	s_cselect_b32 s0, s0, 0x7ffff000
	s_cselect_b32 s1, s30, 0x1000
	s_and_b32 s7, s0, s38
	v_and_b32_e32 v0, 7, v100
	s_movk_i32 s0, 0x660
	s_add_i32 s15, s38, -2
	s_add_i32 s14, s7, s1
	s_lshl_b32 s6, s21, 6
	v_lshlrev_b32_e32 v5, 3, v0
	v_lshlrev_b32_e32 v4, 4, v0
	v_cmp_gt_i32_e32 vcc, s0, v100
	s_and_saveexec_b64 s[8:9], vcc
	s_cbranch_execz .LBB0_187
	s_mov_b32 s0, 0x2aaaaaab
	v_mul_hi_i32 v204, v100, s0
	v_lshrrev_b32_e32 v205, 31, v204
	v_ashrrev_i32_e32 v204, 2, v204
	v_add_u32_e32 v6, v204, v205
	s_movk_i32 s0, 0xffe8
	v_mad_u64_u32 v[204:205], s[0:1], v6, s0, v[100:101]
	v_add_u32_e32 v8, s15, v6
	v_cmp_le_i32_e32 vcc, s7, v8
	v_cmp_gt_i32_e64 s[0:1], s14, v8
	v_ashrrev_i32_e32 v7, 3, v204
	s_and_b64 s[16:17], vcc, s[0:1]
	v_mov_b32_e32 v204, 0
	v_mov_b32_e32 v205, 0
	v_mov_b32_e32 v206, 0
	v_mov_b32_e32 v207, 0
	s_and_saveexec_b64 s[0:1], s[16:17]
	s_cbranch_execz .LBB0_186
	v_mov_b64_e32 v[204:205], s[46:47]
	v_lshlrev_b32_e32 v206, 8, v7
	v_mad_i64_i32 v[204:205], s[16:17], v8, s12, v[204:205]
	v_ashrrev_i32_e32 v207, 31, v206
	v_lshl_add_u64 v[204:205], v[206:207], 1, v[204:205]
	s_lshl_b32 s84, s6, 1
	v_lshl_add_u64 v[204:205], v[204:205], 0, s[84:85]
	v_lshlrev_b32_e32 v160, 1, v5
	v_lshl_add_u64 v[204:205], v[204:205], 0, v[160:161]
	global_load_dwordx4 v[204:207], v[204:205], off offset:1536
.LBB0_186:
	s_or_b64 exec, exec, s[0:1]
	s_movk_i32 s0, 0x190
	v_mul_lo_u32 v6, v6, s0
	v_add_u32_e32 v6, 0, v6
	v_lshlrev_b32_e32 v7, 7, v7
	v_add3_u32 v232, v6, v7, v4
.LBB0_187:
	s_or_b64 exec, exec, s[8:9]
	s_movk_i32 s0, 0x560
	v_add_u32_e32 v102, 0x100, v100
	v_cmp_gt_i32_e32 vcc, s0, v100
	s_and_saveexec_b64 s[8:9], vcc
	s_cbranch_execz .LBB0_191
	s_mov_b32 s0, 0x2aaaaaab
	v_mul_hi_i32 v208, v102, s0
	v_lshrrev_b32_e32 v209, 31, v208
	v_ashrrev_i32_e32 v208, 2, v208
	v_add_u32_e32 v6, v208, v209
	s_movk_i32 s0, 0xffe8
	v_mad_u64_u32 v[208:209], s[0:1], v6, s0, v[102:103]
	v_add_u32_e32 v8, s15, v6
	v_cmp_le_i32_e32 vcc, s7, v8
	v_cmp_gt_i32_e64 s[0:1], s14, v8
	v_ashrrev_i32_e32 v7, 3, v208
	s_and_b64 s[16:17], vcc, s[0:1]
	v_mov_b32_e32 v208, 0
	v_mov_b32_e32 v209, 0
	v_mov_b32_e32 v210, 0
	v_mov_b32_e32 v211, 0
	s_and_saveexec_b64 s[0:1], s[16:17]
	s_cbranch_execz .LBB0_190
	v_mov_b64_e32 v[208:209], s[46:47]
	v_lshlrev_b32_e32 v210, 8, v7
	v_mad_i64_i32 v[208:209], s[16:17], v8, s12, v[208:209]
	v_ashrrev_i32_e32 v211, 31, v210
	v_lshl_add_u64 v[208:209], v[210:211], 1, v[208:209]
	s_lshl_b32 s84, s6, 1
	v_lshl_add_u64 v[208:209], v[208:209], 0, s[84:85]
	v_lshlrev_b32_e32 v160, 1, v5
	v_lshl_add_u64 v[208:209], v[208:209], 0, v[160:161]
	global_load_dwordx4 v[208:211], v[208:209], off offset:1536
.LBB0_190:
	s_or_b64 exec, exec, s[0:1]
	s_movk_i32 s0, 0x190
	v_mul_lo_u32 v6, v6, s0
	v_add_u32_e32 v6, 0, v6
	v_lshlrev_b32_e32 v7, 7, v7
	v_add3_u32 v233, v6, v7, v4
.LBB0_191:
	s_or_b64 exec, exec, s[8:9]
	s_movk_i32 s0, 0x460
	v_add_u32_e32 v104, 0x200, v100
	v_cmp_gt_i32_e32 vcc, s0, v100
	s_and_saveexec_b64 s[8:9], vcc
	s_cbranch_execz .LBB0_195
	s_mov_b32 s0, 0x2aaaaaab
	v_mul_hi_i32 v212, v104, s0
	v_lshrrev_b32_e32 v213, 31, v212
	v_ashrrev_i32_e32 v212, 2, v212
	v_add_u32_e32 v6, v212, v213
	s_movk_i32 s0, 0xffe8
	v_mad_u64_u32 v[212:213], s[0:1], v6, s0, v[104:105]
	v_add_u32_e32 v8, s15, v6
	v_cmp_le_i32_e32 vcc, s7, v8
	v_cmp_gt_i32_e64 s[0:1], s14, v8
	v_ashrrev_i32_e32 v7, 3, v212
	s_and_b64 s[16:17], vcc, s[0:1]
	v_mov_b32_e32 v212, 0
	v_mov_b32_e32 v213, 0
	v_mov_b32_e32 v214, 0
	v_mov_b32_e32 v215, 0
	s_and_saveexec_b64 s[0:1], s[16:17]
	s_cbranch_execz .LBB0_194
	v_mov_b64_e32 v[212:213], s[46:47]
	v_lshlrev_b32_e32 v214, 8, v7
	v_mad_i64_i32 v[212:213], s[16:17], v8, s12, v[212:213]
	v_ashrrev_i32_e32 v215, 31, v214
	v_lshl_add_u64 v[212:213], v[214:215], 1, v[212:213]
	s_lshl_b32 s84, s6, 1
	v_lshl_add_u64 v[212:213], v[212:213], 0, s[84:85]
	v_lshlrev_b32_e32 v160, 1, v5
	v_lshl_add_u64 v[212:213], v[212:213], 0, v[160:161]
	global_load_dwordx4 v[212:215], v[212:213], off offset:1536
.LBB0_194:
	s_or_b64 exec, exec, s[0:1]
	s_movk_i32 s0, 0x190
	v_mul_lo_u32 v6, v6, s0
	v_add_u32_e32 v6, 0, v6
	v_lshlrev_b32_e32 v7, 7, v7
	v_add3_u32 v234, v6, v7, v4
.LBB0_195:
	s_or_b64 exec, exec, s[8:9]
	s_movk_i32 s0, 0x360
	v_add_u32_e32 v106, 0x300, v100
	v_cmp_gt_i32_e32 vcc, s0, v100
	s_and_saveexec_b64 s[8:9], vcc
	s_cbranch_execz .LBB0_199
	s_mov_b32 s0, 0x2aaaaaab
	v_mul_hi_i32 v216, v106, s0
	v_lshrrev_b32_e32 v217, 31, v216
	v_ashrrev_i32_e32 v216, 2, v216
	v_add_u32_e32 v6, v216, v217
	s_movk_i32 s0, 0xffe8
	v_mad_u64_u32 v[216:217], s[0:1], v6, s0, v[106:107]
	v_add_u32_e32 v8, s15, v6
	v_cmp_le_i32_e32 vcc, s7, v8
	v_cmp_gt_i32_e64 s[0:1], s14, v8
	v_ashrrev_i32_e32 v7, 3, v216
	s_and_b64 s[16:17], vcc, s[0:1]
	v_mov_b32_e32 v216, 0
	v_mov_b32_e32 v217, 0
	v_mov_b32_e32 v218, 0
	v_mov_b32_e32 v219, 0
	s_and_saveexec_b64 s[0:1], s[16:17]
	s_cbranch_execz .LBB0_198
	v_mov_b64_e32 v[216:217], s[46:47]
	v_lshlrev_b32_e32 v218, 8, v7
	v_mad_i64_i32 v[216:217], s[16:17], v8, s12, v[216:217]
	v_ashrrev_i32_e32 v219, 31, v218
	v_lshl_add_u64 v[216:217], v[218:219], 1, v[216:217]
	s_lshl_b32 s84, s6, 1
	v_lshl_add_u64 v[216:217], v[216:217], 0, s[84:85]
	v_lshlrev_b32_e32 v160, 1, v5
	v_lshl_add_u64 v[216:217], v[216:217], 0, v[160:161]
	global_load_dwordx4 v[216:219], v[216:217], off offset:1536
.LBB0_198:
	s_or_b64 exec, exec, s[0:1]
	s_movk_i32 s0, 0x190
	v_mul_lo_u32 v6, v6, s0
	v_add_u32_e32 v6, 0, v6
	v_lshlrev_b32_e32 v7, 7, v7
	v_add3_u32 v235, v6, v7, v4
; DI void dn_prep(const Params& p, int layer, int cgi, int h, unsigned char* lds) {
;     ...
; #pragma unroll
;   for (int i = 0; i < 7; ++i) {
;     const int ch = tid + 256 * i;
;     if (ch < 1632) {
;       const int tr = ch / 24, rem = ch - tr * 24, m = rem >> 3, c8 = rem & 7, tt = t0 - 2 + tr;
;       u32x4 v = {0u, 0u, 0u, 0u};
;       if (tt >= s0 && tt < s0 + S) v = *(const u32x4*)(proj + (size_t)tt * PP + B_Q + m * 256 + h * 64 + c8 * 8);
;       *(u32x4*)(stg + tr * 200 + m * 64 + c8 * 8) = v;
;     }
;   }
;   __syncthreads();
.LBB0_199:
	s_or_b64 exec, exec, s[8:9]
	s_movk_i32 s0, 0x260
	v_cmp_gt_i32_e32 vcc, s0, v100
	s_and_saveexec_b64 s[8:9], vcc
	s_cbranch_execz .LBB0_203
	v_add_u32_e32 v220, 0x400, v100
	s_mov_b32 s0, 0x2aaaaaab
	v_mul_hi_i32 v221, v220, s0
	v_lshrrev_b32_e32 v222, 31, v221
	v_ashrrev_i32_e32 v221, 2, v221
	v_add_u32_e32 v6, v221, v222
	s_movk_i32 s0, 0xffe8
	v_mad_u64_u32 v[220:221], s[0:1], v6, s0, v[220:221]
	v_add_u32_e32 v8, s15, v6
	v_cmp_le_i32_e32 vcc, s7, v8
	v_cmp_gt_i32_e64 s[0:1], s14, v8
	v_ashrrev_i32_e32 v7, 3, v220
	s_and_b64 s[16:17], vcc, s[0:1]
	v_mov_b32_e32 v220, 0
	v_mov_b32_e32 v221, 0
	v_mov_b32_e32 v222, 0
	v_mov_b32_e32 v223, 0
	s_and_saveexec_b64 s[0:1], s[16:17]
	s_cbranch_execz .LBB0_202
	v_mov_b64_e32 v[220:221], s[46:47]
	v_lshlrev_b32_e32 v222, 8, v7
	v_mad_i64_i32 v[220:221], s[16:17], v8, s12, v[220:221]
	v_ashrrev_i32_e32 v223, 31, v222
	v_lshl_add_u64 v[220:221], v[222:223], 1, v[220:221]
	s_lshl_b32 s84, s6, 1
	v_lshl_add_u64 v[220:221], v[220:221], 0, s[84:85]
	v_lshlrev_b32_e32 v160, 1, v5
	v_lshl_add_u64 v[220:221], v[220:221], 0, v[160:161]
	global_load_dwordx4 v[220:223], v[220:221], off offset:1536
.LBB0_202:
	s_or_b64 exec, exec, s[0:1]
	s_movk_i32 s0, 0x190
	v_mul_lo_u32 v6, v6, s0
	v_add_u32_e32 v6, 0, v6
	v_lshlrev_b32_e32 v7, 7, v7
	v_add3_u32 v236, v6, v7, v4
.LBB0_203:
	s_or_b64 exec, exec, s[8:9]
	s_movk_i32 s0, 0x160
	v_cmp_gt_i32_e32 vcc, s0, v100
	s_and_saveexec_b64 s[8:9], vcc
	s_cbranch_execz .LBB0_207
	v_add_u32_e32 v224, 0x500, v100
	s_mov_b32 s0, 0x2aaaaaab
	v_mul_hi_i32 v225, v224, s0
	v_lshrrev_b32_e32 v226, 31, v225
	v_ashrrev_i32_e32 v225, 2, v225
	v_add_u32_e32 v6, v225, v226
	s_movk_i32 s0, 0xffe8
	v_mad_u64_u32 v[224:225], s[0:1], v6, s0, v[224:225]
	v_add_u32_e32 v8, s15, v6
	v_cmp_le_i32_e32 vcc, s7, v8
	v_cmp_gt_i32_e64 s[0:1], s14, v8
	v_ashrrev_i32_e32 v7, 3, v224
	s_and_b64 s[16:17], vcc, s[0:1]
	v_mov_b32_e32 v224, 0
	v_mov_b32_e32 v225, 0
	v_mov_b32_e32 v226, 0
	v_mov_b32_e32 v227, 0
	s_and_saveexec_b64 s[0:1], s[16:17]
	s_cbranch_execz .LBB0_206
	v_mov_b64_e32 v[224:225], s[46:47]
	v_lshlrev_b32_e32 v226, 8, v7
	v_mad_i64_i32 v[224:225], s[16:17], v8, s12, v[224:225]
	v_ashrrev_i32_e32 v227, 31, v226
	v_lshl_add_u64 v[224:225], v[226:227], 1, v[224:225]
	s_lshl_b32 s84, s6, 1
	v_lshl_add_u64 v[224:225], v[224:225], 0, s[84:85]
	v_lshlrev_b32_e32 v160, 1, v5
	v_lshl_add_u64 v[224:225], v[224:225], 0, v[160:161]
	global_load_dwordx4 v[224:227], v[224:225], off offset:1536
.LBB0_206:
	s_or_b64 exec, exec, s[0:1]
	s_movk_i32 s0, 0x190
	v_mul_lo_u32 v6, v6, s0
	v_add_u32_e32 v6, 0, v6
	v_lshlrev_b32_e32 v7, 7, v7
	v_add3_u32 v237, v6, v7, v4
.LBB0_207:
	s_or_b64 exec, exec, s[8:9]
	s_movk_i32 s0, 0x60
	v_cmp_gt_i32_e32 vcc, s0, v100
	s_and_saveexec_b64 s[8:9], vcc
	s_cbranch_execz .LBB0_211
	v_add_u32_e32 v228, 0x600, v100
	s_mov_b32 s0, 0x2aaaaaab
	v_mul_hi_i32 v229, v228, s0
	v_lshrrev_b32_e32 v230, 31, v229
	v_ashrrev_i32_e32 v229, 2, v229
	v_add_u32_e32 v6, v229, v230
	s_movk_i32 s0, 0xffe8
	v_mad_u64_u32 v[228:229], s[0:1], v6, s0, v[228:229]
	v_add_u32_e32 v8, s15, v6
	v_cmp_le_i32_e32 vcc, s7, v8
	v_cmp_gt_i32_e64 s[0:1], s14, v8
	v_ashrrev_i32_e32 v7, 3, v228
	s_and_b64 s[14:15], vcc, s[0:1]
	v_mov_b32_e32 v228, 0
	v_mov_b32_e32 v229, 0
	v_mov_b32_e32 v230, 0
	v_mov_b32_e32 v231, 0
	s_and_saveexec_b64 s[0:1], s[14:15]
	s_cbranch_execz .LBB0_210
	v_mov_b64_e32 v[228:229], s[46:47]
	v_lshlrev_b32_e32 v230, 8, v7
	v_mad_i64_i32 v[228:229], s[14:15], v8, s12, v[228:229]
	v_ashrrev_i32_e32 v231, 31, v230
	v_lshl_add_u64 v[228:229], v[230:231], 1, v[228:229]
	s_lshl_b32 s84, s6, 1
	v_lshl_add_u64 v[228:229], v[228:229], 0, s[84:85]
	v_lshlrev_b32_e32 v160, 1, v5
	v_lshl_add_u64 v[228:229], v[228:229], 0, v[160:161]
	global_load_dwordx4 v[228:231], v[228:229], off offset:1536
.LBB0_210:
	s_or_b64 exec, exec, s[0:1]
	s_movk_i32 s0, 0x190
	v_mul_lo_u32 v5, v6, s0
	v_add_u32_e32 v5, 0, v5
	v_lshlrev_b32_e32 v6, 7, v7
	v_add3_u32 v238, v5, v6, v4
.LBB0_211:
	s_or_b64 exec, exec, s[8:9]
	s_waitcnt vmcnt(0)
	ds_write_b128 v232, v[204:207] offset:32768
	ds_write_b128 v233, v[208:211] offset:32768
	ds_write_b128 v234, v[212:215] offset:32768
	ds_write_b128 v235, v[216:219] offset:32768
	ds_write_b128 v236, v[220:223] offset:32768
	ds_write_b128 v237, v[224:227] offset:32768
	v_cmp_gt_i32_e32 vcc, 0x60, v100
	s_and_saveexec_b64 s[8:9], vcc
	ds_write_b128 v238, v[228:231] offset:32768
	s_or_b64 exec, exec, s[8:9]
	v_and_b32_e32 v0, 3, v100
	v_lshlrev_b32_e32 v101, 6, v0
	v_lshl_or_b32 v160, s6, 2, v101
	s_waitcnt lgkmcnt(0)
	s_barrier
; DI float silu(float x) { return x * __builtin_amdgcn_rcpf(1.f + __expf(-x)); }
; DI void unpack8(u32x4 v, float* x) { x[0] = bflo(v.x); x[1] = bfhi(v.x); x[2] = bflo(v.y); x[3] = bfhi(v.y); x[4] = bflo(v.z); x[5] = bfhi(v.z); x[6] = bflo(v.w); x[7] = bfhi(v.w); }
; DI void dn_prep(const Params& p, int layer, int cgi, int h, unsigned char* lds) {
;     ...
;   {
;     const int c = tid >> 2, sub = tid & 3;
;     const float* cw = p.conv_w + (size_t)layer * 5 * 768;
;     float res[3][16];
; #pragma unroll
;     for (int m = 0; m < 3; ++m) {
; #pragma unroll
;       for (int e = 0; e < 16; ++e) res[m][e] = 0.f;
;       const int chb = m * 256 + h * 64 + sub * 16;
; #pragma unroll
;       for (int tap = 0; tap < 5; ++tap) {
;         const bf16_t* src = stg + (c + tap) * 200 + m * 64 + sub * 16;
;         const u32x4 v0 = *(const u32x4*)src, v1 = *(const u32x4*)(src + 8);
;         float x[16]; unpack8(v0, x); unpack8(v1, x + 8);
;         const float* w = cw + tap * 768 + chb;
; #pragma unroll
;         for (int e4 = 0; e4 < 4; ++e4) { const f32x4 wv = *(const f32x4*)(w + 4 * e4); res[m][4 * e4] += x[4 * e4] * wv.x; res[m][4 * e4 + 1] += x[4 * e4 + 1] * wv.y; res[m][4 * e4 + 2] += x[4 * e4 + 2] * wv.z; res[m][4 * e4 + 3] += x[4 * e4 + 3] * wv.w; }
;       }
;       float ss = 0.f;
; #pragma unroll
;       for (int e = 0; e < 16; ++e) { res[m][e] = silu(res[m][e]); ss += res[m][e] * res[m][e]; }
	global_load_dwordx4 v[60:63], v160, s[36:37] offset:48
	global_load_dwordx4 v[64:67], v160, s[36:37] offset:3120
	v_lshl_add_u64 v[108:109], s[36:37], 0, v[160:161]
	s_mov_b64 s[0:1], 0x1800
	v_lshl_add_u64 v[92:93], v[108:109], 0, s[0:1]
	s_mov_b64 s[0:1], 0x2400
	global_load_dwordx4 v[68:71], v[92:93], off offset:48
	v_lshl_add_u64 v[94:95], v[108:109], 0, s[0:1]
	s_mov_b64 s[0:1], 0x3000
	global_load_dwordx4 v[84:87], v[94:95], off offset:48
	v_lshl_add_u64 v[114:115], v[108:109], 0, s[0:1]
	global_load_dwordx4 v[88:91], v[114:115], off offset:48
	v_ashrrev_i32_e32 v105, 2, v100
	s_movk_i32 s0, 0x190
	v_add_co_u32_e32 v116, vcc, s13, v108
	v_mul_lo_u32 v1, v105, s0
	v_lshlrev_b32_e32 v103, 5, v0
	v_addc_co_u32_e32 v117, vcc, 0, v109, vcc
	s_movk_i32 s0, 0x2000
	v_add3_u32 v107, 0, v103, v1
	global_load_dwordx4 v[4:7], v160, s[36:37] offset:32
	global_load_dwordx4 v[0:3], v160, s[36:37] offset:3104
	global_load_dwordx4 v[28:31], v160, s[36:37] offset:16
	global_load_dwordx4 v[52:55], v160, s[36:37]
	v_add_co_u32_e32 v110, vcc, s0, v108
	ds_read_b128 v[36:39], v107 offset:32768
	ds_read_b128 v[8:11], v107 offset:32784
	global_load_dwordx4 v[32:35], v160, s[36:37] offset:3088
	global_load_dwordx4 v[56:59], v160, s[36:37] offset:3072
	v_addc_co_u32_e32 v111, vcc, 0, v109, vcc
	s_movk_i32 s0, 0x3000
	v_add_co_u32_e32 v112, vcc, s0, v108
	ds_read_b128 v[40:43], v107 offset:33168
	ds_read_b128 v[12:15], v107 offset:33184
	ds_read_b128 v[44:47], v107 offset:33568
	ds_read_b128 v[16:19], v107 offset:33584
	global_load_dwordx4 v[80:83], v[116:117], off offset:2048
	global_load_dwordx4 v[72:75], v[110:111], off offset:1024
	v_addc_co_u32_e32 v113, vcc, 0, v109, vcc
	global_load_dwordx4 v[76:79], v[112:113], off
	ds_read_b128 v[48:51], v107 offset:33968
	ds_read_b128 v[24:27], v107 offset:33984
	ds_read_b128 v[20:23], v107 offset:34384
	ds_read_b128 v[118:121], v107 offset:34368
	global_load_dwordx4 v[122:125], v[92:93], off offset:32
	global_load_dwordx4 v[126:129], v[92:93], off offset:16
	global_load_dwordx4 v[130:133], v[94:95], off offset:32
	global_load_dwordx4 v[134:137], v[94:95], off offset:16
	global_load_dwordx4 v[138:141], v[114:115], off offset:16
	global_load_dwordx4 v[96:99], v[110:111], off offset:-4096
	s_nop 0
	global_load_dwordx4 v[92:95], v[116:117], off offset:1024
	s_waitcnt lgkmcnt(8)
	v_and_b32_e32 v143, 0xffff0000, v10
	v_lshlrev_b32_e32 v142, 16, v10
	s_waitcnt lgkmcnt(6)
	v_and_b32_e32 v145, 0xffff0000, v14
	v_lshlrev_b32_e32 v144, 16, v14
	s_waitcnt lgkmcnt(4)
	v_and_b32_e32 v147, 0xffff0000, v18
	v_lshlrev_b32_e32 v146, 16, v18
	s_waitcnt lgkmcnt(2)
	v_and_b32_e32 v149, 0xffff0000, v26
	v_lshlrev_b32_e32 v148, 16, v26
	s_waitcnt lgkmcnt(1)
	v_and_b32_e32 v151, 0xffff0000, v22
	v_lshlrev_b32_e32 v150, 16, v22
	v_and_b32_e32 v153, 0xffff0000, v11
	v_lshlrev_b32_e32 v152, 16, v11
	v_and_b32_e32 v11, 0xffff0000, v15
	v_lshlrev_b32_e32 v10, 16, v15
	v_and_b32_e32 v15, 0xffff0000, v19
	v_lshlrev_b32_e32 v14, 16, v19
	v_and_b32_e32 v19, 0xffff0000, v27
	v_lshlrev_b32_e32 v18, 16, v27
	v_and_b32_e32 v27, 0xffff0000, v23
	v_lshlrev_b32_e32 v26, 16, v23
	s_mov_b64 s[0:1], 0x1000
	v_cmp_lt_i32_e32 vcc, v185, v187
	s_mov_b64 s[6:7], 0x1400
	s_mov_b64 s[2:3], 0x2000
	s_waitcnt vmcnt(20)
	v_pk_fma_f32 v[22:23], v[60:61], v[142:143], 0 op_sel_hi:[1,1,0]
	v_pk_fma_f32 v[60:61], v[62:63], v[152:153], 0 op_sel_hi:[1,1,0]
	s_waitcnt vmcnt(19)
	v_pk_fma_f32 v[22:23], v[64:65], v[144:145], v[22:23]
	v_pk_fma_f32 v[10:11], v[66:67], v[10:11], v[60:61]
	global_load_dwordx4 v[64:67], v[116:117], off offset:3072
	global_load_dwordx4 v[60:63], v[110:111], off
	s_waitcnt vmcnt(20)
	v_pk_fma_f32 v[22:23], v[68:69], v[146:147], v[22:23]
	v_pk_fma_f32 v[10:11], v[70:71], v[14:15], v[10:11]
	global_load_dwordx4 v[68:71], v[114:115], off offset:32
	s_waitcnt vmcnt(20)
	v_pk_fma_f32 v[14:15], v[84:85], v[148:149], v[22:23]
	v_pk_fma_f32 v[10:11], v[86:87], v[18:19], v[10:11]
	s_waitcnt vmcnt(19)
	v_pk_fma_f32 v[14:15], v[88:89], v[150:151], v[14:15]
	v_cndmask_b32_e32 v84, v184, v185, vcc
	v_mul_f32_e32 v18, 0xbfb8aa3b, v14
	v_mul_f32_e32 v19, 0xbfb8aa3b, v15
	v_exp_f32_e32 v22, v18
	v_exp_f32_e32 v23, v19
	v_pk_fma_f32 v[18:19], v[90:91], v[26:27], v[10:11]
	v_lshl_add_u64 v[90:91], v[108:109], 0, s[0:1]
	v_mul_f32_e32 v11, 0xbfb8aa3b, v18
	v_add_f32_e32 v10, 1.0, v22
	v_add_f32_e32 v22, 1.0, v23
	v_exp_f32_e32 v23, v11
	v_mul_f32_e32 v11, 0xbfb8aa3b, v19
	v_exp_f32_e32 v27, v11
	v_rcp_f32_e32 v11, v22
	v_add_f32_e32 v22, 1.0, v23
	v_rcp_f32_e32 v26, v22
	v_add_f32_e32 v22, 1.0, v27
	v_rcp_f32_e32 v10, v10
	v_rcp_f32_e32 v27, v22
	s_mov_b64 s[0:1], 0x1c00
	v_lshlrev_b32_e32 v178, 2, v84
	v_pk_mul_f32 v[10:11], v[14:15], v[10:11]
	v_pk_mul_f32 v[14:15], v[18:19], v[26:27]
	v_lshlrev_b32_e32 v26, 16, v36
	v_and_b32_e32 v27, 0xffff0000, v36
	s_waitcnt vmcnt(15)
	v_pk_fma_f32 v[26:27], v[52:53], v[26:27], 0 op_sel_hi:[1,1,0]
	v_lshlrev_b32_e32 v52, 16, v40
	v_and_b32_e32 v53, 0xffff0000, v40
	s_waitcnt vmcnt(13)
	v_pk_fma_f32 v[26:27], v[56:57], v[52:53], v[26:27]
	v_lshlrev_b32_e32 v52, 16, v44
	v_and_b32_e32 v53, 0xffff0000, v44
	s_waitcnt vmcnt(12)
	v_pk_fma_f32 v[26:27], v[80:81], v[52:53], v[26:27]
	v_lshlrev_b32_e32 v52, 16, v48
	v_and_b32_e32 v53, 0xffff0000, v48
	s_waitcnt vmcnt(11)
	v_pk_fma_f32 v[26:27], v[72:73], v[52:53], v[26:27]
	s_waitcnt lgkmcnt(0)
	v_lshlrev_b32_e32 v52, 16, v118
	v_and_b32_e32 v53, 0xffff0000, v118
	s_waitcnt vmcnt(10)
; DI float silu(float x) { return x * __builtin_amdgcn_rcpf(1.f + __expf(-x)); }
; DI void unpack8(u32x4 v, float* x) { x[0] = bflo(v.x); x[1] = bfhi(v.x); x[2] = bflo(v.y); x[3] = bfhi(v.y); x[4] = bflo(v.z); x[5] = bfhi(v.z); x[6] = bflo(v.w); x[7] = bfhi(v.w); }
; DI void dn_prep(const Params& p, int layer, int cgi, int h, unsigned char* lds) {
;     ...
; #pragma unroll
;       for (int tap = 0; tap < 5; ++tap) {
;         const bf16_t* src = stg + (c + tap) * 200 + m * 64 + sub * 16;
;         const u32x4 v0 = *(const u32x4*)src, v1 = *(const u32x4*)(src + 8);
;         float x[16]; unpack8(v0, x); unpack8(v1, x + 8);
;         const float* w = cw + tap * 768 + chb;
; #pragma unroll
;         for (int e4 = 0; e4 < 4; ++e4) { const f32x4 wv = *(const f32x4*)(w + 4 * e4); res[m][4 * e4] += x[4 * e4] * wv.x; res[m][4 * e4 + 1] += x[4 * e4 + 1] * wv.y; res[m][4 * e4 + 2] += x[4 * e4 + 2] * wv.z; res[m][4 * e4 + 3] += x[4 * e4 + 3] * wv.w; }
;       }
;       float ss = 0.f;
; #pragma unroll
;       for (int e = 0; e < 16; ++e) { res[m][e] = silu(res[m][e]); ss += res[m][e] * res[m][e]; }
	v_pk_fma_f32 v[26:27], v[76:77], v[52:53], v[26:27]
	v_lshlrev_b32_e32 v88, 16, v12
	v_mul_f32_e32 v36, 0xbfb8aa3b, v26
	v_exp_f32_e32 v36, v36
	v_mul_f32_e32 v40, 0xbfb8aa3b, v27
	v_exp_f32_e32 v40, v40
	v_and_b32_e32 v89, 0xffff0000, v12
	v_add_f32_e32 v36, 1.0, v36
	v_rcp_f32_e32 v52, v36
	v_add_f32_e32 v36, 1.0, v40
	v_rcp_f32_e32 v53, v36
	v_lshlrev_b32_e32 v36, 16, v37
	v_and_b32_e32 v37, 0xffff0000, v37
	v_pk_fma_f32 v[36:37], v[54:55], v[36:37], 0 op_sel_hi:[1,1,0]
	v_lshlrev_b32_e32 v40, 16, v41
	v_and_b32_e32 v41, 0xffff0000, v41
	v_pk_fma_f32 v[36:37], v[58:59], v[40:41], v[36:37]
	v_lshlrev_b32_e32 v40, 16, v45
	v_and_b32_e32 v41, 0xffff0000, v45
	v_pk_fma_f32 v[36:37], v[82:83], v[40:41], v[36:37]
	v_lshlrev_b32_e32 v40, 16, v49
	v_and_b32_e32 v41, 0xffff0000, v49
	v_pk_fma_f32 v[36:37], v[74:75], v[40:41], v[36:37]
	v_lshlrev_b32_e32 v40, 16, v119
	v_and_b32_e32 v41, 0xffff0000, v119
	v_pk_fma_f32 v[36:37], v[78:79], v[40:41], v[36:37]
	v_pk_mul_f32 v[48:49], v[26:27], v[52:53]
	v_mul_f32_e32 v40, 0xbfb8aa3b, v36
	v_mul_f32_e32 v41, 0xbfb8aa3b, v37
	v_exp_f32_e32 v40, v40
	v_exp_f32_e32 v41, v41
	v_pk_mul_f32 v[22:23], v[10:11], v[10:11]
	v_pk_mul_f32 v[18:19], v[14:15], v[14:15]
	v_add_f32_e32 v26, 1.0, v40
	v_add_f32_e32 v27, 1.0, v41
	v_lshlrev_b32_e32 v40, 16, v38
	v_and_b32_e32 v41, 0xffff0000, v38
	v_pk_fma_f32 v[28:29], v[28:29], v[40:41], 0 op_sel_hi:[1,1,0]
	v_lshlrev_b32_e32 v40, 16, v42
	v_and_b32_e32 v41, 0xffff0000, v42
	v_pk_fma_f32 v[28:29], v[32:33], v[40:41], v[28:29]
	v_lshlrev_b32_e32 v32, 16, v46
	v_and_b32_e32 v33, 0xffff0000, v46
	s_waitcnt vmcnt(8)
	v_pk_fma_f32 v[28:29], v[126:127], v[32:33], v[28:29]
	v_lshlrev_b32_e32 v32, 16, v50
	v_and_b32_e32 v33, 0xffff0000, v50
	s_waitcnt vmcnt(6)
	v_pk_fma_f32 v[28:29], v[134:135], v[32:33], v[28:29]
	v_lshlrev_b32_e32 v32, 16, v120
	v_and_b32_e32 v33, 0xffff0000, v120
	s_waitcnt vmcnt(5)
	v_pk_fma_f32 v[28:29], v[138:139], v[32:33], v[28:29]
	v_rcp_f32_e32 v26, v26
	v_mul_f32_e32 v32, 0xbfb8aa3b, v28
	v_mul_f32_e32 v33, 0xbfb8aa3b, v29
	v_rcp_f32_e32 v27, v27
	v_exp_f32_e32 v32, v32
	v_exp_f32_e32 v33, v33
	v_lshl_add_u64 v[126:127], v[108:109], 0, s[0:1]
	v_pk_mul_f32 v[52:53], v[36:37], v[26:27]
	v_add_f32_e32 v26, 1.0, v32
	v_add_f32_e32 v27, 1.0, v33
	v_lshlrev_b32_e32 v32, 16, v39
	v_and_b32_e32 v33, 0xffff0000, v39
	v_pk_fma_f32 v[30:31], v[30:31], v[32:33], 0 op_sel_hi:[1,1,0]
	v_lshlrev_b32_e32 v32, 16, v43
	v_and_b32_e32 v33, 0xffff0000, v43
	v_pk_fma_f32 v[30:31], v[34:35], v[32:33], v[30:31]
	v_lshlrev_b32_e32 v32, 16, v47
	v_and_b32_e32 v33, 0xffff0000, v47
	v_pk_fma_f32 v[30:31], v[128:129], v[32:33], v[30:31]
	v_lshlrev_b32_e32 v32, 16, v51
	v_and_b32_e32 v33, 0xffff0000, v51
	v_pk_fma_f32 v[30:31], v[136:137], v[32:33], v[30:31]
	v_lshlrev_b32_e32 v32, 16, v121
	v_and_b32_e32 v33, 0xffff0000, v121
	v_pk_fma_f32 v[50:51], v[140:141], v[32:33], v[30:31]
	v_rcp_f32_e32 v26, v26
	v_mul_f32_e32 v30, 0xbfb8aa3b, v50
	v_rcp_f32_e32 v27, v27
	v_exp_f32_e32 v30, v30
	v_mul_f32_e32 v31, 0xbfb8aa3b, v51
	v_exp_f32_e32 v31, v31
	v_pk_mul_f32 v[46:47], v[28:29], v[26:27]
	v_add_f32_e32 v26, 1.0, v30
	v_rcp_f32_e32 v58, v26
	v_add_f32_e32 v26, 1.0, v31
	v_rcp_f32_e32 v59, v26
	v_lshlrev_b32_e32 v26, 16, v8
	v_and_b32_e32 v27, 0xffff0000, v8
	v_pk_fma_f32 v[4:5], v[4:5], v[26:27], 0 op_sel_hi:[1,1,0]
	global_load_dwordx4 v[54:57], v160, s[36:37] offset:1072
	global_load_dwordx4 v[26:29], v160, s[36:37] offset:1056
	global_load_dwordx4 v[80:83], v[90:91], off offset:16
	global_load_dwordx4 v[30:33], v[90:91], off offset:32
	s_mov_b64 s[0:1], 0x2800
	global_load_dwordx4 v[72:75], v[126:127], off offset:48
	global_load_dwordx4 v[34:37], v[126:127], off offset:32
	v_lshl_add_u64 v[114:115], v[108:109], 0, s[0:1]
	s_mov_b64 s[0:1], 0x3400
	global_load_dwordx4 v[84:87], v[114:115], off offset:16
	global_load_dwordx4 v[38:41], v[114:115], off offset:32
	v_lshl_add_u64 v[158:159], v[108:109], 0, s[0:1]
	global_load_dwordx4 v[76:79], v[158:159], off offset:48
	global_load_dwordx4 v[42:45], v[158:159], off offset:32
	v_pk_fma_f32 v[0:1], v[0:1], v[88:89], v[4:5]
	global_load_dwordx4 v[88:91], v[90:91], off offset:48
	v_lshlrev_b32_e32 v4, 16, v16
	global_load_dwordx4 v[114:117], v[114:115], off offset:48
	v_and_b32_e32 v5, 0xffff0000, v16
	v_pk_fma_f32 v[0:1], v[122:123], v[4:5], v[0:1]
	v_lshlrev_b32_e32 v4, 16, v24
	v_and_b32_e32 v5, 0xffff0000, v24
	v_pk_fma_f32 v[0:1], v[130:131], v[4:5], v[0:1]
	v_lshlrev_b32_e32 v4, 16, v20
	v_and_b32_e32 v5, 0xffff0000, v20
	s_waitcnt vmcnt(12)
	v_pk_fma_f32 v[4:5], v[68:69], v[4:5], v[0:1]
	v_cmp_lt_i32_e32 vcc, v188, v187
	v_mul_f32_e32 v0, 0xbfb8aa3b, v4
	v_exp_f32_e32 v8, v0
	v_mul_f32_e32 v0, 0xbfb8aa3b, v5
	v_exp_f32_e32 v12, v0
	v_pk_mul_f32 v[0:1], v[50:51], v[58:59]
	v_lshlrev_b32_e32 v50, 16, v9
	v_and_b32_e32 v51, 0xffff0000, v9
	v_add_f32_e32 v16, 1.0, v12
	v_pk_fma_f32 v[6:7], v[6:7], v[50:51], 0 op_sel_hi:[1,1,0]
	v_lshlrev_b32_e32 v12, 16, v13
	v_and_b32_e32 v13, 0xffff0000, v13
	v_pk_fma_f32 v[2:3], v[2:3], v[12:13], v[6:7]
	v_lshlrev_b32_e32 v6, 16, v17
	v_and_b32_e32 v7, 0xffff0000, v17
	v_pk_fma_f32 v[2:3], v[124:125], v[6:7], v[2:3]
	v_lshlrev_b32_e32 v6, 16, v25
	v_and_b32_e32 v7, 0xffff0000, v25
	v_pk_fma_f32 v[2:3], v[132:133], v[6:7], v[2:3]
	v_lshlrev_b32_e32 v6, 16, v21
	v_and_b32_e32 v7, 0xffff0000, v21
	v_pk_fma_f32 v[2:3], v[70:71], v[6:7], v[2:3]
	global_load_dwordx4 v[68:71], v160, s[36:37] offset:1040
	global_load_dwordx4 v[118:121], v160, s[36:37] offset:1024
	global_load_dwordx4 v[122:125], v[126:127], off offset:16
	s_nop 0
	global_load_dwordx4 v[126:129], v[110:111], off offset:2048
	global_load_dwordx4 v[130:133], v[112:113], off offset:1024
	ds_read_b128 v[134:137], v107 offset:32896
	ds_read_b128 v[138:141], v107 offset:32912
	ds_read_b128 v[142:145], v107 offset:33296
	ds_read_b128 v[146:149], v107 offset:33312
	ds_read_b128 v[150:153], v107 offset:33696
	ds_read_b128 v[154:157], v107 offset:33712
	ds_read_b128 v[162:165], v107 offset:34096
	ds_read_b128 v[166:169], v107 offset:34112
	ds_read_b128 v[170:173], v107 offset:34496
	ds_read_b128 v[174:177], v107 offset:34512
	global_load_dwordx4 v[202:205], v[158:159], off offset:16
	v_add_f32_e32 v8, 1.0, v8
	v_rcp_f32_e32 v8, v8
	v_rcp_f32_e32 v9, v16
	s_waitcnt lgkmcnt(6)
; DI float silu(float x) { return x * __builtin_amdgcn_rcpf(1.f + __expf(-x)); }
; DI void unpack8(u32x4 v, float* x) { x[0] = bflo(v.x); x[1] = bfhi(v.x); x[2] = bflo(v.y); x[3] = bfhi(v.y); x[4] = bflo(v.z); x[5] = bfhi(v.z); x[6] = bflo(v.w); x[7] = bfhi(v.w); }
; DI void dn_prep(const Params& p, int layer, int cgi, int h, unsigned char* lds) {
;     ...
; #pragma unroll
;       for (int tap = 0; tap < 5; ++tap) {
;         const bf16_t* src = stg + (c + tap) * 200 + m * 64 + sub * 16;
;         const u32x4 v0 = *(const u32x4*)src, v1 = *(const u32x4*)(src + 8);
;         float x[16]; unpack8(v0, x); unpack8(v1, x + 8);
;         const float* w = cw + tap * 768 + chb;
; #pragma unroll
;         for (int e4 = 0; e4 < 4; ++e4) { const f32x4 wv = *(const f32x4*)(w + 4 * e4); res[m][4 * e4] += x[4 * e4] * wv.x; res[m][4 * e4 + 1] += x[4 * e4 + 1] * wv.y; res[m][4 * e4 + 2] += x[4 * e4 + 2] * wv.z; res[m][4 * e4 + 3] += x[4 * e4 + 3] * wv.w; }
;       }
;       float ss = 0.f;
; #pragma unroll
;       for (int e = 0; e < 16; ++e) { res[m][e] = silu(res[m][e]); ss += res[m][e] * res[m][e]; }
;       if (m < 2) {
;         ss += __shfl_xor(ss, 1); ss += __shfl_xor(ss, 2);
;         float rn = rsqrtf(ss + EPSF); if (m == 0) rn *= 0.125f;
; #pragma unroll
;         for (int e = 0; e < 16; ++e) res[m][e] *= rn;
	v_and_b32_e32 v21, 0xffff0000, v147
	v_lshlrev_b32_e32 v20, 16, v147
	v_and_b32_e32 v25, 0xffff0000, v140
	v_pk_mul_f32 v[4:5], v[4:5], v[8:9]
	v_and_b32_e32 v9, 0xffff0000, v139
	v_lshlrev_b32_e32 v8, 16, v139
	v_lshlrev_b32_e32 v24, 16, v140
	v_lshlrev_b32_e32 v50, 16, v135
	v_and_b32_e32 v51, 0xffff0000, v135
	v_lshlrev_b32_e32 v58, 16, v144
	v_and_b32_e32 v59, 0xffff0000, v144
	v_mul_f32_e32 v6, 0xbfb8aa3b, v2
	v_mul_f32_e32 v7, 0xbfb8aa3b, v3
	v_exp_f32_e32 v6, v6
	v_exp_f32_e32 v7, v7
	v_pk_mul_f32 v[16:17], v[0:1], v[0:1]
	v_pk_mul_f32 v[12:13], v[4:5], v[4:5]
	v_add_f32_e32 v6, 1.0, v6
	v_add_f32_e32 v7, 1.0, v7
	v_rcp_f32_e32 v6, v6
	v_rcp_f32_e32 v7, v7
	s_mov_b32 s0, 0x358637bd
	v_pk_mul_f32 v[2:3], v[2:3], v[6:7]
	s_nop 0
	v_pk_mul_f32 v[6:7], v[2:3], v[2:3]
	s_waitcnt vmcnt(17)
	v_pk_fma_f32 v[24:25], v[54:55], v[24:25], 0 op_sel_hi:[1,1,0]
	s_waitcnt vmcnt(16)
	v_pk_fma_f32 v[8:9], v[28:29], v[8:9], 0 op_sel_hi:[1,1,0]
	v_and_b32_e32 v29, 0xffff0000, v148
	s_waitcnt vmcnt(14)
	v_pk_fma_f32 v[8:9], v[32:33], v[20:21], v[8:9]
	s_waitcnt lgkmcnt(4)
	v_and_b32_e32 v21, 0xffff0000, v155
	v_lshlrev_b32_e32 v20, 16, v155
	s_waitcnt vmcnt(12)
	v_pk_fma_f32 v[8:9], v[36:37], v[20:21], v[8:9]
	s_waitcnt lgkmcnt(2)
	v_and_b32_e32 v21, 0xffff0000, v167
	v_lshlrev_b32_e32 v20, 16, v167
	s_waitcnt vmcnt(10)
	v_pk_fma_f32 v[8:9], v[40:41], v[20:21], v[8:9]
	s_waitcnt lgkmcnt(0)
	v_and_b32_e32 v21, 0xffff0000, v175
	v_lshlrev_b32_e32 v20, 16, v175
	s_waitcnt vmcnt(8)
	v_pk_fma_f32 v[8:9], v[44:45], v[20:21], v[8:9]
	v_lshlrev_b32_e32 v28, 16, v148
	v_mul_f32_e32 v20, 0xbfb8aa3b, v8
	v_mul_f32_e32 v21, 0xbfb8aa3b, v9
	v_exp_f32_e32 v20, v20
	v_exp_f32_e32 v21, v21
	s_waitcnt vmcnt(7)
	v_pk_fma_f32 v[24:25], v[88:89], v[28:29], v[24:25]
	v_and_b32_e32 v29, 0xffff0000, v156
	v_lshlrev_b32_e32 v28, 16, v156
	v_pk_fma_f32 v[24:25], v[72:73], v[28:29], v[24:25]
	v_and_b32_e32 v29, 0xffff0000, v168
	v_lshlrev_b32_e32 v28, 16, v168
	s_waitcnt vmcnt(6)
	v_pk_fma_f32 v[24:25], v[114:115], v[28:29], v[24:25]
	v_and_b32_e32 v29, 0xffff0000, v176
	v_lshlrev_b32_e32 v28, 16, v176
	v_pk_fma_f32 v[24:25], v[76:77], v[28:29], v[24:25]
	v_add_f32_e32 v20, 1.0, v20
	v_add_f32_e32 v21, 1.0, v21
	v_mul_f32_e32 v28, 0xbfb8aa3b, v24
	v_mul_f32_e32 v29, 0xbfb8aa3b, v25
	v_rcp_f32_e32 v20, v20
	v_rcp_f32_e32 v21, v21
	v_exp_f32_e32 v28, v28
	v_exp_f32_e32 v29, v29
	v_and_b32_e32 v33, 0xffff0000, v149
	v_pk_mul_f32 v[8:9], v[8:9], v[20:21]
	v_add_f32_e32 v20, 1.0, v28
	v_add_f32_e32 v21, 1.0, v29
	v_and_b32_e32 v29, 0xffff0000, v141
	v_lshlrev_b32_e32 v28, 16, v141
	v_pk_fma_f32 v[28:29], v[56:57], v[28:29], 0 op_sel_hi:[1,1,0]
	v_lshlrev_b32_e32 v32, 16, v149
	v_pk_fma_f32 v[28:29], v[90:91], v[32:33], v[28:29]
	v_and_b32_e32 v33, 0xffff0000, v157
	v_lshlrev_b32_e32 v32, 16, v157
	v_pk_fma_f32 v[28:29], v[74:75], v[32:33], v[28:29]
	v_and_b32_e32 v33, 0xffff0000, v169
	v_lshlrev_b32_e32 v32, 16, v169
	v_pk_fma_f32 v[28:29], v[116:117], v[32:33], v[28:29]
	v_and_b32_e32 v33, 0xffff0000, v177
	v_lshlrev_b32_e32 v32, 16, v177
	v_pk_fma_f32 v[28:29], v[78:79], v[32:33], v[28:29]
	v_rcp_f32_e32 v20, v20
	v_mul_f32_e32 v32, 0xbfb8aa3b, v28
	v_mul_f32_e32 v33, 0xbfb8aa3b, v29
	v_exp_f32_e32 v32, v32
	v_exp_f32_e32 v33, v33
	v_rcp_f32_e32 v21, v21
	s_waitcnt vmcnt(4)
	v_pk_fma_f32 v[50:51], v[120:121], v[50:51], 0 op_sel_hi:[1,1,0]
	v_add_f32_e32 v32, 1.0, v32
	v_add_f32_e32 v33, 1.0, v33
	v_rcp_f32_e32 v32, v32
	v_rcp_f32_e32 v33, v33
	v_pk_mul_f32 v[40:41], v[24:25], v[20:21]
	v_lshlrev_b32_e32 v24, 16, v134
	v_and_b32_e32 v25, 0xffff0000, v134
	v_pk_mul_f32 v[44:45], v[28:29], v[32:33]
	v_pk_fma_f32 v[24:25], v[118:119], v[24:25], 0 op_sel_hi:[1,1,0]
	v_lshlrev_b32_e32 v28, 16, v142
	v_and_b32_e32 v29, 0xffff0000, v142
	v_pk_fma_f32 v[24:25], v[96:97], v[28:29], v[24:25]
	v_lshlrev_b32_e32 v28, 16, v150
	v_and_b32_e32 v29, 0xffff0000, v150
	v_lshlrev_b32_e32 v54, 16, v143
	v_and_b32_e32 v55, 0xffff0000, v143
	v_pk_fma_f32 v[24:25], v[64:65], v[28:29], v[24:25]
	v_pk_fma_f32 v[50:51], v[98:99], v[54:55], v[50:51]
	v_lshlrev_b32_e32 v54, 16, v151
	v_and_b32_e32 v55, 0xffff0000, v151
	v_lshlrev_b32_e32 v56, 16, v136
	v_and_b32_e32 v57, 0xffff0000, v136
	v_lshlrev_b32_e32 v64, 16, v137
	v_and_b32_e32 v65, 0xffff0000, v137
	v_lshlrev_b32_e32 v28, 16, v162
	v_and_b32_e32 v29, 0xffff0000, v162
	v_pk_fma_f32 v[50:51], v[66:67], v[54:55], v[50:51]
	v_pk_fma_f32 v[56:57], v[68:69], v[56:57], 0 op_sel_hi:[1,1,0]
	v_pk_fma_f32 v[64:65], v[70:71], v[64:65], 0 op_sel_hi:[1,1,0]
	v_lshlrev_b32_e32 v66, 16, v145
	v_and_b32_e32 v67, 0xffff0000, v145
	s_waitcnt vmcnt(2)
	v_pk_fma_f32 v[24:25], v[126:127], v[28:29], v[24:25]
	v_lshlrev_b32_e32 v28, 16, v170
	v_and_b32_e32 v29, 0xffff0000, v170
	v_pk_fma_f32 v[56:57], v[80:81], v[58:59], v[56:57]
	v_lshlrev_b32_e32 v58, 16, v152
	v_and_b32_e32 v59, 0xffff0000, v152
	v_pk_fma_f32 v[64:65], v[82:83], v[66:67], v[64:65]
	v_lshlrev_b32_e32 v66, 16, v153
	v_and_b32_e32 v67, 0xffff0000, v153
	s_waitcnt vmcnt(1)
	v_pk_fma_f32 v[24:25], v[130:131], v[28:29], v[24:25]
	v_lshlrev_b32_e32 v54, 16, v163
	v_and_b32_e32 v55, 0xffff0000, v163
	v_pk_fma_f32 v[56:57], v[122:123], v[58:59], v[56:57]
	v_lshlrev_b32_e32 v58, 16, v164
	v_and_b32_e32 v59, 0xffff0000, v164
	v_pk_fma_f32 v[64:65], v[124:125], v[66:67], v[64:65]
	v_lshlrev_b32_e32 v66, 16, v165
	v_and_b32_e32 v67, 0xffff0000, v165
	v_mul_f32_e32 v28, 0xbfb8aa3b, v24
	v_pk_fma_f32 v[50:51], v[128:129], v[54:55], v[50:51]
	v_lshlrev_b32_e32 v54, 16, v171
	v_and_b32_e32 v55, 0xffff0000, v171
	v_pk_fma_f32 v[56:57], v[84:85], v[58:59], v[56:57]
	v_lshlrev_b32_e32 v58, 16, v172
	v_and_b32_e32 v59, 0xffff0000, v172
	v_pk_fma_f32 v[64:65], v[86:87], v[66:67], v[64:65]
	v_lshlrev_b32_e32 v66, 16, v173
	v_and_b32_e32 v67, 0xffff0000, v173
	v_exp_f32_e32 v32, v28
	v_mul_f32_e32 v28, 0xbfb8aa3b, v25
	v_pk_fma_f32 v[50:51], v[132:133], v[54:55], v[50:51]
	s_waitcnt vmcnt(0)
; DI float silu(float x) { return x * __builtin_amdgcn_rcpf(1.f + __expf(-x)); }
; DI void dn_prep(const Params& p, int layer, int cgi, int h, unsigned char* lds) {
;     ...
;       float ss = 0.f;
; #pragma unroll
;       for (int e = 0; e < 16; ++e) { res[m][e] = silu(res[m][e]); ss += res[m][e] * res[m][e]; }
;       if (m < 2) {
;         ss += __shfl_xor(ss, 1); ss += __shfl_xor(ss, 2);
;         float rn = rsqrtf(ss + EPSF); if (m == 0) rn *= 0.125f;
; #pragma unroll
;         for (int e = 0; e < 16; ++e) res[m][e] *= rn;
	v_pk_fma_f32 v[56:57], v[202:203], v[58:59], v[56:57]
	v_pk_fma_f32 v[64:65], v[204:205], v[66:67], v[64:65]
	global_load_dwordx4 v[96:99], v160, s[36:37] offset:2048
	v_exp_f32_e32 v33, v28
	v_mul_f32_e32 v54, 0xbfb8aa3b, v50
	v_mul_f32_e32 v55, 0xbfb8aa3b, v51
	v_mul_f32_e32 v58, 0xbfb8aa3b, v56
	v_mul_f32_e32 v59, 0xbfb8aa3b, v57
	v_mul_f32_e32 v66, 0xbfb8aa3b, v64
	v_mul_f32_e32 v67, 0xbfb8aa3b, v65
	v_exp_f32_e32 v54, v54
	v_exp_f32_e32 v55, v55
	v_exp_f32_e32 v58, v58
	v_exp_f32_e32 v59, v59
	v_exp_f32_e32 v66, v66
	v_exp_f32_e32 v67, v67
	global_load_dwordx4 v[76:79], v[110:111], off offset:3072
	global_load_dwordx4 v[72:75], v[112:113], off offset:2048
	v_add_f32_e32 v32, 1.0, v32
	v_add_f32_e32 v33, 1.0, v33
	v_rcp_f32_e32 v32, v32
	v_rcp_f32_e32 v33, v33
	v_add_f32_e32 v54, 1.0, v54
	v_add_f32_e32 v55, 1.0, v55
	v_add_f32_e32 v58, 1.0, v58
	v_add_f32_e32 v59, 1.0, v59
	v_add_f32_e32 v66, 1.0, v66
	v_add_f32_e32 v67, 1.0, v67
	v_rcp_f32_e32 v54, v54
	v_rcp_f32_e32 v55, v55
	v_rcp_f32_e32 v58, v58
	v_rcp_f32_e32 v59, v59
	v_rcp_f32_e32 v66, v66
	v_rcp_f32_e32 v67, v67
	v_pk_mul_f32 v[32:33], v[24:25], v[32:33]
	v_pk_mul_f32 v[50:51], v[50:51], v[54:55]
	v_pk_mul_f32 v[54:55], v[56:57], v[58:59]
	v_pk_mul_f32 v[56:57], v[64:65], v[66:67]
	v_mov_b32_e32 v64, v33
	v_mov_b32_e32 v65, v49
	v_mov_b32_e32 v58, v32
	v_mov_b32_e32 v59, v48
	v_pk_mul_f32 v[64:65], v[64:65], v[64:65]
	v_mov_b32_e32 v66, v51
	v_pk_fma_f32 v[58:59], v[58:59], v[58:59], v[64:65]
	v_mov_b32_e32 v64, v50
	v_mov_b32_e32 v65, v52
	v_mov_b32_e32 v67, v53
	v_pk_fma_f32 v[58:59], v[64:65], v[64:65], v[58:59]
	v_mov_b32_e32 v64, v54
	v_pk_fma_f32 v[58:59], v[66:67], v[66:67], v[58:59]
	v_mov_b32_e32 v65, v46
	v_mov_b32_e32 v66, v55
	v_mov_b32_e32 v67, v47
	v_pk_fma_f32 v[58:59], v[64:65], v[64:65], v[58:59]
	v_pk_mul_f32 v[24:25], v[56:57], v[56:57]
	v_pk_fma_f32 v[58:59], v[66:67], v[66:67], v[58:59]
	v_lshlrev_b32_e32 v66, 16, v138
	v_and_b32_e32 v67, 0xffff0000, v138
	v_pk_fma_f32 v[26:27], v[26:27], v[66:67], 0 op_sel_hi:[1,1,0]
	v_lshlrev_b32_e32 v66, 16, v146
	v_and_b32_e32 v67, 0xffff0000, v146
	v_pk_fma_f32 v[26:27], v[30:31], v[66:67], v[26:27]
	v_lshlrev_b32_e32 v30, 16, v154
	v_and_b32_e32 v31, 0xffff0000, v154
	v_pk_fma_f32 v[26:27], v[34:35], v[30:31], v[26:27]
	v_lshlrev_b32_e32 v30, 16, v166
	v_and_b32_e32 v31, 0xffff0000, v166
	v_pk_fma_f32 v[26:27], v[38:39], v[30:31], v[26:27]
	v_lshlrev_b32_e32 v30, 16, v174
	v_and_b32_e32 v31, 0xffff0000, v174
	v_pk_fma_f32 v[26:27], v[42:43], v[30:31], v[26:27]
	v_mov_b32_e32 v64, v24
	v_mul_f32_e32 v24, 0xbfb8aa3b, v26
	v_exp_f32_e32 v24, v24
	v_mul_f32_e32 v30, 0xbfb8aa3b, v27
	v_exp_f32_e32 v31, v30
	v_mov_b32_e32 v65, v16
	v_add_f32_e32 v16, 1.0, v24
	v_rcp_f32_e32 v30, v16
	v_add_f32_e32 v16, 1.0, v31
	v_rcp_f32_e32 v31, v16
	v_pk_add_f32 v[34:35], v[64:65], v[58:59]
	v_mov_b32_e32 v16, v25
	v_pk_add_f32 v[16:17], v[16:17], v[34:35]
	v_pk_mul_f32 v[42:43], v[26:27], v[30:31]
	v_mov_b32_e32 v27, v12
	v_pk_mul_f32 v[24:25], v[42:43], v[42:43]
	v_pk_mul_f32 v[36:37], v[8:9], v[8:9]
	v_mov_b32_e32 v26, v24
	v_pk_add_f32 v[16:17], v[16:17], v[26:27]
	v_mov_b32_e32 v12, v25
	v_pk_add_f32 v[12:13], v[12:13], v[16:17]
	v_mov_b32_e32 v16, v36
	v_mov_b32_e32 v17, v6
	v_pk_mul_f32 v[20:21], v[40:41], v[40:41]
	v_pk_add_f32 v[12:13], v[16:17], v[12:13]
	v_mov_b32_e32 v6, v37
	v_pk_add_f32 v[6:7], v[6:7], v[12:13]
	v_mov_b32_e32 v12, v20
	v_mov_b32_e32 v13, v22
	v_pk_mul_f32 v[28:29], v[44:45], v[44:45]
	v_pk_add_f32 v[6:7], v[12:13], v[6:7]
	v_mov_b32_e32 v22, v21
	v_pk_add_f32 v[6:7], v[22:23], v[6:7]
	v_mov_b32_e32 v12, v28
	v_mov_b32_e32 v13, v18
	v_pk_add_f32 v[6:7], v[12:13], v[6:7]
	v_mov_b32_e32 v18, v29
	v_pk_add_f32 v[6:7], v[18:19], v[6:7]
	ds_bpermute_b32 v13, v178, v7
	ds_bpermute_b32 v12, v178, v6
	v_cndmask_b32_e32 v16, v184, v188, vcc
	v_lshlrev_b32_e32 v16, 2, v16
	global_load_dwordx4 v[110:113], v160, s[36:37] offset:2064
	s_waitcnt lgkmcnt(0)
	v_pk_add_f32 v[6:7], v[6:7], v[12:13]
	ds_bpermute_b32 v13, v16, v7
	ds_bpermute_b32 v12, v16, v6
	s_waitcnt lgkmcnt(0)
	v_pk_add_f32 v[6:7], v[6:7], v[12:13]
	s_nop 0
	v_pk_add_f32 v[6:7], v[6:7], s[0:1] op_sel_hi:[1,0]
	s_mul_i32 s1, s4, 0x10400
	v_mul_f32_e32 v12, 0x4b800000, v7
	v_cmp_gt_f32_e32 vcc, s44, v7
	s_mul_hi_i32 s0, s4, 0x10400
	s_add_u32 s34, s10, s1
	v_cndmask_b32_e32 v7, v7, v12, vcc
	v_rsq_f32_e32 v7, v7
	s_addc_u32 s35, s11, s0
	v_mul_f32_e32 v12, 0x45800000, v7
	v_cndmask_b32_e32 v7, v7, v12, vcc
	v_mul_f32_e32 v12, 0x3e000000, v7
	v_pk_mul_f32 v[26:27], v[0:1], v[12:13] op_sel_hi:[1,0]
	v_mul_f32_e32 v0, 0x4b800000, v6
	v_cmp_gt_f32_e32 vcc, s44, v6
	v_pk_mul_f32 v[28:29], v[48:49], v[12:13] op_sel_hi:[1,0]
	v_pk_mul_f32 v[30:31], v[52:53], v[12:13] op_sel_hi:[1,0]
	v_cndmask_b32_e32 v0, v6, v0, vcc
	v_rsq_f32_e32 v0, v0
	v_pk_mul_f32 v[24:25], v[46:47], v[12:13] op_sel_hi:[1,0]
	v_pk_mul_f32 v[16:17], v[4:5], v[12:13] op_sel_hi:[1,0]
	v_pk_mul_f32 v[18:19], v[2:3], v[12:13] op_sel_hi:[1,0]
	v_pk_mul_f32 v[20:21], v[10:11], v[12:13] op_sel_hi:[1,0]
	v_pk_mul_f32 v[22:23], v[14:15], v[12:13] op_sel_hi:[1,0]
	v_mul_f32_e32 v1, 0x45800000, v0
	v_lshl_add_u64 v[12:13], v[108:109], 0, s[6:7]
	s_mov_b64 s[6:7], 0x2c00
	v_cndmask_b32_e32 v10, v0, v1, vcc
	global_load_dwordx4 v[88:91], v[12:13], off offset:32
	global_load_dwordx4 v[114:117], v[12:13], off offset:16
	v_lshl_add_u64 v[48:49], v[108:109], 0, s[2:3]
	global_load_dwordx4 v[36:39], v[12:13], off offset:48
	global_load_dwordx4 v[118:121], v[48:49], off offset:16
	v_lshl_add_u64 v[12:13], v[108:109], 0, s[6:7]
	s_mov_b64 s[6:7], 0x3800
	v_pk_mul_f32 v[4:5], v[32:33], v[10:11] op_sel_hi:[1,0]
	global_load_dwordx4 v[84:87], v[12:13], off offset:32
	global_load_dwordx4 v[122:125], v[12:13], off offset:16
	v_lshl_add_u64 v[108:109], v[108:109], 0, s[6:7]
	global_load_dwordx4 v[32:35], v[12:13], off offset:48
	global_load_dwordx4 v[126:129], v[108:109], off offset:16
	ds_read_b128 v[130:133], v107 offset:33024
	ds_read_b128 v[68:71], v107 offset:33040
	v_pk_mul_f32 v[0:1], v[54:55], v[10:11] op_sel_hi:[1,0]
	v_pk_mul_f32 v[2:3], v[56:57], v[10:11] op_sel_hi:[1,0]
	global_load_dwordx4 v[56:59], v160, s[36:37] offset:2096
	global_load_dwordx4 v[134:137], v160, s[36:37] offset:2080
	ds_read_b128 v[138:141], v107 offset:33424
	ds_read_b128 v[64:67], v107 offset:33440
	ds_read_b128 v[142:145], v107 offset:33824
	ds_read_b128 v[52:55], v107 offset:33840
	s_waitcnt lgkmcnt(5)
; DI float silu(float x) { return x * __builtin_amdgcn_rcpf(1.f + __expf(-x)); }
; DI void unpack8(u32x4 v, float* x) { x[0] = bflo(v.x); x[1] = bfhi(v.x); x[2] = bflo(v.y); x[3] = bfhi(v.y); x[4] = bflo(v.z); x[5] = bfhi(v.z); x[6] = bflo(v.w); x[7] = bfhi(v.w); }
; DI void dn_prep(const Params& p, int layer, int cgi, int h, unsigned char* lds) {
;     ...
; #pragma unroll
;       for (int tap = 0; tap < 5; ++tap) {
;         const bf16_t* src = stg + (c + tap) * 200 + m * 64 + sub * 16;
;         const u32x4 v0 = *(const u32x4*)src, v1 = *(const u32x4*)(src + 8);
;         float x[16]; unpack8(v0, x); unpack8(v1, x + 8);
;         const float* w = cw + tap * 768 + chb;
; #pragma unroll
;         for (int e4 = 0; e4 < 4; ++e4) { const f32x4 wv = *(const f32x4*)(w + 4 * e4); res[m][4 * e4] += x[4 * e4] * wv.x; res[m][4 * e4 + 1] += x[4 * e4 + 1] * wv.y; res[m][4 * e4 + 2] += x[4 * e4 + 2] * wv.z; res[m][4 * e4 + 3] += x[4 * e4 + 3] * wv.w; }
;       }
;       float ss = 0.f;
; #pragma unroll
;       for (int e = 0; e < 16; ++e) { res[m][e] = silu(res[m][e]); ss += res[m][e] * res[m][e]; }
	v_lshlrev_b32_e32 v80, 16, v130
	v_and_b32_e32 v81, 0xffff0000, v130
	v_pk_mul_f32 v[6:7], v[50:51], v[10:11] op_sel_hi:[1,0]
	v_pk_mul_f32 v[12:13], v[42:43], v[10:11] op_sel_hi:[1,0]
	v_pk_mul_f32 v[14:15], v[8:9], v[10:11] op_sel_hi:[1,0]
	v_pk_mul_f32 v[8:9], v[40:41], v[10:11] op_sel_hi:[1,0]
	v_pk_mul_f32 v[10:11], v[44:45], v[10:11] op_sel_hi:[1,0]
	global_load_dwordx4 v[44:47], v[48:49], off offset:48
	global_load_dwordx4 v[146:149], v[48:49], off offset:32
	ds_read_b128 v[150:153], v107 offset:34224
	ds_read_b128 v[48:51], v107 offset:34240
	ds_read_b128 v[154:157], v107 offset:34624
	ds_read_b128 v[40:43], v107 offset:34640
	s_waitcnt vmcnt(15)
	v_pk_fma_f32 v[80:81], v[96:97], v[80:81], 0 op_sel_hi:[1,1,0]
	s_waitcnt lgkmcnt(7)
	v_lshlrev_b32_e32 v82, 16, v138
	v_and_b32_e32 v83, 0xffff0000, v138
	v_pk_fma_f32 v[80:81], v[92:93], v[82:83], v[80:81]
	s_waitcnt lgkmcnt(5)
	v_lshlrev_b32_e32 v82, 16, v142
	v_and_b32_e32 v83, 0xffff0000, v142
	v_pk_fma_f32 v[60:61], v[60:61], v[82:83], v[80:81]
	s_waitcnt lgkmcnt(3)
	v_lshlrev_b32_e32 v80, 16, v150
	v_and_b32_e32 v81, 0xffff0000, v150
	s_waitcnt vmcnt(14)
	v_pk_fma_f32 v[60:61], v[76:77], v[80:81], v[60:61]
	global_load_dwordx4 v[80:83], v[108:109], off offset:48
	global_load_dwordx4 v[162:165], v[108:109], off offset:32
	s_waitcnt lgkmcnt(1)
	v_lshlrev_b32_e32 v76, 16, v154
	v_and_b32_e32 v77, 0xffff0000, v154
	s_waitcnt vmcnt(15)
	v_pk_fma_f32 v[60:61], v[72:73], v[76:77], v[60:61]
	v_lshlrev_b32_e32 v76, 16, v131
	v_and_b32_e32 v77, 0xffff0000, v131
	v_lshlrev_b32_e32 v96, 16, v68
	v_and_b32_e32 v97, 0xffff0000, v68
	v_pk_fma_f32 v[76:77], v[98:99], v[76:77], 0 op_sel_hi:[1,1,0]
	v_lshlrev_b32_e32 v98, 16, v64
	v_and_b32_e32 v99, 0xffff0000, v64
	v_lshlrev_b32_e32 v68, 16, v69
	v_and_b32_e32 v69, 0xffff0000, v69
	v_lshlrev_b32_e32 v92, 16, v139
	v_and_b32_e32 v93, 0xffff0000, v139
	v_lshlrev_b32_e32 v64, 16, v65
	v_and_b32_e32 v65, 0xffff0000, v65
	v_pk_fma_f32 v[76:77], v[94:95], v[92:93], v[76:77]
	v_lshlrev_b32_e32 v92, 16, v143
	v_and_b32_e32 v93, 0xffff0000, v143
	v_pk_fma_f32 v[62:63], v[62:63], v[92:93], v[76:77]
	v_lshlrev_b32_e32 v76, 16, v151
	v_and_b32_e32 v77, 0xffff0000, v151
	v_pk_fma_f32 v[62:63], v[78:79], v[76:77], v[62:63]
	v_lshlrev_b32_e32 v76, 16, v155
	v_and_b32_e32 v77, 0xffff0000, v155
	v_pk_fma_f32 v[62:63], v[74:75], v[76:77], v[62:63]
	v_lshlrev_b32_e32 v76, 16, v132
	v_and_b32_e32 v77, 0xffff0000, v132
	v_lshlrev_b32_e32 v92, 16, v133
	v_and_b32_e32 v93, 0xffff0000, v133
	s_waitcnt vmcnt(14)
	v_pk_fma_f32 v[76:77], v[110:111], v[76:77], 0 op_sel_hi:[1,1,0]
	v_lshlrev_b32_e32 v78, 16, v140
	v_and_b32_e32 v79, 0xffff0000, v140
	v_pk_fma_f32 v[92:93], v[112:113], v[92:93], 0 op_sel_hi:[1,1,0]
	v_lshlrev_b32_e32 v94, 16, v141
	v_and_b32_e32 v95, 0xffff0000, v141
	v_mul_f32_e32 v72, 0xbfb8aa3b, v60
	v_mul_f32_e32 v73, 0xbfb8aa3b, v61
	v_mul_f32_e32 v74, 0xbfb8aa3b, v62
	v_mul_f32_e32 v75, 0xbfb8aa3b, v63
	v_exp_f32_e32 v72, v72
	v_exp_f32_e32 v73, v73
	v_exp_f32_e32 v74, v74
	v_exp_f32_e32 v75, v75
	s_movk_i32 s2, 0xff90
	s_waitcnt vmcnt(12) lgkmcnt(0)
	v_pk_fma_f32 v[76:77], v[114:115], v[78:79], v[76:77]
	v_lshlrev_b32_e32 v78, 16, v144
	v_and_b32_e32 v79, 0xffff0000, v144
	v_pk_fma_f32 v[92:93], v[116:117], v[94:95], v[92:93]
	v_lshlrev_b32_e32 v94, 16, v145
	v_and_b32_e32 v95, 0xffff0000, v145
	s_waitcnt vmcnt(10)
	v_pk_fma_f32 v[76:77], v[118:119], v[78:79], v[76:77]
	v_lshlrev_b32_e32 v78, 16, v152
	v_and_b32_e32 v79, 0xffff0000, v152
	v_pk_fma_f32 v[92:93], v[120:121], v[94:95], v[92:93]
	v_lshlrev_b32_e32 v94, 16, v153
	v_and_b32_e32 v95, 0xffff0000, v153
	s_waitcnt vmcnt(4)
	v_pk_fma_f32 v[96:97], v[134:135], v[96:97], 0 op_sel_hi:[1,1,0]
	v_pk_fma_f32 v[68:69], v[136:137], v[68:69], 0 op_sel_hi:[1,1,0]
	v_pk_fma_f32 v[88:89], v[88:89], v[98:99], v[96:97]
	v_lshlrev_b32_e32 v96, 16, v52
	v_and_b32_e32 v97, 0xffff0000, v52
	v_pk_fma_f32 v[64:65], v[90:91], v[64:65], v[68:69]
	v_lshlrev_b32_e32 v52, 16, v53
	v_and_b32_e32 v53, 0xffff0000, v53
	v_pk_fma_f32 v[76:77], v[122:123], v[78:79], v[76:77]
	s_waitcnt vmcnt(2)
	v_pk_fma_f32 v[88:89], v[146:147], v[96:97], v[88:89]
	v_lshlrev_b32_e32 v96, 16, v48
	v_and_b32_e32 v97, 0xffff0000, v48
	v_pk_fma_f32 v[84:85], v[84:85], v[96:97], v[88:89]
	v_lshlrev_b32_e32 v88, 16, v40
	v_and_b32_e32 v89, 0xffff0000, v40
	v_pk_fma_f32 v[52:53], v[148:149], v[52:53], v[64:65]
	v_lshlrev_b32_e32 v64, 16, v70
	v_and_b32_e32 v65, 0xffff0000, v70
	v_pk_fma_f32 v[56:57], v[56:57], v[64:65], 0 op_sel_hi:[1,1,0]
	v_lshlrev_b32_e32 v64, 16, v66
	v_and_b32_e32 v65, 0xffff0000, v66
	s_waitcnt vmcnt(0)
	v_pk_fma_f32 v[84:85], v[162:163], v[88:89], v[84:85]
	v_pk_fma_f32 v[36:37], v[36:37], v[64:65], v[56:57]
	v_mul_f32_e32 v48, 0xbfb8aa3b, v85
	v_exp_f32_e32 v48, v48
	v_lshlrev_b32_e32 v56, 16, v54
	v_and_b32_e32 v57, 0xffff0000, v54
	v_pk_fma_f32 v[36:37], v[44:45], v[56:57], v[36:37]
	v_lshlrev_b32_e32 v44, 16, v50
	v_and_b32_e32 v45, 0xffff0000, v50
	v_pk_fma_f32 v[32:33], v[32:33], v[44:45], v[36:37]
	v_lshlrev_b32_e32 v44, 16, v71
	v_and_b32_e32 v45, 0xffff0000, v71
	v_add_f32_e32 v88, 1.0, v48
	v_lshlrev_b32_e32 v48, 16, v49
	v_and_b32_e32 v49, 0xffff0000, v49
	v_pk_fma_f32 v[44:45], v[58:59], v[44:45], 0 op_sel_hi:[1,1,0]
	v_lshlrev_b32_e32 v56, 16, v67
	v_and_b32_e32 v57, 0xffff0000, v67
	v_lshlrev_b32_e32 v78, 16, v156
	v_and_b32_e32 v79, 0xffff0000, v156
	v_pk_fma_f32 v[92:93], v[124:125], v[94:95], v[92:93]
	v_lshlrev_b32_e32 v94, 16, v157
	v_and_b32_e32 v95, 0xffff0000, v157
	v_pk_fma_f32 v[48:49], v[86:87], v[48:49], v[52:53]
	v_lshlrev_b32_e32 v52, 16, v41
	v_and_b32_e32 v53, 0xffff0000, v41
	v_pk_fma_f32 v[38:39], v[38:39], v[56:57], v[44:45]
	v_lshlrev_b32_e32 v44, 16, v55
	v_and_b32_e32 v45, 0xffff0000, v55
	v_pk_fma_f32 v[76:77], v[126:127], v[78:79], v[76:77]
	v_pk_fma_f32 v[92:93], v[128:129], v[94:95], v[92:93]
	v_pk_fma_f32 v[48:49], v[164:165], v[52:53], v[48:49]
	v_pk_fma_f32 v[38:39], v[46:47], v[44:45], v[38:39]
	v_lshlrev_b32_e32 v44, 16, v51
	v_and_b32_e32 v45, 0xffff0000, v51
	v_mul_f32_e32 v78, 0xbfb8aa3b, v76
	v_mul_f32_e32 v79, 0xbfb8aa3b, v77
	v_mul_f32_e32 v94, 0xbfb8aa3b, v92
	v_mul_f32_e32 v95, 0xbfb8aa3b, v93
	v_mul_f32_e32 v41, 0xbfb8aa3b, v48
	v_lshlrev_b32_e32 v36, 16, v42
	v_and_b32_e32 v37, 0xffff0000, v42
	v_pk_fma_f32 v[34:35], v[34:35], v[44:45], v[38:39]
	v_lshlrev_b32_e32 v38, 16, v43
	v_and_b32_e32 v39, 0xffff0000, v43
	v_lshl_add_u32 v43, v105, 8, 0
	v_exp_f32_e32 v78, v78
	v_exp_f32_e32 v79, v79
	v_exp_f32_e32 v94, v94
	v_exp_f32_e32 v95, v95
	v_mul_f32_e32 v40, 0xbfb8aa3b, v84
	v_exp_f32_e32 v52, v41
	v_mul_f32_e32 v41, 0xbfb8aa3b, v49
	v_pk_fma_f32 v[32:33], v[80:81], v[36:37], v[32:33]
	v_pk_fma_f32 v[34:35], v[82:83], v[38:39], v[34:35]
	v_add_u32_e32 v44, v43, v101
	v_exp_f32_e32 v40, v40
	v_exp_f32_e32 v53, v41
	v_mul_f32_e32 v36, 0xbfb8aa3b, v32
	v_mul_f32_e32 v37, 0xbfb8aa3b, v33
	v_mul_f32_e32 v38, 0xbfb8aa3b, v34
	v_mul_f32_e32 v39, 0xbfb8aa3b, v35
	s_barrier
; DI float bf2f(bf16_t v) { return __uint_as_float((unsigned)v << 16); }
; DI unsigned pk2(float lo, float hi) { f32x2 v = {lo, hi}; bfv2 b = __builtin_convertvector(v, bfv2); return __builtin_bit_cast(unsigned, b); }
; DI void dn_prep(const Params& p, int layer, int cgi, int h, unsigned char* lds) {
;     ...
;     __syncthreads();
; #pragma unroll
;     for (int m = 0; m < 3; ++m) {
;       float* d32 = m == 0 ? q32 : (m == 1 ? k32 : v32);
; #pragma unroll
;       for (int e4 = 0; e4 < 4; ++e4) *(f32x4*)(d32 + c * 64 + sub * 16 + 4 * e4) = (f32x4){res[m][4 * e4], res[m][4 * e4 + 1], res[m][4 * e4 + 2], res[m][4 * e4 + 3]};
;       if (m < 2) {
;         bf16_t* db = m == 0 ? qb : kb;
;         *(u32x4*)(db + c * 72 + sub * 16) = (u32x4){pk2(res[m][0], res[m][1]), pk2(res[m][2], res[m][3]), pk2(res[m][4], res[m][5]), pk2(res[m][6], res[m][7])};
;         *(u32x4*)(db + c * 72 + sub * 16 + 8) = (u32x4){pk2(res[m][8], res[m][9]), pk2(res[m][10], res[m][11]), pk2(res[m][12], res[m][13]), pk2(res[m][14], res[m][15])};
;       }
;     }
;   }
;   if (tid < 64) {
;     const bf16_t* row = proj + (size_t)(t0 + tid) * PP;
;     float beta[2], g[2];
; #pragma unroll
;     for (int d = 0; d < 2; ++d) {
;       const float braw = bf2f(row[B_BETA + d * 4 + h]), araw = bf2f(row[B_ALPHA + d * 4 + h]);
;       beta[d] = 1.f / (1.f + __expf(-braw));
;       const float xx = araw + p.dt_bias[layer * 8 + d * 4 + h];
;       const float sp = fmaxf(xx, 0.f) + log1pf(__expf(-fabsf(xx)));
;       g[d] = -__expf(p.a_log[layer * 8 + d * 4 + h]) * sp;
	ds_write_b128 v44, v[28:31] offset:32768
	ds_write_b128 v44, v[24:27] offset:32784
	ds_write_b128 v44, v[16:19] offset:32800
	ds_write_b128 v44, v[20:23] offset:32816
	v_cvt_pk_bf16_f32 v28, v28, v29
	v_cvt_pk_bf16_f32 v29, v30, v31
	v_cvt_pk_bf16_f32 v30, v24, v25
	v_mul_lo_u32 v24, v105, s2
	v_exp_f32_e32 v36, v36
	v_exp_f32_e32 v37, v37
	v_exp_f32_e32 v38, v38
	v_exp_f32_e32 v39, v39
	v_add_u32_e32 v25, v43, v24
	v_add_f32_e32 v72, 1.0, v72
	v_add_f32_e32 v73, 1.0, v73
	v_add_f32_e32 v74, 1.0, v74
	v_add_f32_e32 v75, 1.0, v75
	v_cvt_pk_bf16_f32 v31, v26, v27
	v_add_u32_e32 v26, v25, v103
	v_cvt_pk_bf16_f32 v16, v16, v17
	v_cvt_pk_bf16_f32 v17, v18, v19
	v_cvt_pk_bf16_f32 v18, v20, v21
	v_cvt_pk_bf16_f32 v19, v22, v23
	s_movk_i32 s2, 0x70
	v_rcp_f32_e32 v72, v72
	v_rcp_f32_e32 v73, v73
	v_rcp_f32_e32 v74, v74
	v_rcp_f32_e32 v75, v75
	v_add_f32_e32 v78, 1.0, v78
	v_add_f32_e32 v79, 1.0, v79
	v_add_f32_e32 v94, 1.0, v94
	v_add_f32_e32 v95, 1.0, v95
	ds_write_b128 v26, v[16:19] offset:49168
	v_mul_lo_u32 v16, v105, s2
	v_rcp_f32_e32 v78, v78
	v_rcp_f32_e32 v79, v79
	v_rcp_f32_e32 v94, v94
	v_rcp_f32_e32 v95, v95
	v_add_f32_e32 v40, 1.0, v40
	v_add_f32_e32 v52, 1.0, v52
	v_add_f32_e32 v53, 1.0, v53
	v_add_u32_e32 v17, v25, v16
	v_rcp_f32_e32 v40, v40
	v_rcp_f32_e32 v41, v88
	v_rcp_f32_e32 v52, v52
	v_rcp_f32_e32 v53, v53
	v_add_f32_e32 v36, 1.0, v36
	v_add_f32_e32 v37, 1.0, v37
	v_add_f32_e32 v38, 1.0, v38
	v_add_f32_e32 v39, 1.0, v39
	v_add_u32_e32 v18, v17, v101
	v_add_u32_e32 v17, v17, v24
	v_rcp_f32_e32 v36, v36
	v_rcp_f32_e32 v37, v37
	v_rcp_f32_e32 v38, v38
	v_rcp_f32_e32 v39, v39
	ds_write_b128 v26, v[28:31] offset:49152
	ds_write_b128 v18, v[4:7]
	ds_write_b128 v18, v[0:3] offset:16
	ds_write_b128 v18, v[12:15] offset:32
	ds_write_b128 v18, v[8:11] offset:48
	v_cvt_pk_bf16_f32 v4, v4, v5
	v_cvt_pk_bf16_f32 v5, v6, v7
	v_cvt_pk_bf16_f32 v6, v0, v1
	v_cvt_pk_bf16_f32 v7, v2, v3
	v_add_u32_e32 v18, v17, v103
	v_cvt_pk_bf16_f32 v0, v12, v13
	v_cvt_pk_bf16_f32 v1, v14, v15
	v_cvt_pk_bf16_f32 v2, v8, v9
	v_cvt_pk_bf16_f32 v3, v10, v11
	ds_write_b128 v18, v[4:7] offset:58368
	ds_write_b128 v18, v[0:3] offset:58384
	v_add3_u32 v4, v17, v16, v101
	v_pk_mul_f32 v[0:1], v[60:61], v[72:73]
	v_pk_mul_f32 v[2:3], v[62:63], v[74:75]
	ds_write_b128 v4, v[0:3] offset:16384
	v_pk_mul_f32 v[0:1], v[76:77], v[78:79]
	v_pk_mul_f32 v[2:3], v[92:93], v[94:95]
	ds_write_b128 v4, v[0:3] offset:16400
	v_pk_mul_f32 v[0:1], v[84:85], v[40:41]
	v_pk_mul_f32 v[2:3], v[48:49], v[52:53]
	v_and_b32_e32 v42, 63, v100
	ds_write_b128 v4, v[0:3] offset:16416
	v_pk_mul_f32 v[0:1], v[32:33], v[36:37]
	v_pk_mul_f32 v[2:3], v[34:35], v[38:39]
	v_cmp_gt_i32_e32 vcc, 64, v100
	ds_write_b128 v4, v[0:3] offset:16432
	s_and_saveexec_b64 s[8:9], vcc
	s_cbranch_execz .LBB0_213
	v_add_u32_e32 v2, s38, v100
	v_mov_b64_e32 v[0:1], s[46:47]
	v_mad_i64_i32 v[0:1], s[0:1], v2, s12, v[0:1]
	s_or_b32 s0, s21, s5
	s_lshl_b32 s84, s21, 1
	v_lshl_add_u64 v[0:1], v[0:1], 0, s[84:85]
	s_ashr_i32 s1, s0, 31
	v_add_co_u32_e32 v0, vcc, 0x1000, v0
	s_lshl_b64 s[38:39], s[0:1], 2
	s_nop 0
	v_addc_co_u32_e32 v1, vcc, 0, v1, vcc
	s_add_u32 s0, s64, s38
	global_load_ushort v2, v[0:1], off offset:2048
	global_load_ushort v3, v[0:1], off offset:2064
	s_addc_u32 s1, s65, s39
	global_load_dword v4, v161, s[0:1]
	global_load_ushort v5, v[0:1], off offset:2072
	global_load_ushort v6, v[0:1], off offset:2056
	s_add_u32 s6, s62, s38
	s_addc_u32 s7, s63, s39
	global_load_dword v7, v161, s[6:7]
	global_load_dword v8, v161, s[6:7] offset:16
	global_load_dword v9, v161, s[0:1] offset:16
	s_mov_b32 s14, 0xbfb8aa3b
	s_mov_b32 s2, 0x3f2aaaab
	s_mov_b32 s3, 0x3f317218
	s_mov_b32 s6, 0x7f800000
	s_mov_b32 s7, 0x33800000
	v_ashrrev_i32_e32 v101, 31, v100
	s_waitcnt vmcnt(7)
	v_lshlrev_b32_e32 v0, 16, v2
	s_waitcnt vmcnt(6)
	v_lshlrev_b32_e32 v1, 16, v3
	v_mul_f32_e32 v0, 0xbfb8aa3b, v0
	s_waitcnt vmcnt(5)
	v_add_f32_e32 v1, v4, v1
	v_exp_f32_e32 v0, v0
	v_max_f32_e32 v2, 0, v1
	v_mul_f32_e64 v1, |v1|, s14
	v_exp_f32_e32 v3, v1
	v_add_f32_e32 v4, 1.0, v0
	v_div_scale_f32 v10, s[0:1], v4, v4, 1.0
	v_add_f32_e32 v12, 1.0, v3
	v_rcp_f32_e32 v13, v10
	v_add_f32_e32 v14, -1.0, v12
	v_frexp_mant_f32_e32 v15, v12
	v_cvt_f64_f32_e32 v[0:1], v12
	v_sub_f32_e32 v16, v14, v12
	v_frexp_exp_i32_f64_e32 v0, v[0:1]
	v_cmp_gt_f32_e64 s[0:1], s2, v15
	v_sub_f32_e32 v14, v3, v14
	v_add_f32_e32 v1, 1.0, v16
	v_subbrev_co_u32_e64 v0, s[0:1], 0, v0, s[0:1]
	v_add_f32_e32 v1, v14, v1
	v_sub_u32_e32 v14, 0, v0
	v_cvt_f32_i32_e32 v0, v0
	v_fma_f32 v15, -v10, v13, 1.0
	v_ldexp_f32 v12, v12, v14
	v_div_scale_f32 v11, vcc, 1.0, v4, 1.0
	v_ldexp_f32 v1, v1, v14
	v_fmac_f32_e32 v13, v15, v13
	v_add_f32_e32 v14, -1.0, v12
	v_add_f32_e32 v15, 1.0, v12
	v_mul_f32_e32 v16, v11, v13
	v_add_f32_e32 v17, 1.0, v14
	v_add_f32_e32 v18, -1.0, v15
	v_fma_f32 v19, -v10, v16, v11
	v_sub_f32_e32 v17, v12, v17
	v_sub_f32_e32 v12, v12, v18
	v_mul_f32_e32 v18, 0x3f317218, v0
	v_fmac_f32_e32 v16, v19, v13
	v_add_f32_e32 v17, v1, v17
	v_add_f32_e32 v1, v1, v12
	v_fma_f32 v12, v0, s3, -v18
	v_fma_f32 v10, -v10, v16, v11
	v_add_f32_e32 v11, v14, v17
	v_add_f32_e32 v19, v15, v1
	v_fmac_f32_e32 v12, 0xb102e308, v0
	v_div_fmas_f32 v0, v10, v13, v16
	v_sub_f32_e32 v10, v11, v14
	v_rcp_f32_e32 v14, v19
	v_sub_f32_e32 v13, v19, v15
	v_add_f32_e32 v15, v18, v12
	v_div_fixup_f32 v4, v0, v4, 1.0
	v_sub_f32_e32 v0, v17, v10
	v_sub_f32_e32 v10, v15, v18
	v_sub_f32_e32 v10, v12, v10
	v_mul_f32_e32 v12, v11, v14
	v_sub_f32_e32 v1, v1, v13
	v_mul_f32_e32 v13, v19, v12
	v_fma_f32 v16, v12, v19, -v13
	v_fmac_f32_e32 v16, v12, v1
	v_add_f32_e32 v17, v13, v16
	v_sub_f32_e32 v18, v11, v17
; DI float bf2f(bf16_t v) { return __uint_as_float((unsigned)v << 16); }
; DI void dn_prep(const Params& p, int layer, int cgi, int h, unsigned char* lds) {
;     ...
;     for (int d = 0; d < 2; ++d) {
;       const float braw = bf2f(row[B_BETA + d * 4 + h]), araw = bf2f(row[B_ALPHA + d * 4 + h]);
;       beta[d] = 1.f / (1.f + __expf(-braw));
;       const float xx = araw + p.dt_bias[layer * 8 + d * 4 + h];
;       const float sp = fmaxf(xx, 0.f) + log1pf(__expf(-fabsf(xx)));
;       g[d] = -__expf(p.a_log[layer * 8 + d * 4 + h]) * sp;
	v_sub_f32_e32 v11, v11, v18
	v_sub_f32_e32 v13, v17, v13
	v_sub_f32_e32 v11, v11, v17
	v_sub_f32_e32 v13, v13, v16
	v_add_f32_e32 v0, v0, v11
	v_add_f32_e32 v0, v13, v0
	v_add_f32_e32 v11, v18, v0
	v_mul_f32_e32 v13, v14, v11
	v_sub_f32_e32 v16, v18, v11
	v_mul_f32_e32 v17, v19, v13
	v_add_f32_e32 v0, v0, v16
	v_add_f32_e32 v16, v12, v13
	v_fma_f32 v18, v13, v19, -v17
	v_sub_f32_e32 v12, v16, v12
	v_fmac_f32_e32 v18, v13, v1
	v_sub_f32_e32 v1, v13, v12
	v_add_f32_e32 v12, v17, v18
	v_sub_f32_e32 v13, v12, v17
	v_sub_f32_e32 v17, v11, v12
	v_sub_f32_e32 v11, v11, v17
	v_sub_f32_e32 v11, v11, v12
	v_sub_f32_e32 v13, v13, v18
	v_add_f32_e32 v0, v0, v11
	v_add_f32_e32 v0, v13, v0
	v_add_f32_e32 v0, v17, v0
	v_mul_f32_e32 v0, v14, v0
	v_add_f32_e32 v0, v1, v0
	v_add_f32_e32 v1, v16, v0
	v_mul_f32_e32 v11, v1, v1
	v_fmamk_f32 v14, v11, 0x3e9b6dac, v182
	v_sub_f32_e32 v12, v1, v16
	v_ldexp_f32 v13, v1, 1
	v_mul_f32_e32 v1, v1, v11
	v_fmaak_f32 v11, v11, v14, 0x3f2aaada
	v_mul_f32_e32 v1, v1, v11
	v_add_f32_e32 v11, v13, v1
	v_sub_f32_e32 v0, v0, v12
	v_sub_f32_e32 v12, v11, v13
	v_ldexp_f32 v0, v0, 1
	v_sub_f32_e32 v1, v1, v12
	v_add_f32_e32 v0, v0, v1
	v_add_f32_e32 v1, v11, v0
	v_sub_f32_e32 v11, v1, v11
	v_add_f32_e32 v12, v15, v1
	v_sub_f32_e32 v0, v0, v11
	v_sub_f32_e32 v11, v12, v15
	v_sub_f32_e32 v13, v12, v11
	v_sub_f32_e32 v1, v1, v11
	v_add_f32_e32 v11, v10, v0
	v_sub_f32_e32 v13, v15, v13
	v_sub_f32_e32 v14, v11, v10
	v_add_f32_e32 v1, v1, v13
	v_sub_f32_e32 v13, v11, v14
	v_sub_f32_e32 v0, v0, v14
	v_sub_f32_e32 v10, v10, v13
	v_add_f32_e32 v1, v11, v1
	v_add_f32_e32 v0, v0, v10
	v_add_f32_e32 v10, v12, v1
	v_sub_f32_e32 v11, v10, v12
	v_sub_f32_e32 v1, v1, v11
	v_add_f32_e32 v0, v0, v1
	s_waitcnt vmcnt(3)
	v_lshlrev_b32_e32 v1, 16, v6
	v_mul_f32_e32 v1, 0xbfb8aa3b, v1
	v_exp_f32_e32 v1, v1
	v_add_f32_e32 v0, v10, v0
	v_cmp_neq_f32_e32 vcc, s6, v3
	v_add_f32_e32 v6, 1.0, v1
	s_nop 0
	v_cndmask_b32_e32 v0, v195, v0, vcc
	v_cmp_ngt_f32_e32 vcc, -1.0, v3
	s_nop 1
	v_cndmask_b32_e32 v0, v196, v0, vcc
	v_cmp_neq_f32_e32 vcc, -1.0, v3
	s_nop 1
	v_cndmask_b32_e32 v0, v197, v0, vcc
	v_cmp_lt_f32_e64 vcc, |v3|, s7
	s_nop 1
	v_cndmask_b32_e32 v0, v0, v3, vcc
	s_waitcnt vmcnt(2)
	v_mul_f32_e32 v3, 0x3fb8aa3b, v7
	v_div_scale_f32 v7, s[0:1], v6, v6, 1.0
	v_rcp_f32_e32 v10, v7
	v_add_f32_e32 v2, v2, v0
	v_lshlrev_b32_e32 v0, 16, v5
	s_waitcnt vmcnt(0)
	v_add_f32_e32 v0, v9, v0
	v_fma_f32 v1, -v7, v10, 1.0
	v_fmac_f32_e32 v10, v1, v10
	v_mul_f32_e64 v1, |v0|, s14
	v_exp_f32_e32 v5, v1
	v_max_f32_e32 v12, 0, v0
	v_exp_f32_e32 v3, v3
	v_div_scale_f32 v9, vcc, 1.0, v6, 1.0
	v_add_f32_e32 v13, 1.0, v5
	v_add_f32_e32 v0, -1.0, v13
	v_sub_f32_e32 v1, v0, v13
	v_add_f32_e32 v1, 1.0, v1
	v_sub_f32_e32 v0, v5, v0
	v_add_f32_e32 v14, v0, v1
	v_frexp_mant_f32_e32 v15, v13
	v_cvt_f64_f32_e32 v[0:1], v13
	v_frexp_exp_i32_f64_e32 v0, v[0:1]
	v_cmp_gt_f32_e64 s[0:1], s2, v15
	v_mul_f32_e64 v11, v2, -v3
	s_nop 0
	v_subbrev_co_u32_e64 v0, s[0:1], 0, v0, s[0:1]
	v_sub_u32_e32 v1, 0, v0
	v_ldexp_f32 v13, v13, v1
	v_ldexp_f32 v1, v14, v1
	v_add_f32_e32 v14, -1.0, v13
	v_add_f32_e32 v17, 1.0, v13
	v_add_f32_e32 v15, 1.0, v14
	v_add_f32_e32 v18, -1.0, v17
	v_sub_f32_e32 v15, v13, v15
	v_sub_f32_e32 v13, v13, v18
	v_add_f32_e32 v15, v1, v15
	v_add_f32_e32 v1, v1, v13
	v_add_f32_e32 v13, v17, v1
	v_rcp_f32_e32 v18, v13
	v_add_f32_e32 v16, v14, v15
	v_sub_f32_e32 v14, v16, v14
	v_sub_f32_e32 v14, v15, v14
	v_sub_f32_e32 v15, v13, v17
	v_sub_f32_e32 v1, v1, v15
	v_mul_f32_e32 v15, v16, v18
	v_mul_f32_e32 v17, v13, v15
	v_fma_f32 v19, v15, v13, -v17
	v_fmac_f32_e32 v19, v15, v1
	v_add_f32_e32 v20, v17, v19
	v_sub_f32_e32 v21, v16, v20
	v_sub_f32_e32 v16, v16, v21
	v_sub_f32_e32 v17, v20, v17
	v_sub_f32_e32 v16, v16, v20
	v_add_f32_e32 v14, v14, v16
	v_sub_f32_e32 v16, v17, v19
	v_add_f32_e32 v14, v16, v14
	v_add_f32_e32 v16, v21, v14
	v_mul_f32_e32 v17, v18, v16
	v_mul_f32_e32 v19, v13, v17
	v_fma_f32 v13, v17, v13, -v19
	v_fmac_f32_e32 v13, v17, v1
	v_sub_f32_e32 v1, v21, v16
	v_add_f32_e32 v1, v14, v1
	v_add_f32_e32 v14, v19, v13
	v_sub_f32_e32 v20, v16, v14
	v_sub_f32_e32 v16, v16, v20
	v_sub_f32_e32 v19, v14, v19
	v_sub_f32_e32 v14, v16, v14
	v_add_f32_e32 v1, v1, v14
	v_sub_f32_e32 v13, v19, v13
	v_cvt_f32_i32_e32 v0, v0
	v_add_f32_e32 v1, v13, v1
	v_add_f32_e32 v13, v15, v17
	v_add_f32_e32 v1, v20, v1
	v_sub_f32_e32 v14, v13, v15
	v_mul_f32_e32 v1, v18, v1
	v_sub_f32_e32 v14, v17, v14
	v_add_f32_e32 v1, v14, v1
	v_mul_f32_e32 v17, 0x3f317218, v0
	v_add_f32_e32 v14, v13, v1
	v_fma_f32 v18, v0, s3, -v17
	v_mul_f32_e32 v15, v14, v14
	v_fmac_f32_e32 v18, 0xb102e308, v0
	v_sub_f32_e32 v0, v14, v13
	v_fmamk_f32 v16, v15, 0x3e9b6dac, v182
	v_sub_f32_e32 v0, v1, v0
	v_add_f32_e32 v1, v17, v18
	v_fmaak_f32 v16, v15, v16, 0x3f2aaada
	v_sub_f32_e32 v13, v1, v17
	v_ldexp_f32 v17, v14, 1
	v_mul_f32_e32 v14, v14, v15
	v_mul_f32_e32 v14, v14, v16
	v_add_f32_e32 v15, v17, v14
	v_sub_f32_e32 v16, v15, v17
	v_ldexp_f32 v0, v0, 1
	v_sub_f32_e32 v14, v14, v16
	v_add_f32_e32 v0, v0, v14
	v_add_f32_e32 v14, v15, v0
	v_sub_f32_e32 v15, v14, v15
	v_sub_f32_e32 v0, v0, v15
	v_add_f32_e32 v15, v1, v14
	v_sub_f32_e32 v16, v15, v1
	v_sub_f32_e32 v17, v15, v16
	v_sub_f32_e32 v13, v18, v13
	v_sub_f32_e32 v1, v1, v17
	v_sub_f32_e32 v14, v14, v16
	v_add_f32_e32 v1, v14, v1
	v_add_f32_e32 v14, v13, v0
	v_sub_f32_e32 v16, v14, v13
	v_sub_f32_e32 v17, v14, v16
	v_sub_f32_e32 v13, v13, v17
	v_sub_f32_e32 v0, v0, v16
	v_add_f32_e32 v1, v14, v1
	v_add_f32_e32 v0, v0, v13
	v_add_f32_e32 v13, v15, v1
	v_sub_f32_e32 v14, v13, v15
	v_sub_f32_e32 v1, v1, v14
	v_add_f32_e32 v0, v0, v1
	v_add_f32_e32 v0, v13, v0
	v_cmp_neq_f32_e64 s[0:1], s6, v5
	v_mul_f32_e32 v1, 0x3fb8aa3b, v8
	v_exp_f32_e32 v1, v1
	v_cndmask_b32_e64 v0, v195, v0, s[0:1]
	v_cmp_ngt_f32_e64 s[0:1], -1.0, v5
	v_and_b32_e32 v8, 63, v184
	v_mul_f32_e32 v14, v9, v10
	v_cndmask_b32_e64 v0, v196, v0, s[0:1]
	v_cmp_neq_f32_e64 s[0:1], -1.0, v5
	s_nop 1
	v_cndmask_b32_e64 v0, v197, v0, s[0:1]
	v_cmp_lt_f32_e64 s[0:1], |v5|, s7
	s_nop 1
	v_cndmask_b32_e64 v0, v0, v5, s[0:1]
	v_add_f32_e32 v0, v12, v0
	v_add_u32_e32 v12, -1, v184
	v_cmp_lt_i32_e64 s[0:1], v12, v186
	v_mul_f32_e64 v5, v0, -v1
	s_nop 0
	v_cndmask_b32_e64 v12, v12, v184, s[0:1]
	v_cmp_ne_u32_e64 s[0:1], 63, v8
	v_lshlrev_b32_e32 v12, 2, v12
	ds_bpermute_b32 v12, v12, v11
	v_addc_co_u32_e64 v13, s[0:1], 0, v184, s[0:1]
	v_lshlrev_b32_e32 v13, 2, v13
	ds_bpermute_b32 v13, v13, v5
	s_waitcnt lgkmcnt(1)
; DI void dn_prep(const Params& p, int layer, int cgi, int h, unsigned char* lds) {
;     ...
;     float gf = g[0], gb = g[1];
; #pragma unroll
;     for (int o = 1; o < 64; o <<= 1) { const float vf = __shfl_up(gf, o), vb = __shfl_down(gb, o); if (lane >= o) gf += vf; if (lane + o < 64) gb += vb; }
;     gv[tid] = beta[0]; gv[64 + tid] = beta[1]; gv[128 + tid] = gf; gv[192 + tid] = gb;
;     const float egf = __expf(gf), egb = __expf(gb);
;     gv[256 + tid] = egf; gv[320 + tid] = egb;
;     const float glf = __shfl(gf, 63), glb = __shfl(gb, 0);
;     float* vec = (float*)(ops + 65536);
;     vec[tid] = egf; vec[64 + tid] = __expf(glf - gf); vec[128 + tid] = egb; vec[192 + tid] = __expf(glb - gb);
	v_fma_f32 v2, v2, -v3, v12
	v_cmp_eq_u32_e64 s[0:1], 0, v42
	s_waitcnt lgkmcnt(0)
	v_fma_f32 v0, v0, -v1, v13
	v_cndmask_b32_e64 v2, v2, v11, s[0:1]
	v_cmp_eq_u32_e64 s[0:1], 63, v42
	v_add_u32_e32 v1, -2, v184
	s_nop 0
	v_cndmask_b32_e64 v0, v0, v5, s[0:1]
	v_cmp_lt_i32_e64 s[0:1], v1, v186
	v_fma_f32 v5, -v7, v14, v9
	v_fmac_f32_e32 v14, v5, v10
	v_cndmask_b32_e64 v1, v1, v184, s[0:1]
	v_cmp_gt_u32_e64 s[0:1], 62, v8
	v_lshlrev_b32_e32 v1, 2, v1
	ds_bpermute_b32 v1, v1, v2
	v_cndmask_b32_e64 v3, 0, 2, s[0:1]
	v_add_lshl_u32 v3, v3, v184, 2
	ds_bpermute_b32 v3, v3, v0
	v_cmp_gt_u32_e64 s[0:1], 2, v42
	s_waitcnt lgkmcnt(1)
	v_add_f32_e32 v1, v2, v1
	v_fma_f32 v5, -v7, v14, v9
	v_cndmask_b32_e64 v1, v1, v2, s[0:1]
	s_waitcnt lgkmcnt(0)
	v_add_f32_e32 v2, v0, v3
	v_cmp_gt_u32_e64 s[0:1], 62, v42
	v_div_fmas_f32 v5, v5, v10, v14
	v_cmp_gt_u32_e32 vcc, 16, v42
	v_cndmask_b32_e64 v0, v0, v2, s[0:1]
	v_add_u32_e32 v2, -4, v184
	v_cmp_lt_i32_e64 s[0:1], v2, v186
	v_div_fixup_f32 v5, v5, v6, 1.0
	s_nop 0
	v_cndmask_b32_e64 v2, v2, v184, s[0:1]
	v_cmp_gt_u32_e64 s[0:1], 60, v8
	v_lshlrev_b32_e32 v2, 2, v2
	ds_bpermute_b32 v2, v2, v1
	v_cndmask_b32_e64 v3, 0, 4, s[0:1]
	v_add_lshl_u32 v3, v3, v184, 2
	ds_bpermute_b32 v3, v3, v0
	v_cmp_gt_u32_e64 s[0:1], 4, v42
	s_waitcnt lgkmcnt(1)
	v_add_f32_e32 v2, v1, v2
	v_cndmask_b32_e64 v1, v2, v1, s[0:1]
	s_waitcnt lgkmcnt(0)
	v_add_f32_e32 v2, v0, v3
	v_cmp_gt_u32_e64 s[0:1], 60, v42
	s_nop 1
	v_cndmask_b32_e64 v0, v0, v2, s[0:1]
	v_add_u32_e32 v2, -8, v184
	v_cmp_lt_i32_e64 s[0:1], v2, v186
	s_nop 1
	v_cndmask_b32_e64 v2, v2, v184, s[0:1]
	v_cmp_gt_u32_e64 s[0:1], 56, v8
	v_lshlrev_b32_e32 v2, 2, v2
	ds_bpermute_b32 v2, v2, v1
	v_cndmask_b32_e64 v3, 0, 8, s[0:1]
	v_add_lshl_u32 v3, v3, v184, 2
	ds_bpermute_b32 v3, v3, v0
	v_cmp_gt_u32_e64 s[0:1], 8, v42
	s_waitcnt lgkmcnt(1)
	v_add_f32_e32 v2, v1, v2
	v_cndmask_b32_e64 v1, v2, v1, s[0:1]
	s_waitcnt lgkmcnt(0)
	v_add_f32_e32 v2, v0, v3
	v_cmp_gt_u32_e64 s[0:1], 56, v42
	s_nop 1
	v_cndmask_b32_e64 v0, v0, v2, s[0:1]
	v_add_u32_e32 v2, -16, v184
	v_cmp_lt_i32_e64 s[0:1], v2, v186
	s_nop 1
	v_cndmask_b32_e64 v2, v2, v184, s[0:1]
	v_cmp_gt_u32_e64 s[0:1], 48, v8
	v_lshlrev_b32_e32 v2, 2, v2
	ds_bpermute_b32 v2, v2, v1
	v_cndmask_b32_e64 v3, 0, 16, s[0:1]
	v_add_lshl_u32 v3, v3, v184, 2
	ds_bpermute_b32 v3, v3, v0
	s_mov_b64 s[0:1], 0x10000
	s_waitcnt lgkmcnt(1)
	v_add_f32_e32 v2, v1, v2
	v_cndmask_b32_e32 v1, v2, v1, vcc
	v_cmp_gt_u32_e32 vcc, 48, v42
	s_waitcnt lgkmcnt(0)
	v_add_f32_e32 v2, v0, v3
	v_lshlrev_b32_e32 v3, 2, v184
	v_cndmask_b32_e32 v0, v0, v2, vcc
	v_subrev_u32_e32 v2, 32, v184
	v_cmp_lt_i32_e32 vcc, v2, v186
	v_or_b32_e32 v7, 0x80, v3
	ds_bpermute_b32 v7, v7, v0
	v_cndmask_b32_e32 v2, v2, v184, vcc
	v_lshlrev_b32_e32 v2, 2, v2
	ds_bpermute_b32 v2, v2, v1
	v_cmp_gt_u32_e32 vcc, 32, v42
	s_waitcnt lgkmcnt(0)
	v_add_f32_e32 v2, v1, v2
	v_cndmask_b32_e32 v6, v2, v1, vcc
	v_add_f32_e32 v1, v0, v7
	v_cndmask_b32_e32 v7, v0, v1, vcc
	v_mul_f32_e32 v1, 0x3fb8aa3b, v6
	v_exp_f32_e32 v8, v1
	v_mul_f32_e32 v1, 0x3fb8aa3b, v7
	v_lshl_add_u32 v0, v100, 2, 0
	v_exp_f32_e32 v9, v1
	v_add_u32_e32 v0, 0x11a00, v0
	ds_write2st64_b32 v0, v4, v5 offset1:1
	ds_write2st64_b32 v0, v6, v7 offset0:2 offset1:3
	ds_write2st64_b32 v0, v8, v9 offset0:4 offset1:5
	v_or_b32_e32 v0, 0xfc, v3
	ds_bpermute_b32 v4, v0, v6
	v_and_b32_e32 v0, 0x100, v3
	ds_bpermute_b32 v5, v0, v7
	v_lshl_add_u64 v[0:1], v[100:101], 2, s[34:35]
	v_lshl_add_u64 v[2:3], v[0:1], 0, s[0:1]
	s_waitcnt lgkmcnt(1)
	v_sub_f32_e32 v4, v4, v6
	v_mul_f32_e32 v4, 0x3fb8aa3b, v4
	v_exp_f32_e32 v4, v4
	s_waitcnt lgkmcnt(0)
	v_sub_f32_e32 v5, v5, v7
	v_add_co_u32_e32 v0, vcc, 0x10000, v0
	v_mul_f32_e32 v5, 0x3fb8aa3b, v5
	s_nop 0
	v_addc_co_u32_e32 v1, vcc, 0, v1, vcc
	v_exp_f32_e32 v5, v5
	global_store_dword v[0:1], v8, off
	global_store_dword v[2:3], v4, off offset:256
	global_store_dword v[2:3], v9, off offset:512
	global_store_dword v[2:3], v5, off offset:768
